# write-through sc1 policy on all 16-byte global stores (GEMM epilogues etc.): less dirty L2 for the grid barrier release fence
# speedup vs baseline: 1.0529x; 1.0139x over previous
.LBB0_57:
	v_lshl_add_u64 v[198:199], v[196:197], 0, v[176:177]
	s_waitcnt vmcnt(0)
	v_lshlrev_b32_e32 v176, 16, v164
	v_and_b32_e32 v164, 0xffff0000, v164
	v_max_f32_e32 v164, v164, v164
	v_max_f32_e32 v203, 0x21800000, v164
	v_lshlrev_b32_e32 v164, 16, v165
	v_and_b32_e32 v165, 0xffff0000, v165
	v_max_f32_e32 v164, v164, v164
	v_max_f32_e32 v165, v165, v165
	v_max_f32_e32 v164, 0x21800000, v164
	v_max_f32_e32 v165, 0x21800000, v165
	v_pk_mul_f32 v[204:205], v[106:107], v[164:165]
	v_lshlrev_b32_e32 v164, 16, v166
	v_and_b32_e32 v165, 0xffff0000, v166
	v_lshlrev_b32_e32 v166, 16, v167
	v_and_b32_e32 v167, 0xffff0000, v167
	v_max_f32_e32 v176, v176, v176
	v_max_f32_e32 v164, v164, v164
	v_max_f32_e32 v165, v165, v165
	v_max_f32_e32 v166, v166, v166
	v_max_f32_e32 v167, v167, v167
	v_max_f32_e32 v202, 0x21800000, v176
	v_max_f32_e32 v164, 0x21800000, v164
	v_max_f32_e32 v165, 0x21800000, v165
	v_max_f32_e32 v166, 0x21800000, v166
	v_max_f32_e32 v167, 0x21800000, v167
	v_pk_mul_f32 v[202:203], v[104:105], v[202:203]
	v_pk_mul_f32 v[164:165], v[124:125], v[164:165]
	v_pk_mul_f32 v[166:167], v[126:127], v[166:167]
	s_mov_b64 s[2:3], -1
	s_and_b64 vcc, exec, s[4:5]
	s_cbranch_vccz .LBB0_59
	v_cvt_pk_bf16_f32 v238, v202, v203
	v_cvt_pk_bf16_f32 v239, v204, v205
	v_cvt_pk_bf16_f32 v240, v164, v165
	v_cvt_pk_bf16_f32 v241, v166, v167
	global_store_dwordx4 v[198:199], v[238:241], off sc1
	s_mov_b64 s[2:3], 0

.LBB0_61:
	v_lshlrev_b32_e32 v152, 16, v140
	v_and_b32_e32 v140, 0xffff0000, v140
	v_max_f32_e32 v140, v140, v140
	v_max_f32_e32 v153, 0x21800000, v140
	v_lshlrev_b32_e32 v140, 16, v141
	v_and_b32_e32 v141, 0xffff0000, v141
	v_max_f32_e32 v140, v140, v140
	v_max_f32_e32 v141, v141, v141
	v_max_f32_e32 v140, 0x21800000, v140
	v_max_f32_e32 v141, 0x21800000, v141
	v_pk_mul_f32 v[154:155], v[74:75], v[140:141]
	v_lshlrev_b32_e32 v140, 16, v142
	v_and_b32_e32 v141, 0xffff0000, v142
	v_lshlrev_b32_e32 v142, 16, v143
	v_and_b32_e32 v143, 0xffff0000, v143
	v_max_f32_e32 v152, v152, v152
	v_max_f32_e32 v140, v140, v140
	v_max_f32_e32 v141, v141, v141
	v_max_f32_e32 v142, v142, v142
	v_max_f32_e32 v143, v143, v143
	v_max_f32_e32 v152, 0x21800000, v152
	v_max_f32_e32 v140, 0x21800000, v140
	v_max_f32_e32 v141, 0x21800000, v141
	v_max_f32_e32 v142, 0x21800000, v142
	v_max_f32_e32 v143, 0x21800000, v143
	v_cndmask_b32_e64 v164, 0, 1, s[4:5]
	v_pk_mul_f32 v[152:153], v[72:73], v[152:153]
	v_pk_mul_f32 v[140:141], v[108:109], v[140:141]
	v_pk_mul_f32 v[142:143], v[110:111], v[142:143]
	v_cmp_ne_u32_e64 s[36:37], 1, v164
	s_andn2_b64 vcc, exec, s[4:5]
	s_mov_b64 s[2:3], -1
	s_cbranch_vccnz .LBB0_63
	v_cvt_pk_bf16_f32 v164, v152, v153
	v_cvt_pk_bf16_f32 v165, v154, v155
	v_cvt_pk_bf16_f32 v166, v140, v141
	v_cvt_pk_bf16_f32 v167, v142, v143
	s_mov_b64 s[2:3], 0
	global_store_dwordx4 v[198:199], v[164:167], off offset:256 sc1

.LBB0_69:
	v_lshlrev_b32_e32 v176, 16, v168
	v_and_b32_e32 v168, 0xffff0000, v168
	v_max_f32_e32 v168, v168, v168
	v_max_f32_e32 v203, 0x21800000, v168
	v_lshlrev_b32_e32 v168, 16, v169
	v_and_b32_e32 v169, 0xffff0000, v169
	v_max_f32_e32 v168, v168, v168
	v_max_f32_e32 v169, v169, v169
	v_max_f32_e32 v168, 0x21800000, v168
	v_max_f32_e32 v169, 0x21800000, v169
	v_pk_mul_f32 v[204:205], v[98:99], v[168:169]
	v_lshlrev_b32_e32 v168, 16, v170
	v_and_b32_e32 v169, 0xffff0000, v170
	v_lshlrev_b32_e32 v170, 16, v171
	v_and_b32_e32 v171, 0xffff0000, v171
	v_max_f32_e32 v176, v176, v176
	v_max_f32_e32 v168, v168, v168
	v_max_f32_e32 v169, v169, v169
	v_max_f32_e32 v170, v170, v170
	v_max_f32_e32 v171, v171, v171
	v_max_f32_e32 v202, 0x21800000, v176
	v_max_f32_e32 v168, 0x21800000, v168
	v_max_f32_e32 v169, 0x21800000, v169
	v_max_f32_e32 v170, 0x21800000, v170
	v_max_f32_e32 v171, 0x21800000, v171
	v_pk_mul_f32 v[202:203], v[96:97], v[202:203]
	v_pk_mul_f32 v[168:169], v[120:121], v[168:169]
	v_pk_mul_f32 v[170:171], v[122:123], v[170:171]
	s_and_b64 vcc, exec, s[36:37]
	s_mov_b64 s[2:3], -1
	s_cbranch_vccnz .LBB0_71
	v_add_co_u32_e32 v214, vcc, 0x8000, v198
	v_cvt_pk_bf16_f32 v238, v202, v203
	v_cvt_pk_bf16_f32 v239, v204, v205
	v_cvt_pk_bf16_f32 v240, v168, v169
	v_cvt_pk_bf16_f32 v241, v170, v171
	v_addc_co_u32_e32 v215, vcc, 0, v199, vcc
	s_mov_b64 s[2:3], 0
	global_store_dwordx4 v[214:215], v[238:241], off sc1

.LBB0_73:
	v_lshlrev_b32_e32 v156, 16, v144
	v_and_b32_e32 v144, 0xffff0000, v144
	v_max_f32_e32 v144, v144, v144
	v_max_f32_e32 v157, 0x21800000, v144
	v_lshlrev_b32_e32 v144, 16, v145
	v_and_b32_e32 v145, 0xffff0000, v145
	v_max_f32_e32 v144, v144, v144
	v_max_f32_e32 v145, v145, v145
	v_max_f32_e32 v144, 0x21800000, v144
	v_max_f32_e32 v145, 0x21800000, v145
	v_pk_mul_f32 v[158:159], v[66:67], v[144:145]
	v_lshlrev_b32_e32 v144, 16, v146
	v_and_b32_e32 v145, 0xffff0000, v146
	v_lshlrev_b32_e32 v146, 16, v147
	v_and_b32_e32 v147, 0xffff0000, v147
	v_max_f32_e32 v156, v156, v156
	v_max_f32_e32 v144, v144, v144
	v_max_f32_e32 v145, v145, v145
	v_max_f32_e32 v146, v146, v146
	v_max_f32_e32 v147, v147, v147
	v_max_f32_e32 v156, 0x21800000, v156
	v_max_f32_e32 v144, 0x21800000, v144
	v_max_f32_e32 v145, 0x21800000, v145
	v_max_f32_e32 v146, 0x21800000, v146
	v_max_f32_e32 v147, 0x21800000, v147
	v_pk_mul_f32 v[156:157], v[64:65], v[156:157]
	v_pk_mul_f32 v[144:145], v[100:101], v[144:145]
	v_pk_mul_f32 v[146:147], v[102:103], v[146:147]
	s_and_b64 vcc, exec, s[36:37]
	s_mov_b64 s[2:3], -1
	s_cbranch_vccnz .LBB0_75
	v_add_co_u32_e32 v202, vcc, 0x8000, v198
	v_cvt_pk_bf16_f32 v168, v156, v157
	v_cvt_pk_bf16_f32 v169, v158, v159
	v_cvt_pk_bf16_f32 v170, v144, v145
	v_cvt_pk_bf16_f32 v171, v146, v147
	v_addc_co_u32_e32 v203, vcc, 0, v199, vcc
	s_mov_b64 s[2:3], 0
	global_store_dwordx4 v[202:203], v[168:171], off offset:256 sc1

.LBB0_81:
	v_lshlrev_b32_e32 v176, 16, v172
	v_and_b32_e32 v172, 0xffff0000, v172
	v_max_f32_e32 v172, v172, v172
	v_max_f32_e32 v203, 0x21800000, v172
	v_lshlrev_b32_e32 v172, 16, v173
	v_and_b32_e32 v173, 0xffff0000, v173
	v_max_f32_e32 v172, v172, v172
	v_max_f32_e32 v173, v173, v173
	v_max_f32_e32 v172, 0x21800000, v172
	v_max_f32_e32 v173, 0x21800000, v173
	v_pk_mul_f32 v[204:205], v[90:91], v[172:173]
	v_lshlrev_b32_e32 v172, 16, v174
	v_and_b32_e32 v173, 0xffff0000, v174
	v_lshlrev_b32_e32 v174, 16, v175
	v_and_b32_e32 v175, 0xffff0000, v175
	v_max_f32_e32 v176, v176, v176
	v_max_f32_e32 v172, v172, v172
	v_max_f32_e32 v173, v173, v173
	v_max_f32_e32 v174, v174, v174
	v_max_f32_e32 v175, v175, v175
	v_max_f32_e32 v202, 0x21800000, v176
	v_max_f32_e32 v172, 0x21800000, v172
	v_max_f32_e32 v173, 0x21800000, v173
	v_max_f32_e32 v174, 0x21800000, v174
	v_max_f32_e32 v175, 0x21800000, v175
	v_pk_mul_f32 v[202:203], v[88:89], v[202:203]
	v_pk_mul_f32 v[172:173], v[116:117], v[172:173]
	v_pk_mul_f32 v[174:175], v[118:119], v[174:175]
	s_and_b64 vcc, exec, s[36:37]
	s_mov_b64 s[2:3], -1
	s_cbranch_vccnz .LBB0_83
	v_add_co_u32_e32 v214, vcc, 0x10000, v198
	v_cvt_pk_bf16_f32 v238, v202, v203
	v_cvt_pk_bf16_f32 v239, v204, v205
	v_cvt_pk_bf16_f32 v240, v172, v173
	v_cvt_pk_bf16_f32 v241, v174, v175
	v_addc_co_u32_e32 v215, vcc, 0, v199, vcc
	s_mov_b64 s[2:3], 0
	global_store_dwordx4 v[214:215], v[238:241], off sc1

.LBB0_85:
	v_lshlrev_b32_e32 v160, 16, v148
	v_and_b32_e32 v148, 0xffff0000, v148
	v_max_f32_e32 v148, v148, v148
	v_max_f32_e32 v161, 0x21800000, v148
	v_lshlrev_b32_e32 v148, 16, v149
	v_and_b32_e32 v149, 0xffff0000, v149
	v_max_f32_e32 v148, v148, v148
	v_max_f32_e32 v149, v149, v149
	v_max_f32_e32 v148, 0x21800000, v148
	v_max_f32_e32 v149, 0x21800000, v149
	v_pk_mul_f32 v[162:163], v[58:59], v[148:149]
	v_lshlrev_b32_e32 v148, 16, v150
	v_and_b32_e32 v149, 0xffff0000, v150
	v_lshlrev_b32_e32 v150, 16, v151
	v_and_b32_e32 v151, 0xffff0000, v151
	v_max_f32_e32 v160, v160, v160
	v_max_f32_e32 v148, v148, v148
	v_max_f32_e32 v149, v149, v149
	v_max_f32_e32 v150, v150, v150
	v_max_f32_e32 v151, v151, v151
	v_max_f32_e32 v160, 0x21800000, v160
	v_max_f32_e32 v148, 0x21800000, v148
	v_max_f32_e32 v149, 0x21800000, v149
	v_max_f32_e32 v150, 0x21800000, v150
	v_max_f32_e32 v151, 0x21800000, v151
	v_pk_mul_f32 v[160:161], v[56:57], v[160:161]
	v_pk_mul_f32 v[148:149], v[92:93], v[148:149]
	v_pk_mul_f32 v[150:151], v[94:95], v[150:151]
	s_and_b64 vcc, exec, s[36:37]
	s_mov_b64 s[2:3], -1
	s_cbranch_vccnz .LBB0_87
	v_add_co_u32_e32 v202, vcc, 0x10000, v198
	v_cvt_pk_bf16_f32 v172, v160, v161
	v_cvt_pk_bf16_f32 v173, v162, v163
	v_cvt_pk_bf16_f32 v174, v148, v149
	v_cvt_pk_bf16_f32 v175, v150, v151
	v_addc_co_u32_e32 v203, vcc, 0, v199, vcc
	s_mov_b64 s[2:3], 0
	global_store_dwordx4 v[202:203], v[172:175], off offset:256 sc1

.LBB0_93:
	s_waitcnt vmcnt(5)
	v_lshlrev_b32_e32 v176, 16, v164
	v_and_b32_e32 v164, 0xffff0000, v164
	v_max_f32_e32 v164, v164, v164
	v_max_f32_e32 v203, 0x21800000, v164
	v_lshlrev_b32_e32 v164, 16, v165
	v_and_b32_e32 v165, 0xffff0000, v165
	v_max_f32_e32 v164, v164, v164
	v_max_f32_e32 v165, v165, v165
	v_max_f32_e32 v164, 0x21800000, v164
	v_max_f32_e32 v165, 0x21800000, v165
	v_pk_mul_f32 v[204:205], v[82:83], v[164:165]
	v_lshlrev_b32_e32 v164, 16, v166
	v_and_b32_e32 v165, 0xffff0000, v166
	v_lshlrev_b32_e32 v166, 16, v167
	v_and_b32_e32 v167, 0xffff0000, v167
	v_max_f32_e32 v176, v176, v176
	v_max_f32_e32 v164, v164, v164
	v_max_f32_e32 v165, v165, v165
	v_max_f32_e32 v166, v166, v166
	v_max_f32_e32 v167, v167, v167
	v_max_f32_e32 v202, 0x21800000, v176
	v_max_f32_e32 v164, 0x21800000, v164
	v_max_f32_e32 v165, 0x21800000, v165
	v_max_f32_e32 v166, 0x21800000, v166
	v_max_f32_e32 v167, 0x21800000, v167
	v_pk_mul_f32 v[202:203], v[80:81], v[202:203]
	v_pk_mul_f32 v[164:165], v[112:113], v[164:165]
	v_pk_mul_f32 v[166:167], v[114:115], v[166:167]
	s_and_b64 vcc, exec, s[36:37]
	s_mov_b64 s[2:3], -1
	s_cbranch_vccnz .LBB0_95
	v_add_co_u32_e32 v214, vcc, 0x18000, v198
	v_cvt_pk_bf16_f32 v238, v202, v203
	v_cvt_pk_bf16_f32 v239, v204, v205
	v_cvt_pk_bf16_f32 v240, v164, v165
	v_cvt_pk_bf16_f32 v241, v166, v167
	v_addc_co_u32_e32 v215, vcc, 0, v199, vcc
	s_mov_b64 s[2:3], 0
	global_store_dwordx4 v[214:215], v[238:241], off sc1

.LBB0_97:
	s_waitcnt vmcnt(4)
	v_lshlrev_b32_e32 v152, 16, v140
	v_and_b32_e32 v140, 0xffff0000, v140
	v_max_f32_e32 v140, v140, v140
	v_max_f32_e32 v153, 0x21800000, v140
	v_lshlrev_b32_e32 v140, 16, v141
	v_and_b32_e32 v141, 0xffff0000, v141
	v_max_f32_e32 v140, v140, v140
	v_max_f32_e32 v141, v141, v141
	v_max_f32_e32 v140, 0x21800000, v140
	v_max_f32_e32 v141, 0x21800000, v141
	v_pk_mul_f32 v[154:155], v[50:51], v[140:141]
	v_lshlrev_b32_e32 v140, 16, v142
	v_and_b32_e32 v141, 0xffff0000, v142
	v_lshlrev_b32_e32 v142, 16, v143
	v_and_b32_e32 v143, 0xffff0000, v143
	v_max_f32_e32 v152, v152, v152
	v_max_f32_e32 v140, v140, v140
	v_max_f32_e32 v141, v141, v141
	v_max_f32_e32 v142, v142, v142
	v_max_f32_e32 v143, v143, v143
	v_max_f32_e32 v152, 0x21800000, v152
	v_max_f32_e32 v140, 0x21800000, v140
	v_max_f32_e32 v141, 0x21800000, v141
	v_max_f32_e32 v142, 0x21800000, v142
	v_max_f32_e32 v143, 0x21800000, v143
	v_pk_mul_f32 v[152:153], v[48:49], v[152:153]
	v_pk_mul_f32 v[140:141], v[84:85], v[140:141]
	v_pk_mul_f32 v[142:143], v[86:87], v[142:143]
	s_and_b64 vcc, exec, s[36:37]
	s_mov_b64 s[2:3], -1
	s_cbranch_vccnz .LBB0_99
	v_add_co_u32_e32 v202, vcc, 0x18000, v198
	v_cvt_pk_bf16_f32 v164, v152, v153
	v_cvt_pk_bf16_f32 v165, v154, v155
	v_cvt_pk_bf16_f32 v166, v140, v141
	v_cvt_pk_bf16_f32 v167, v142, v143
	v_addc_co_u32_e32 v203, vcc, 0, v199, vcc
	s_mov_b64 s[2:3], 0
	global_store_dwordx4 v[202:203], v[164:167], off offset:256 sc1

.LBB0_105:
	s_waitcnt vmcnt(5)
	v_lshlrev_b32_e32 v176, 16, v168
	v_and_b32_e32 v168, 0xffff0000, v168
	v_max_f32_e32 v168, v168, v168
	v_max_f32_e32 v203, 0x21800000, v168
	v_lshlrev_b32_e32 v168, 16, v169
	v_and_b32_e32 v169, 0xffff0000, v169
	v_max_f32_e32 v168, v168, v168
	v_max_f32_e32 v169, v169, v169
	v_max_f32_e32 v168, 0x21800000, v168
	v_max_f32_e32 v169, 0x21800000, v169
	v_pk_mul_f32 v[204:205], v[42:43], v[168:169]
	v_lshlrev_b32_e32 v168, 16, v170
	v_and_b32_e32 v169, 0xffff0000, v170
	v_lshlrev_b32_e32 v170, 16, v171
	v_and_b32_e32 v171, 0xffff0000, v171
	v_max_f32_e32 v176, v176, v176
	v_max_f32_e32 v168, v168, v168
	v_max_f32_e32 v169, v169, v169
	v_max_f32_e32 v170, v170, v170
	v_max_f32_e32 v171, v171, v171
	v_max_f32_e32 v202, 0x21800000, v176
	v_max_f32_e32 v168, 0x21800000, v168
	v_max_f32_e32 v169, 0x21800000, v169
	v_max_f32_e32 v170, 0x21800000, v170
	v_max_f32_e32 v171, 0x21800000, v171
	v_pk_mul_f32 v[202:203], v[40:41], v[202:203]
	v_pk_mul_f32 v[168:169], v[76:77], v[168:169]
	v_pk_mul_f32 v[170:171], v[78:79], v[170:171]
	s_and_b64 vcc, exec, s[36:37]
	s_mov_b64 s[2:3], -1
	s_cbranch_vccnz .LBB0_107
	v_add_co_u32_e32 v214, vcc, 0x40000, v198
	v_cvt_pk_bf16_f32 v238, v202, v203
	v_cvt_pk_bf16_f32 v239, v204, v205
	v_cvt_pk_bf16_f32 v240, v168, v169
	v_cvt_pk_bf16_f32 v241, v170, v171
	v_addc_co_u32_e32 v215, vcc, 0, v199, vcc
	s_mov_b64 s[2:3], 0
	global_store_dwordx4 v[214:215], v[238:241], off sc1

.LBB0_109:
	s_waitcnt vmcnt(4)
	v_lshlrev_b32_e32 v156, 16, v144
	v_and_b32_e32 v144, 0xffff0000, v144
	v_max_f32_e32 v144, v144, v144
	v_max_f32_e32 v157, 0x21800000, v144
	v_lshlrev_b32_e32 v144, 16, v145
	v_and_b32_e32 v145, 0xffff0000, v145
	v_max_f32_e32 v144, v144, v144
	v_max_f32_e32 v145, v145, v145
	v_max_f32_e32 v144, 0x21800000, v144
	v_max_f32_e32 v145, 0x21800000, v145
	v_pk_mul_f32 v[158:159], v[18:19], v[144:145]
	v_lshlrev_b32_e32 v144, 16, v146
	v_and_b32_e32 v145, 0xffff0000, v146
	v_lshlrev_b32_e32 v146, 16, v147
	v_and_b32_e32 v147, 0xffff0000, v147
	v_max_f32_e32 v156, v156, v156
	v_max_f32_e32 v144, v144, v144
	v_max_f32_e32 v145, v145, v145
	v_max_f32_e32 v146, v146, v146
	v_max_f32_e32 v147, v147, v147
	v_max_f32_e32 v156, 0x21800000, v156
	v_max_f32_e32 v144, 0x21800000, v144
	v_max_f32_e32 v145, 0x21800000, v145
	v_max_f32_e32 v146, 0x21800000, v146
	v_max_f32_e32 v147, 0x21800000, v147
	v_pk_mul_f32 v[156:157], v[16:17], v[156:157]
	v_pk_mul_f32 v[144:145], v[44:45], v[144:145]
	v_pk_mul_f32 v[146:147], v[46:47], v[146:147]
	s_and_b64 vcc, exec, s[36:37]
	s_mov_b64 s[2:3], -1
	s_cbranch_vccnz .LBB0_111
	v_add_co_u32_e32 v202, vcc, 0x40000, v198
	v_cvt_pk_bf16_f32 v168, v156, v157
	v_cvt_pk_bf16_f32 v169, v158, v159
	v_cvt_pk_bf16_f32 v170, v144, v145
	v_cvt_pk_bf16_f32 v171, v146, v147
	v_addc_co_u32_e32 v203, vcc, 0, v199, vcc
	s_mov_b64 s[2:3], 0
	global_store_dwordx4 v[202:203], v[168:171], off offset:256 sc1

.LBB0_117:
	s_waitcnt vmcnt(5)
	v_lshlrev_b32_e32 v176, 16, v172
	v_and_b32_e32 v172, 0xffff0000, v172
	v_max_f32_e32 v172, v172, v172
	v_max_f32_e32 v201, 0x21800000, v172
	v_lshlrev_b32_e32 v172, 16, v173
	v_and_b32_e32 v173, 0xffff0000, v173
	v_max_f32_e32 v172, v172, v172
	v_max_f32_e32 v173, v173, v173
	v_max_f32_e32 v172, 0x21800000, v172
	v_max_f32_e32 v173, 0x21800000, v173
	v_pk_mul_f32 v[202:203], v[34:35], v[172:173]
	v_lshlrev_b32_e32 v172, 16, v174
	v_and_b32_e32 v173, 0xffff0000, v174
	v_lshlrev_b32_e32 v174, 16, v175
	v_and_b32_e32 v175, 0xffff0000, v175
	v_max_f32_e32 v176, v176, v176
	v_max_f32_e32 v172, v172, v172
	v_max_f32_e32 v173, v173, v173
	v_max_f32_e32 v174, v174, v174
	v_max_f32_e32 v175, v175, v175
	v_max_f32_e32 v200, 0x21800000, v176
	v_max_f32_e32 v172, 0x21800000, v172
	v_max_f32_e32 v173, 0x21800000, v173
	v_max_f32_e32 v174, 0x21800000, v174
	v_max_f32_e32 v175, 0x21800000, v175
	v_pk_mul_f32 v[200:201], v[32:33], v[200:201]
	v_pk_mul_f32 v[172:173], v[68:69], v[172:173]
	v_pk_mul_f32 v[174:175], v[70:71], v[174:175]
	s_and_b64 vcc, exec, s[36:37]
	s_mov_b64 s[2:3], -1
	s_cbranch_vccnz .LBB0_119
	v_add_co_u32_e32 v204, vcc, 0x48000, v198
	v_cvt_pk_bf16_f32 v238, v200, v201
	v_cvt_pk_bf16_f32 v239, v202, v203
	v_cvt_pk_bf16_f32 v240, v172, v173
	v_cvt_pk_bf16_f32 v241, v174, v175
	v_addc_co_u32_e32 v205, vcc, 0, v199, vcc
	s_mov_b64 s[2:3], 0
	global_store_dwordx4 v[204:205], v[238:241], off sc1

.LBB0_121:
	s_waitcnt vmcnt(4)
	v_lshlrev_b32_e32 v160, 16, v148
	v_and_b32_e32 v148, 0xffff0000, v148
	v_max_f32_e32 v148, v148, v148
	v_max_f32_e32 v161, 0x21800000, v148
	v_lshlrev_b32_e32 v148, 16, v149
	v_and_b32_e32 v149, 0xffff0000, v149
	v_max_f32_e32 v148, v148, v148
	v_max_f32_e32 v149, v149, v149
	v_max_f32_e32 v148, 0x21800000, v148
	v_max_f32_e32 v149, 0x21800000, v149
	v_pk_mul_f32 v[162:163], v[14:15], v[148:149]
	v_lshlrev_b32_e32 v148, 16, v150
	v_and_b32_e32 v149, 0xffff0000, v150
	v_lshlrev_b32_e32 v150, 16, v151
	v_and_b32_e32 v151, 0xffff0000, v151
	v_max_f32_e32 v160, v160, v160
	v_max_f32_e32 v148, v148, v148
	v_max_f32_e32 v149, v149, v149
	v_max_f32_e32 v150, v150, v150
	v_max_f32_e32 v151, v151, v151
	v_max_f32_e32 v160, 0x21800000, v160
	v_max_f32_e32 v148, 0x21800000, v148
	v_max_f32_e32 v149, 0x21800000, v149
	v_max_f32_e32 v150, 0x21800000, v150
	v_max_f32_e32 v151, 0x21800000, v151
	v_pk_mul_f32 v[160:161], v[12:13], v[160:161]
	v_pk_mul_f32 v[148:149], v[36:37], v[148:149]
	v_pk_mul_f32 v[150:151], v[38:39], v[150:151]
	s_and_b64 vcc, exec, s[36:37]
	s_mov_b64 s[2:3], -1
	s_cbranch_vccnz .LBB0_123
	v_add_co_u32_e32 v200, vcc, 0x48000, v198
	v_cvt_pk_bf16_f32 v172, v160, v161
	v_cvt_pk_bf16_f32 v173, v162, v163
	v_cvt_pk_bf16_f32 v174, v148, v149
	v_cvt_pk_bf16_f32 v175, v150, v151
	v_addc_co_u32_e32 v201, vcc, 0, v199, vcc
	s_mov_b64 s[2:3], 0
	global_store_dwordx4 v[200:201], v[172:175], off offset:256 sc1

.LBB0_125:
	s_waitcnt vmcnt(3)
	v_lshlrev_b32_e32 v136, 16, v164
	v_and_b32_e32 v137, 0xffff0000, v164
	v_max_f32_e32 v136, v136, v136
	v_max_f32_e32 v137, v137, v137
	v_max_f32_e32 v136, 0x21800000, v136
	v_max_f32_e32 v137, 0x21800000, v137
	v_pk_mul_f32 v[148:149], v[24:25], v[136:137]
	v_lshlrev_b32_e32 v136, 16, v165
	v_and_b32_e32 v137, 0xffff0000, v165
	v_max_f32_e32 v136, v136, v136
	v_max_f32_e32 v137, v137, v137
	v_max_f32_e32 v136, 0x21800000, v136
	v_max_f32_e32 v137, 0x21800000, v137
	v_pk_mul_f32 v[150:151], v[26:27], v[136:137]
	v_lshlrev_b32_e32 v136, 16, v166
	v_and_b32_e32 v137, 0xffff0000, v166
	v_lshlrev_b32_e32 v138, 16, v167
	v_and_b32_e32 v139, 0xffff0000, v167
	v_max_f32_e32 v136, v136, v136
	v_max_f32_e32 v137, v137, v137
	v_max_f32_e32 v138, v138, v138
	v_max_f32_e32 v139, v139, v139
	v_max_f32_e32 v136, 0x21800000, v136
	v_max_f32_e32 v137, 0x21800000, v137
	v_max_f32_e32 v138, 0x21800000, v138
	v_max_f32_e32 v139, 0x21800000, v139
	v_pk_mul_f32 v[136:137], v[60:61], v[136:137]
	v_pk_mul_f32 v[138:139], v[62:63], v[138:139]
	s_and_b64 vcc, exec, s[36:37]
	s_mov_b64 s[2:3], -1
	s_cbranch_vccnz .LBB0_127
	v_add_co_u32_e32 v164, vcc, 0x50000, v198
	v_cvt_pk_bf16_f32 v160, v148, v149
	v_cvt_pk_bf16_f32 v161, v150, v151
	v_cvt_pk_bf16_f32 v162, v136, v137
	v_cvt_pk_bf16_f32 v163, v138, v139
	v_addc_co_u32_e32 v165, vcc, 0, v199, vcc
	s_mov_b64 s[2:3], 0
	global_store_dwordx4 v[164:165], v[160:163], off sc1

.LBB0_129:
	s_waitcnt vmcnt(2)
	v_lshlrev_b32_e32 v136, 16, v140
	v_and_b32_e32 v137, 0xffff0000, v140
	v_max_f32_e32 v136, v136, v136
	v_max_f32_e32 v137, v137, v137
	v_max_f32_e32 v136, 0x21800000, v136
	v_max_f32_e32 v137, 0x21800000, v137
	v_pk_mul_f32 v[148:149], v[4:5], v[136:137]
	v_lshlrev_b32_e32 v136, 16, v141
	v_and_b32_e32 v137, 0xffff0000, v141
	v_max_f32_e32 v136, v136, v136
	v_max_f32_e32 v137, v137, v137
	v_max_f32_e32 v136, 0x21800000, v136
	v_max_f32_e32 v137, 0x21800000, v137
	v_pk_mul_f32 v[140:141], v[6:7], v[136:137]
	v_lshlrev_b32_e32 v136, 16, v142
	v_and_b32_e32 v137, 0xffff0000, v142
	v_lshlrev_b32_e32 v138, 16, v143
	v_and_b32_e32 v139, 0xffff0000, v143
	v_max_f32_e32 v136, v136, v136
	v_max_f32_e32 v137, v137, v137
	v_max_f32_e32 v138, v138, v138
	v_max_f32_e32 v139, v139, v139
	v_max_f32_e32 v136, 0x21800000, v136
	v_max_f32_e32 v137, 0x21800000, v137
	v_max_f32_e32 v138, 0x21800000, v138
	v_max_f32_e32 v139, 0x21800000, v139
	v_pk_mul_f32 v[136:137], v[28:29], v[136:137]
	v_pk_mul_f32 v[138:139], v[30:31], v[138:139]
	s_and_b64 vcc, exec, s[36:37]
	s_mov_b64 s[2:3], -1
	s_cbranch_vccnz .LBB0_131
	v_add_co_u32_e32 v142, vcc, 0x50000, v198
	v_cvt_pk_bf16_f32 v150, v148, v149
	v_cvt_pk_bf16_f32 v151, v140, v141
	v_cvt_pk_bf16_f32 v152, v136, v137
	v_cvt_pk_bf16_f32 v153, v138, v139
	v_addc_co_u32_e32 v143, vcc, 0, v199, vcc
	s_mov_b64 s[2:3], 0
	global_store_dwordx4 v[142:143], v[150:153], off offset:256 sc1

.LBB0_133:
	s_waitcnt vmcnt(1)
	v_lshlrev_b32_e32 v128, 16, v168
	v_and_b32_e32 v129, 0xffff0000, v168
	v_max_f32_e32 v128, v128, v128
	v_max_f32_e32 v129, v129, v129
	v_max_f32_e32 v128, 0x21800000, v128
	v_max_f32_e32 v129, 0x21800000, v129
	v_pk_mul_f32 v[136:137], v[20:21], v[128:129]
	v_lshlrev_b32_e32 v128, 16, v169
	v_and_b32_e32 v129, 0xffff0000, v169
	v_max_f32_e32 v128, v128, v128
	v_max_f32_e32 v129, v129, v129
	v_max_f32_e32 v128, 0x21800000, v128
	v_max_f32_e32 v129, 0x21800000, v129
	v_pk_mul_f32 v[138:139], v[22:23], v[128:129]
	v_lshlrev_b32_e32 v128, 16, v170
	v_and_b32_e32 v129, 0xffff0000, v170
	v_lshlrev_b32_e32 v130, 16, v171
	v_and_b32_e32 v131, 0xffff0000, v171
	v_max_f32_e32 v128, v128, v128
	v_max_f32_e32 v129, v129, v129
	v_max_f32_e32 v130, v130, v130
	v_max_f32_e32 v131, v131, v131
	v_max_f32_e32 v128, 0x21800000, v128
	v_max_f32_e32 v129, 0x21800000, v129
	v_max_f32_e32 v130, 0x21800000, v130
	v_max_f32_e32 v131, 0x21800000, v131
	v_pk_mul_f32 v[128:129], v[52:53], v[128:129]
	v_pk_mul_f32 v[130:131], v[54:55], v[130:131]
	s_and_b64 vcc, exec, s[36:37]
	s_mov_b64 s[2:3], -1
	s_cbranch_vccnz .LBB0_135
	v_add_co_u32_e32 v148, vcc, 0x58000, v198
	v_cvt_pk_bf16_f32 v140, v136, v137
	v_cvt_pk_bf16_f32 v141, v138, v139
	v_cvt_pk_bf16_f32 v142, v128, v129
	v_cvt_pk_bf16_f32 v143, v130, v131
	v_addc_co_u32_e32 v149, vcc, 0, v199, vcc
	s_mov_b64 s[2:3], 0
	global_store_dwordx4 v[148:149], v[140:143], off sc1

.LBB0_137:
	s_waitcnt vmcnt(0)
	v_lshlrev_b32_e32 v128, 16, v144
	v_and_b32_e32 v129, 0xffff0000, v144
	v_max_f32_e32 v128, v128, v128
	v_max_f32_e32 v129, v129, v129
	v_max_f32_e32 v128, 0x21800000, v128
	v_max_f32_e32 v129, 0x21800000, v129
	v_pk_mul_f32 v[136:137], v[0:1], v[128:129]
	v_lshlrev_b32_e32 v128, 16, v145
	v_and_b32_e32 v129, 0xffff0000, v145
	v_max_f32_e32 v128, v128, v128
	v_max_f32_e32 v129, v129, v129
	v_max_f32_e32 v128, 0x21800000, v128
	v_max_f32_e32 v129, 0x21800000, v129
	v_pk_mul_f32 v[138:139], v[2:3], v[128:129]
	v_lshlrev_b32_e32 v128, 16, v146
	v_and_b32_e32 v129, 0xffff0000, v146
	v_lshlrev_b32_e32 v130, 16, v147
	v_and_b32_e32 v131, 0xffff0000, v147
	v_max_f32_e32 v128, v128, v128
	v_max_f32_e32 v129, v129, v129
	v_max_f32_e32 v130, v130, v130
	v_max_f32_e32 v131, v131, v131
	v_max_f32_e32 v128, 0x21800000, v128
	v_max_f32_e32 v129, 0x21800000, v129
	v_max_f32_e32 v130, 0x21800000, v130
	v_max_f32_e32 v131, 0x21800000, v131
	v_pk_mul_f32 v[128:129], v[8:9], v[128:129]
	v_pk_mul_f32 v[130:131], v[10:11], v[130:131]
	s_and_b64 vcc, exec, s[36:37]
	s_mov_b64 s[2:3], -1
	s_cbranch_vccnz .LBB0_139
	v_add_co_u32_e32 v144, vcc, 0x58000, v198
	v_cvt_pk_bf16_f32 v140, v136, v137
	v_cvt_pk_bf16_f32 v141, v138, v139
	v_cvt_pk_bf16_f32 v142, v128, v129
	v_cvt_pk_bf16_f32 v143, v130, v131
	v_addc_co_u32_e32 v145, vcc, 0, v199, vcc
	s_mov_b64 s[2:3], 0
	global_store_dwordx4 v[144:145], v[140:143], off offset:256 sc1

.LBB0_160:
	v_mul_f32_e32 v120, 0xbfb8aa3b, v120
	v_exp_f32_e32 v120, v120
	v_mul_f32_e32 v121, 0xbfb8aa3b, v121
	v_exp_f32_e32 v121, v121
	v_mul_f32_e32 v124, 0xbfb8aa3b, v124
	v_add_f32_e32 v120, 1.0, v120
	v_rcp_f32_e32 v147, v120
	v_add_f32_e32 v120, 1.0, v121
	v_mul_f32_e32 v121, 0xbfb8aa3b, v122
	v_exp_f32_e32 v145, v124
	v_mul_f32_e32 v124, 0xbfb8aa3b, v125
	v_mul_f32_e32 v126, 0xbfb8aa3b, v126
	v_mul_f32_e32 v127, 0xbfb8aa3b, v127
	v_exp_f32_e32 v121, v121
	v_mul_f32_e32 v122, 0xbfb8aa3b, v123
	v_exp_f32_e32 v146, v124
	v_exp_f32_e32 v126, v126
	v_exp_f32_e32 v127, v127
	v_exp_f32_e32 v122, v122
	v_rcp_f32_e32 v123, v120
	v_add_f32_e32 v120, 1.0, v121
	v_add_f32_e32 v145, 1.0, v145
	v_add_f32_e32 v146, 1.0, v146
	v_add_f32_e32 v126, 1.0, v126
	v_add_f32_e32 v127, 1.0, v127
	v_rcp_f32_e32 v148, v120
	v_add_f32_e32 v120, 1.0, v122
	v_mul_f32_e32 v112, 0xbfb8aa3b, v112
	v_rcp_f32_e32 v145, v145
	v_rcp_f32_e32 v146, v146
	v_rcp_f32_e32 v126, v126
	v_rcp_f32_e32 v127, v127
	v_rcp_f32_e32 v149, v120
	v_exp_f32_e32 v112, v112
	v_mul_f32_e32 v113, 0xbfb8aa3b, v113
	v_lshl_or_b32 v138, s95, 8, v143
	v_exp_f32_e32 v113, v113
	v_ashrrev_i32_e32 v139, 31, v138
	v_lshl_add_u32 v144, s86, 8, v140
	v_lshl_add_u64 v[138:139], v[138:139], 1, s[76:77]
	v_mad_i64_i32 v[124:125], s[8:9], v144, s33, v[138:139]
	v_cvt_pk_bf16_f32 v120, v145, v146
	v_cvt_pk_bf16_f32 v121, v126, v127
	v_cvt_pk_bf16_f32 v122, v147, v123
	v_cvt_pk_bf16_f32 v123, v148, v149
	v_add_f32_e32 v112, 1.0, v112
	global_store_dwordx4 v[124:125], v[120:123], off sc1
	v_mul_f32_e32 v116, 0xbfb8aa3b, v116
	v_mul_f32_e32 v117, 0xbfb8aa3b, v117
	v_rcp_f32_e32 v120, v112
	v_add_f32_e32 v112, 1.0, v113
	v_mul_f32_e32 v113, 0xbfb8aa3b, v114
	v_mul_f32_e32 v118, 0xbfb8aa3b, v118
	v_mul_f32_e32 v119, 0xbfb8aa3b, v119
	v_exp_f32_e32 v113, v113
	v_mul_f32_e32 v114, 0xbfb8aa3b, v115
	v_exp_f32_e32 v116, v116
	v_exp_f32_e32 v117, v117
	v_exp_f32_e32 v118, v118
	v_exp_f32_e32 v119, v119
	v_exp_f32_e32 v114, v114
	v_rcp_f32_e32 v115, v112
	v_add_f32_e32 v112, 1.0, v113
	v_add_f32_e32 v116, 1.0, v116
	v_add_f32_e32 v117, 1.0, v117
	v_add_f32_e32 v118, 1.0, v118
	v_add_f32_e32 v119, 1.0, v119
	v_rcp_f32_e32 v121, v112
	v_add_f32_e32 v112, 1.0, v114
	v_rcp_f32_e32 v116, v116
	v_rcp_f32_e32 v117, v117
	v_rcp_f32_e32 v118, v118
	v_rcp_f32_e32 v119, v119
	v_rcp_f32_e32 v122, v112
	v_cvt_pk_bf16_f32 v112, v116, v117
	v_cvt_pk_bf16_f32 v114, v120, v115
	v_cvt_pk_bf16_f32 v113, v118, v119
	v_cvt_pk_bf16_f32 v115, v121, v122
	v_mul_f32_e32 v108, 0xbfb8aa3b, v108
	v_mul_f32_e32 v104, 0xbfb8aa3b, v104
	global_store_dwordx4 v[124:125], v[112:115], off offset:256 sc1
	v_exp_f32_e32 v104, v104
	v_mul_f32_e32 v105, 0xbfb8aa3b, v105
	v_exp_f32_e32 v113, v108
	v_mul_f32_e32 v108, 0xbfb8aa3b, v109
	v_exp_f32_e32 v114, v108
	v_exp_f32_e32 v105, v105
	v_or_b32_e32 v112, 16, v144
	v_add_f32_e32 v104, 1.0, v104
	v_mad_i64_i32 v[108:109], s[8:9], v112, s33, v[138:139]
	v_add_f32_e32 v112, 1.0, v113
	v_add_f32_e32 v113, 1.0, v114
	v_rcp_f32_e32 v114, v104
	v_add_f32_e32 v104, 1.0, v105
	v_mul_f32_e32 v105, 0xbfb8aa3b, v106
	v_mul_f32_e32 v110, 0xbfb8aa3b, v110
	v_mul_f32_e32 v111, 0xbfb8aa3b, v111
	v_exp_f32_e32 v105, v105
	v_mul_f32_e32 v106, 0xbfb8aa3b, v107
	v_exp_f32_e32 v110, v110
	v_exp_f32_e32 v111, v111
	v_exp_f32_e32 v106, v106
	v_rcp_f32_e32 v107, v104
	v_add_f32_e32 v104, 1.0, v105
	v_add_f32_e32 v110, 1.0, v110
	v_add_f32_e32 v111, 1.0, v111
	v_rcp_f32_e32 v115, v104
	v_add_f32_e32 v104, 1.0, v106
	v_mul_f32_e32 v96, 0xbfb8aa3b, v96
	v_rcp_f32_e32 v112, v112
	v_rcp_f32_e32 v113, v113
	v_rcp_f32_e32 v110, v110
	v_rcp_f32_e32 v111, v111
	v_rcp_f32_e32 v116, v104
	v_exp_f32_e32 v96, v96
	v_mul_f32_e32 v97, 0xbfb8aa3b, v97
	v_exp_f32_e32 v97, v97
	v_cvt_pk_bf16_f32 v104, v112, v113
	v_cvt_pk_bf16_f32 v105, v110, v111
	v_cvt_pk_bf16_f32 v106, v114, v107
	v_cvt_pk_bf16_f32 v107, v115, v116
	v_add_f32_e32 v96, 1.0, v96
	global_store_dwordx4 v[108:109], v[104:107], off sc1
	v_mul_f32_e32 v100, 0xbfb8aa3b, v100
	v_mul_f32_e32 v101, 0xbfb8aa3b, v101
	v_rcp_f32_e32 v104, v96
	v_add_f32_e32 v96, 1.0, v97
	v_mul_f32_e32 v97, 0xbfb8aa3b, v98
	v_mul_f32_e32 v102, 0xbfb8aa3b, v102
	v_mul_f32_e32 v103, 0xbfb8aa3b, v103
	v_exp_f32_e32 v97, v97
	v_mul_f32_e32 v98, 0xbfb8aa3b, v99
	v_exp_f32_e32 v100, v100
	v_exp_f32_e32 v101, v101
	v_exp_f32_e32 v102, v102
	v_exp_f32_e32 v103, v103
	v_exp_f32_e32 v98, v98
	v_rcp_f32_e32 v99, v96
	v_add_f32_e32 v96, 1.0, v97
	v_add_f32_e32 v100, 1.0, v100
	v_add_f32_e32 v101, 1.0, v101
	v_add_f32_e32 v102, 1.0, v102
	v_add_f32_e32 v103, 1.0, v103
	v_rcp_f32_e32 v105, v96
	v_add_f32_e32 v96, 1.0, v98
	v_rcp_f32_e32 v100, v100
	v_rcp_f32_e32 v101, v101
	v_rcp_f32_e32 v102, v102
	v_rcp_f32_e32 v103, v103
	v_rcp_f32_e32 v106, v96
	v_cvt_pk_bf16_f32 v96, v100, v101
	v_cvt_pk_bf16_f32 v98, v104, v99
	v_cvt_pk_bf16_f32 v97, v102, v103
	v_cvt_pk_bf16_f32 v99, v105, v106
	v_mul_f32_e32 v92, 0xbfb8aa3b, v92
	v_mul_f32_e32 v88, 0xbfb8aa3b, v88
	global_store_dwordx4 v[108:109], v[96:99], off offset:256 sc1
	v_exp_f32_e32 v88, v88
	v_mul_f32_e32 v89, 0xbfb8aa3b, v89
	v_exp_f32_e32 v97, v92
	v_mul_f32_e32 v92, 0xbfb8aa3b, v93
	v_exp_f32_e32 v98, v92
	v_exp_f32_e32 v89, v89
	v_or_b32_e32 v96, 32, v144
	v_add_f32_e32 v88, 1.0, v88
	v_mad_i64_i32 v[92:93], s[8:9], v96, s33, v[138:139]
	v_add_f32_e32 v96, 1.0, v97
	v_add_f32_e32 v97, 1.0, v98
	v_rcp_f32_e32 v98, v88
	v_add_f32_e32 v88, 1.0, v89
	v_mul_f32_e32 v89, 0xbfb8aa3b, v90
	v_mul_f32_e32 v94, 0xbfb8aa3b, v94
	v_mul_f32_e32 v95, 0xbfb8aa3b, v95
	v_exp_f32_e32 v89, v89
	v_mul_f32_e32 v90, 0xbfb8aa3b, v91
	v_exp_f32_e32 v94, v94
	v_exp_f32_e32 v95, v95
	v_exp_f32_e32 v90, v90
	v_rcp_f32_e32 v91, v88
	v_add_f32_e32 v88, 1.0, v89
	v_add_f32_e32 v94, 1.0, v94
	v_add_f32_e32 v95, 1.0, v95
	v_rcp_f32_e32 v99, v88
	v_add_f32_e32 v88, 1.0, v90
	v_mul_f32_e32 v80, 0xbfb8aa3b, v80
	v_rcp_f32_e32 v96, v96
	v_rcp_f32_e32 v97, v97
	v_rcp_f32_e32 v94, v94
	v_rcp_f32_e32 v95, v95
	v_rcp_f32_e32 v100, v88
	v_exp_f32_e32 v80, v80
	v_mul_f32_e32 v81, 0xbfb8aa3b, v81
	v_exp_f32_e32 v81, v81
	v_cvt_pk_bf16_f32 v88, v96, v97
	v_cvt_pk_bf16_f32 v89, v94, v95
	v_cvt_pk_bf16_f32 v90, v98, v91
	v_cvt_pk_bf16_f32 v91, v99, v100
	v_add_f32_e32 v80, 1.0, v80
	global_store_dwordx4 v[92:93], v[88:91], off sc1
	v_mul_f32_e32 v84, 0xbfb8aa3b, v84
	v_mul_f32_e32 v85, 0xbfb8aa3b, v85
	v_rcp_f32_e32 v88, v80
	v_add_f32_e32 v80, 1.0, v81
	v_mul_f32_e32 v81, 0xbfb8aa3b, v82
	v_mul_f32_e32 v86, 0xbfb8aa3b, v86
	v_mul_f32_e32 v87, 0xbfb8aa3b, v87
	v_exp_f32_e32 v81, v81
	v_mul_f32_e32 v82, 0xbfb8aa3b, v83
	v_exp_f32_e32 v84, v84
	v_exp_f32_e32 v85, v85
	v_exp_f32_e32 v86, v86
	v_exp_f32_e32 v87, v87
	v_exp_f32_e32 v82, v82
	v_rcp_f32_e32 v83, v80
	v_add_f32_e32 v80, 1.0, v81
	v_add_f32_e32 v84, 1.0, v84
	v_add_f32_e32 v85, 1.0, v85
	v_add_f32_e32 v86, 1.0, v86
	v_add_f32_e32 v87, 1.0, v87
	v_rcp_f32_e32 v89, v80
	v_add_f32_e32 v80, 1.0, v82
	v_rcp_f32_e32 v84, v84
	v_rcp_f32_e32 v85, v85
	v_rcp_f32_e32 v86, v86
	v_rcp_f32_e32 v87, v87
	v_rcp_f32_e32 v90, v80
	v_cvt_pk_bf16_f32 v80, v84, v85
	v_cvt_pk_bf16_f32 v82, v88, v83
	v_cvt_pk_bf16_f32 v81, v86, v87
	v_cvt_pk_bf16_f32 v83, v89, v90
	v_mul_f32_e32 v76, 0xbfb8aa3b, v76
	v_mul_f32_e32 v72, 0xbfb8aa3b, v72
	global_store_dwordx4 v[92:93], v[80:83], off offset:256 sc1
	v_exp_f32_e32 v72, v72
	v_mul_f32_e32 v73, 0xbfb8aa3b, v73
	v_exp_f32_e32 v81, v76
	v_mul_f32_e32 v76, 0xbfb8aa3b, v77
	v_exp_f32_e32 v82, v76
	v_exp_f32_e32 v73, v73
	v_or_b32_e32 v80, 48, v144
	v_add_f32_e32 v72, 1.0, v72
	v_mad_i64_i32 v[76:77], s[8:9], v80, s33, v[138:139]
	v_add_f32_e32 v80, 1.0, v81
	v_add_f32_e32 v81, 1.0, v82
	v_rcp_f32_e32 v82, v72
	v_add_f32_e32 v72, 1.0, v73
	v_mul_f32_e32 v73, 0xbfb8aa3b, v74
	v_mul_f32_e32 v78, 0xbfb8aa3b, v78
	v_mul_f32_e32 v79, 0xbfb8aa3b, v79
	v_exp_f32_e32 v73, v73
	v_mul_f32_e32 v74, 0xbfb8aa3b, v75
	v_exp_f32_e32 v78, v78
	v_exp_f32_e32 v79, v79
	v_exp_f32_e32 v74, v74
	v_rcp_f32_e32 v75, v72
	v_add_f32_e32 v72, 1.0, v73
	v_add_f32_e32 v78, 1.0, v78
	v_add_f32_e32 v79, 1.0, v79
	v_rcp_f32_e32 v83, v72
	v_add_f32_e32 v72, 1.0, v74
	v_mul_f32_e32 v64, 0xbfb8aa3b, v64
	v_rcp_f32_e32 v80, v80
	v_rcp_f32_e32 v81, v81
	v_rcp_f32_e32 v78, v78
	v_rcp_f32_e32 v79, v79
	v_rcp_f32_e32 v84, v72
	v_exp_f32_e32 v64, v64
	v_mul_f32_e32 v65, 0xbfb8aa3b, v65
	v_exp_f32_e32 v65, v65
	v_cvt_pk_bf16_f32 v72, v80, v81
	v_cvt_pk_bf16_f32 v73, v78, v79
	v_cvt_pk_bf16_f32 v74, v82, v75
	v_cvt_pk_bf16_f32 v75, v83, v84
	v_add_f32_e32 v64, 1.0, v64
	global_store_dwordx4 v[76:77], v[72:75], off sc1
	v_mul_f32_e32 v68, 0xbfb8aa3b, v68
	v_mul_f32_e32 v69, 0xbfb8aa3b, v69
	v_rcp_f32_e32 v72, v64
	v_add_f32_e32 v64, 1.0, v65
	v_mul_f32_e32 v65, 0xbfb8aa3b, v66
	v_mul_f32_e32 v70, 0xbfb8aa3b, v70
	v_mul_f32_e32 v71, 0xbfb8aa3b, v71
	v_exp_f32_e32 v65, v65
	v_mul_f32_e32 v66, 0xbfb8aa3b, v67
	v_exp_f32_e32 v68, v68
	v_exp_f32_e32 v69, v69
	v_exp_f32_e32 v70, v70
	v_exp_f32_e32 v71, v71
	v_exp_f32_e32 v66, v66
	v_rcp_f32_e32 v67, v64
	v_add_f32_e32 v64, 1.0, v65
	v_add_f32_e32 v68, 1.0, v68
	v_add_f32_e32 v69, 1.0, v69
	v_add_f32_e32 v70, 1.0, v70
	v_add_f32_e32 v71, 1.0, v71
	v_rcp_f32_e32 v73, v64
	v_add_f32_e32 v64, 1.0, v66
	v_rcp_f32_e32 v68, v68
	v_rcp_f32_e32 v69, v69
	v_rcp_f32_e32 v70, v70
	v_rcp_f32_e32 v71, v71
	v_rcp_f32_e32 v74, v64
	v_cvt_pk_bf16_f32 v64, v68, v69
	v_cvt_pk_bf16_f32 v66, v72, v67
	v_cvt_pk_bf16_f32 v65, v70, v71
	v_cvt_pk_bf16_f32 v67, v73, v74
	v_mul_f32_e32 v60, 0xbfb8aa3b, v60
	v_mul_f32_e32 v56, 0xbfb8aa3b, v56
	global_store_dwordx4 v[76:77], v[64:67], off offset:256 sc1
	v_exp_f32_e32 v56, v56
	v_mul_f32_e32 v57, 0xbfb8aa3b, v57
	v_exp_f32_e32 v65, v60
	v_mul_f32_e32 v60, 0xbfb8aa3b, v61
	v_exp_f32_e32 v66, v60
	v_exp_f32_e32 v57, v57
	v_add_u32_e32 v64, 0x80, v144
	v_add_f32_e32 v56, 1.0, v56
	v_mad_i64_i32 v[60:61], s[8:9], v64, s33, v[138:139]
	v_add_f32_e32 v64, 1.0, v65
	v_add_f32_e32 v65, 1.0, v66
	v_rcp_f32_e32 v66, v56
	v_add_f32_e32 v56, 1.0, v57
	v_mul_f32_e32 v57, 0xbfb8aa3b, v58
	v_mul_f32_e32 v62, 0xbfb8aa3b, v62
	v_mul_f32_e32 v63, 0xbfb8aa3b, v63
	v_exp_f32_e32 v57, v57
	v_mul_f32_e32 v58, 0xbfb8aa3b, v59
	v_exp_f32_e32 v62, v62
	v_exp_f32_e32 v63, v63
	v_exp_f32_e32 v58, v58
	v_rcp_f32_e32 v59, v56
	v_add_f32_e32 v56, 1.0, v57
	v_add_f32_e32 v62, 1.0, v62
	v_add_f32_e32 v63, 1.0, v63
	v_rcp_f32_e32 v67, v56
	v_add_f32_e32 v56, 1.0, v58
	v_mul_f32_e32 v48, 0xbfb8aa3b, v48
	v_rcp_f32_e32 v64, v64
	v_rcp_f32_e32 v65, v65
	v_rcp_f32_e32 v62, v62
	v_rcp_f32_e32 v63, v63
	v_rcp_f32_e32 v68, v56
	v_exp_f32_e32 v48, v48
	v_mul_f32_e32 v49, 0xbfb8aa3b, v49
	v_exp_f32_e32 v49, v49
	v_cvt_pk_bf16_f32 v56, v64, v65
	v_cvt_pk_bf16_f32 v57, v62, v63
	v_cvt_pk_bf16_f32 v58, v66, v59
	v_cvt_pk_bf16_f32 v59, v67, v68
	v_add_f32_e32 v48, 1.0, v48
	global_store_dwordx4 v[60:61], v[56:59], off sc1
	v_mul_f32_e32 v52, 0xbfb8aa3b, v52
	v_mul_f32_e32 v53, 0xbfb8aa3b, v53
	v_rcp_f32_e32 v56, v48
	v_add_f32_e32 v48, 1.0, v49
	v_mul_f32_e32 v49, 0xbfb8aa3b, v50
	v_mul_f32_e32 v54, 0xbfb8aa3b, v54
	v_mul_f32_e32 v55, 0xbfb8aa3b, v55
	v_exp_f32_e32 v49, v49
	v_mul_f32_e32 v50, 0xbfb8aa3b, v51
	v_exp_f32_e32 v52, v52
	v_exp_f32_e32 v53, v53
	v_exp_f32_e32 v54, v54
	v_exp_f32_e32 v55, v55
	v_exp_f32_e32 v50, v50
	v_rcp_f32_e32 v51, v48
	v_add_f32_e32 v48, 1.0, v49
	v_add_f32_e32 v52, 1.0, v52
	v_add_f32_e32 v53, 1.0, v53
	v_add_f32_e32 v54, 1.0, v54
	v_add_f32_e32 v55, 1.0, v55
	v_rcp_f32_e32 v57, v48
	v_add_f32_e32 v48, 1.0, v50
	v_rcp_f32_e32 v52, v52
	v_rcp_f32_e32 v53, v53
	v_rcp_f32_e32 v54, v54
	v_rcp_f32_e32 v55, v55
	v_rcp_f32_e32 v58, v48
	v_cvt_pk_bf16_f32 v48, v52, v53
	v_cvt_pk_bf16_f32 v50, v56, v51
	v_cvt_pk_bf16_f32 v49, v54, v55
	v_cvt_pk_bf16_f32 v51, v57, v58
	v_mul_f32_e32 v44, 0xbfb8aa3b, v44
	v_mul_f32_e32 v40, 0xbfb8aa3b, v40
	global_store_dwordx4 v[60:61], v[48:51], off offset:256 sc1
	v_exp_f32_e32 v40, v40
	v_mul_f32_e32 v41, 0xbfb8aa3b, v41
	v_exp_f32_e32 v49, v44
	v_mul_f32_e32 v44, 0xbfb8aa3b, v45
	v_exp_f32_e32 v50, v44
	v_exp_f32_e32 v41, v41
	v_add_u32_e32 v48, 0x90, v144
	v_add_f32_e32 v40, 1.0, v40
	v_mad_i64_i32 v[44:45], s[8:9], v48, s33, v[138:139]
	v_add_f32_e32 v48, 1.0, v49
	v_add_f32_e32 v49, 1.0, v50
	v_rcp_f32_e32 v50, v40
	v_add_f32_e32 v40, 1.0, v41
	v_mul_f32_e32 v41, 0xbfb8aa3b, v42
	v_mul_f32_e32 v46, 0xbfb8aa3b, v46
	v_mul_f32_e32 v47, 0xbfb8aa3b, v47
	v_exp_f32_e32 v41, v41
	v_mul_f32_e32 v42, 0xbfb8aa3b, v43
	v_exp_f32_e32 v46, v46
	v_exp_f32_e32 v47, v47
	v_exp_f32_e32 v42, v42
	v_rcp_f32_e32 v43, v40
	v_add_f32_e32 v40, 1.0, v41
	v_add_f32_e32 v46, 1.0, v46
	v_add_f32_e32 v47, 1.0, v47
	v_rcp_f32_e32 v51, v40
	v_add_f32_e32 v40, 1.0, v42
	v_mul_f32_e32 v32, 0xbfb8aa3b, v32
	v_rcp_f32_e32 v48, v48
	v_rcp_f32_e32 v49, v49
	v_rcp_f32_e32 v46, v46
	v_rcp_f32_e32 v47, v47
	v_rcp_f32_e32 v52, v40
	v_exp_f32_e32 v32, v32
	v_mul_f32_e32 v33, 0xbfb8aa3b, v33
	v_exp_f32_e32 v33, v33
	v_cvt_pk_bf16_f32 v40, v48, v49
	v_cvt_pk_bf16_f32 v41, v46, v47
	v_cvt_pk_bf16_f32 v42, v50, v43
	v_cvt_pk_bf16_f32 v43, v51, v52
	v_add_f32_e32 v32, 1.0, v32
	global_store_dwordx4 v[44:45], v[40:43], off sc1
	v_mul_f32_e32 v36, 0xbfb8aa3b, v36
	v_mul_f32_e32 v37, 0xbfb8aa3b, v37
	v_rcp_f32_e32 v40, v32
	v_add_f32_e32 v32, 1.0, v33
	v_mul_f32_e32 v33, 0xbfb8aa3b, v34
	v_mul_f32_e32 v38, 0xbfb8aa3b, v38
	v_mul_f32_e32 v39, 0xbfb8aa3b, v39
	v_exp_f32_e32 v33, v33
	v_mul_f32_e32 v34, 0xbfb8aa3b, v35
	v_exp_f32_e32 v36, v36
	v_exp_f32_e32 v37, v37
	v_exp_f32_e32 v38, v38
	v_exp_f32_e32 v39, v39
	v_exp_f32_e32 v34, v34
	v_rcp_f32_e32 v35, v32
	v_add_f32_e32 v32, 1.0, v33
	v_add_f32_e32 v36, 1.0, v36
	v_add_f32_e32 v37, 1.0, v37
	v_add_f32_e32 v38, 1.0, v38
	v_add_f32_e32 v39, 1.0, v39
	v_rcp_f32_e32 v41, v32
	v_add_f32_e32 v32, 1.0, v34
	v_rcp_f32_e32 v36, v36
	v_rcp_f32_e32 v37, v37
	v_rcp_f32_e32 v38, v38
	v_rcp_f32_e32 v39, v39
	v_rcp_f32_e32 v42, v32
	v_cvt_pk_bf16_f32 v32, v36, v37
	v_cvt_pk_bf16_f32 v34, v40, v35
	v_cvt_pk_bf16_f32 v33, v38, v39
	v_cvt_pk_bf16_f32 v35, v41, v42
	v_mul_f32_e32 v28, 0xbfb8aa3b, v28
	v_mul_f32_e32 v24, 0xbfb8aa3b, v24
	global_store_dwordx4 v[44:45], v[32:35], off offset:256 sc1
	v_exp_f32_e32 v24, v24
	v_mul_f32_e32 v25, 0xbfb8aa3b, v25
	v_exp_f32_e32 v33, v28
	v_mul_f32_e32 v28, 0xbfb8aa3b, v29
	v_exp_f32_e32 v34, v28
	v_exp_f32_e32 v25, v25
	v_add_u32_e32 v32, 0xa0, v144
	v_add_f32_e32 v24, 1.0, v24
	v_mad_i64_i32 v[28:29], s[8:9], v32, s33, v[138:139]
	v_add_f32_e32 v32, 1.0, v33
	v_add_f32_e32 v33, 1.0, v34
	v_rcp_f32_e32 v34, v24
	v_add_f32_e32 v24, 1.0, v25
	v_mul_f32_e32 v25, 0xbfb8aa3b, v26
	v_mul_f32_e32 v30, 0xbfb8aa3b, v30
	v_mul_f32_e32 v31, 0xbfb8aa3b, v31
	v_exp_f32_e32 v25, v25
	v_mul_f32_e32 v26, 0xbfb8aa3b, v27
	v_exp_f32_e32 v30, v30
	v_exp_f32_e32 v31, v31
	v_exp_f32_e32 v26, v26
	v_rcp_f32_e32 v27, v24
	v_add_f32_e32 v24, 1.0, v25
	v_add_f32_e32 v30, 1.0, v30
	v_add_f32_e32 v31, 1.0, v31
	v_rcp_f32_e32 v35, v24
	v_add_f32_e32 v24, 1.0, v26
	v_mul_f32_e32 v16, 0xbfb8aa3b, v16
	v_rcp_f32_e32 v32, v32
	v_rcp_f32_e32 v33, v33
	v_rcp_f32_e32 v30, v30
	v_rcp_f32_e32 v31, v31
	v_rcp_f32_e32 v36, v24
	v_exp_f32_e32 v16, v16
	v_mul_f32_e32 v17, 0xbfb8aa3b, v17
	v_exp_f32_e32 v17, v17
	v_cvt_pk_bf16_f32 v24, v32, v33
	v_cvt_pk_bf16_f32 v25, v30, v31
	v_cvt_pk_bf16_f32 v26, v34, v27
	v_cvt_pk_bf16_f32 v27, v35, v36
	v_add_f32_e32 v16, 1.0, v16
	global_store_dwordx4 v[28:29], v[24:27], off sc1
	v_mul_f32_e32 v20, 0xbfb8aa3b, v20
	v_mul_f32_e32 v21, 0xbfb8aa3b, v21
	v_rcp_f32_e32 v24, v16
	v_add_f32_e32 v16, 1.0, v17
	v_mul_f32_e32 v17, 0xbfb8aa3b, v18
	v_mul_f32_e32 v22, 0xbfb8aa3b, v22
	v_mul_f32_e32 v23, 0xbfb8aa3b, v23
	v_exp_f32_e32 v17, v17
	v_mul_f32_e32 v18, 0xbfb8aa3b, v19
	v_exp_f32_e32 v20, v20
	v_exp_f32_e32 v21, v21
	v_exp_f32_e32 v22, v22
	v_exp_f32_e32 v23, v23
	v_exp_f32_e32 v18, v18
	v_rcp_f32_e32 v19, v16
	v_add_f32_e32 v16, 1.0, v17
	v_add_f32_e32 v20, 1.0, v20
	v_add_f32_e32 v21, 1.0, v21
	v_add_f32_e32 v22, 1.0, v22
	v_add_f32_e32 v23, 1.0, v23
	v_rcp_f32_e32 v25, v16
	v_add_f32_e32 v16, 1.0, v18
	v_rcp_f32_e32 v20, v20
	v_rcp_f32_e32 v21, v21
	v_rcp_f32_e32 v22, v22
	v_rcp_f32_e32 v23, v23
	v_rcp_f32_e32 v26, v16
	v_cvt_pk_bf16_f32 v16, v20, v21
	v_cvt_pk_bf16_f32 v18, v24, v19
	v_cvt_pk_bf16_f32 v17, v22, v23
	v_cvt_pk_bf16_f32 v19, v25, v26
	v_mul_f32_e32 v12, 0xbfb8aa3b, v12
	v_mul_f32_e32 v8, 0xbfb8aa3b, v8
	global_store_dwordx4 v[28:29], v[16:19], off offset:256 sc1
	v_exp_f32_e32 v8, v8
	v_mul_f32_e32 v9, 0xbfb8aa3b, v9
	v_exp_f32_e32 v17, v12
	v_mul_f32_e32 v12, 0xbfb8aa3b, v13
	v_exp_f32_e32 v18, v12
	v_exp_f32_e32 v9, v9
	v_add_u32_e32 v16, 0xb0, v144
	v_add_f32_e32 v8, 1.0, v8
	v_mad_i64_i32 v[12:13], s[8:9], v16, s33, v[138:139]
	v_add_f32_e32 v16, 1.0, v17
	v_add_f32_e32 v17, 1.0, v18
	v_rcp_f32_e32 v18, v8
	v_add_f32_e32 v8, 1.0, v9
	v_mul_f32_e32 v9, 0xbfb8aa3b, v10
	v_mul_f32_e32 v14, 0xbfb8aa3b, v14
	v_mul_f32_e32 v15, 0xbfb8aa3b, v15
	v_exp_f32_e32 v9, v9
	v_mul_f32_e32 v10, 0xbfb8aa3b, v11
	v_exp_f32_e32 v14, v14
	v_exp_f32_e32 v15, v15
	v_exp_f32_e32 v10, v10
	v_rcp_f32_e32 v11, v8
	v_add_f32_e32 v8, 1.0, v9
	v_add_f32_e32 v14, 1.0, v14
	v_add_f32_e32 v15, 1.0, v15
	v_rcp_f32_e32 v19, v8
	v_add_f32_e32 v8, 1.0, v10
	v_mul_f32_e32 v0, 0xbfb8aa3b, v0
	v_rcp_f32_e32 v16, v16
	v_rcp_f32_e32 v17, v17
	v_rcp_f32_e32 v14, v14
	v_rcp_f32_e32 v15, v15
	v_rcp_f32_e32 v20, v8
	v_exp_f32_e32 v0, v0
	v_mul_f32_e32 v1, 0xbfb8aa3b, v1
	v_exp_f32_e32 v1, v1
	v_cvt_pk_bf16_f32 v8, v16, v17
	v_cvt_pk_bf16_f32 v9, v14, v15
	v_cvt_pk_bf16_f32 v10, v18, v11
	v_cvt_pk_bf16_f32 v11, v19, v20
	v_add_f32_e32 v0, 1.0, v0
	global_store_dwordx4 v[12:13], v[8:11], off sc1
	v_mul_f32_e32 v4, 0xbfb8aa3b, v4
	v_mul_f32_e32 v5, 0xbfb8aa3b, v5
	v_rcp_f32_e32 v8, v0
	v_add_f32_e32 v0, 1.0, v1
	v_mul_f32_e32 v1, 0xbfb8aa3b, v2
	v_mul_f32_e32 v6, 0xbfb8aa3b, v6
	v_mul_f32_e32 v7, 0xbfb8aa3b, v7
	v_exp_f32_e32 v1, v1
	v_mul_f32_e32 v2, 0xbfb8aa3b, v3
	v_exp_f32_e32 v4, v4
	v_exp_f32_e32 v5, v5
	v_exp_f32_e32 v6, v6
	v_exp_f32_e32 v7, v7
	v_exp_f32_e32 v2, v2
	v_rcp_f32_e32 v3, v0
	v_add_f32_e32 v0, 1.0, v1
	v_add_f32_e32 v4, 1.0, v4
	v_add_f32_e32 v5, 1.0, v5
	v_add_f32_e32 v6, 1.0, v6
	v_add_f32_e32 v7, 1.0, v7
	v_rcp_f32_e32 v9, v0
	v_add_f32_e32 v0, 1.0, v2
	v_rcp_f32_e32 v4, v4
	v_rcp_f32_e32 v5, v5
	v_rcp_f32_e32 v6, v6
	v_rcp_f32_e32 v7, v7
	v_rcp_f32_e32 v10, v0
	v_cvt_pk_bf16_f32 v0, v4, v5
	v_cvt_pk_bf16_f32 v2, v8, v3
	v_cvt_pk_bf16_f32 v1, v6, v7
	v_cvt_pk_bf16_f32 v3, v9, v10
	s_andn2_b64 vcc, exec, s[36:37]
	s_mov_b64 s[8:9], -1
	global_store_dwordx4 v[12:13], v[0:3], off offset:256 sc1
	s_cbranch_vccnz .LBB0_153
	s_andn2_b64 vcc, exec, s[38:39]
	s_cbranch_vccnz .LBB0_152
	s_barrier
	s_branch .LBB0_152

.LBB0_200:
	s_or_b64 exec, exec, s[2:3]
	s_movk_i32 s2, 0x840
	v_mad_u32_u24 v12, v108, s2, v105
	v_add_u32_e32 v4, 0xffffff7c, v12
	v_cmp_eq_u32_e64 s[36:37], 0, v108
	v_cmp_ne_u32_e32 vcc, 0, v108
	v_mov_b32_e32 v25, 0
	v_lshl_add_u32 v14, v15, 2, v4
	v_mov_b32_e32 v26, 0
	s_and_saveexec_b64 s[2:3], vcc
	ds_read_b32 v26, v14
	s_or_b64 exec, exec, s[2:3]
	v_lshlrev_b32_e32 v13, 2, v15
	s_and_saveexec_b64 s[2:3], vcc
	s_movk_i32 s4, 0xff80
	v_add3_u32 v4, v12, v13, s4
	ds_read_b32 v25, v4
	s_or_b64 exec, exec, s[2:3]
	v_mul_u32_u24_e32 v4, 0x84, v110
	v_add3_u32 v11, v105, v4, v13
	ds_read2_b32 v[4:5], v11 offset1:1
	v_mov_b32_e32 v27, 0
	v_mov_b32_e32 v28, 0
	s_and_saveexec_b64 s[2:3], vcc
	ds_read_b32 v28, v14 offset:8
	s_or_b64 exec, exec, s[2:3]
	s_and_saveexec_b64 s[2:3], vcc
	s_movk_i32 s4, 0xff88
	v_add3_u32 v6, v12, v13, s4
	ds_read_b32 v27, v6
	s_or_b64 exec, exec, s[2:3]
	ds_read2_b32 v[6:7], v11 offset0:2 offset1:3
	v_mov_b32_e32 v20, 0
	v_mov_b32_e32 v21, 0
	s_and_saveexec_b64 s[2:3], vcc
	ds_read_b32 v21, v14 offset:16
	s_or_b64 exec, exec, s[2:3]
	s_and_saveexec_b64 s[2:3], vcc
	s_movk_i32 s4, 0xff90
	v_add3_u32 v8, v12, v13, s4
	ds_read_b32 v20, v8
	s_or_b64 exec, exec, s[2:3]
	ds_read2_b32 v[8:9], v11 offset0:4 offset1:5
	v_mov_b32_e32 v22, 0
	v_mov_b32_e32 v23, 0
	s_and_saveexec_b64 s[2:3], vcc
	ds_read_b32 v23, v14 offset:24
	s_or_b64 exec, exec, s[2:3]
	s_and_saveexec_b64 s[2:3], vcc
	s_movk_i32 s4, 0xff98
	v_add3_u32 v12, v12, v13, s4
	ds_read_b32 v22, v12
	s_or_b64 exec, exec, s[2:3]
	s_waitcnt lgkmcnt(2)
	v_sub_f32_e32 v12, v4, v26
	v_sub_f32_e32 v13, v5, v25
	v_mul_f32_e32 v4, 0x3fb8aa3b, v4
	v_mul_f32_e32 v5, 0x3fb8aa3b, v5
	v_exp_f32_e32 v4, v4
	v_exp_f32_e32 v5, v5
	v_mul_f32_e32 v12, 0x3fb8aa3b, v12
	v_mul_f32_e32 v13, 0x3fb8aa3b, v13
	v_exp_f32_e32 v12, v12
	v_exp_f32_e32 v13, v13
	v_lshlrev_b32_e32 v16, 16, v0
	v_and_b32_e32 v17, 0xffff0000, v0
	s_mov_b32 s2, 0x3e3504f3
	v_pk_mul_f32 v[16:17], v[16:17], s[2:3] op_sel_hi:[1,0]
	s_movk_i32 s4, 0x300
	v_pk_mul_f32 v[4:5], v[16:17], v[4:5]
	v_pk_mul_f32 v[12:13], v[16:17], v[12:13]
	v_cvt_pk_bf16_f32 v4, v4, v5
	s_waitcnt lgkmcnt(1)
	v_sub_f32_e32 v5, v6, v28
	v_mul_f32_e32 v5, 0x3fb8aa3b, v5
	v_cvt_pk_bf16_f32 v0, v12, v13
	v_exp_f32_e32 v12, v5
	v_sub_f32_e32 v5, v7, v27
	v_mul_f32_e32 v5, 0x3fb8aa3b, v5
	v_exp_f32_e32 v13, v5
	v_mul_f32_e32 v5, 0x3fb8aa3b, v6
	v_exp_f32_e32 v6, v5
	v_mul_f32_e32 v5, 0x3fb8aa3b, v7
	v_exp_f32_e32 v7, v5
	v_lshlrev_b32_e32 v16, 16, v1
	v_and_b32_e32 v17, 0xffff0000, v1
	v_pk_mul_f32 v[16:17], v[16:17], s[2:3] op_sel_hi:[1,0]
	v_or_b32_e32 v31, 2, v24
	v_pk_mul_f32 v[6:7], v[16:17], v[6:7]
	v_pk_mul_f32 v[12:13], v[16:17], v[12:13]
	v_cvt_pk_bf16_f32 v5, v6, v7
	s_waitcnt lgkmcnt(0)
	v_sub_f32_e32 v6, v8, v21
	v_sub_f32_e32 v7, v9, v20
	v_mul_f32_e32 v6, 0x3fb8aa3b, v6
	v_mul_f32_e32 v7, 0x3fb8aa3b, v7
	v_exp_f32_e32 v6, v6
	v_exp_f32_e32 v7, v7
	v_mul_f32_e32 v8, 0x3fb8aa3b, v8
	v_mul_f32_e32 v9, 0x3fb8aa3b, v9
	v_exp_f32_e32 v8, v8
	v_exp_f32_e32 v9, v9
	v_cvt_pk_bf16_f32 v1, v12, v13
	v_lshlrev_b32_e32 v12, 16, v2
	v_and_b32_e32 v13, 0xffff0000, v2
	v_pk_mul_f32 v[12:13], v[12:13], s[2:3] op_sel_hi:[1,0]
	v_lshlrev_b32_e32 v16, 16, v3
	v_pk_mul_f32 v[6:7], v[12:13], v[6:7]
	v_and_b32_e32 v17, 0xffff0000, v3
	v_cvt_pk_bf16_f32 v2, v6, v7
	v_pk_mul_f32 v[6:7], v[12:13], v[8:9]
	ds_read2_b32 v[8:9], v11 offset0:6 offset1:7
	v_cvt_pk_bf16_f32 v6, v6, v7
	v_pk_mul_f32 v[16:17], v[16:17], s[2:3] op_sel_hi:[1,0]
	v_or_b32_e32 v30, 3, v24
	s_waitcnt lgkmcnt(0)
	v_sub_f32_e32 v7, v8, v23
	v_mul_f32_e32 v7, 0x3fb8aa3b, v7
	v_exp_f32_e32 v12, v7
	v_sub_f32_e32 v7, v9, v22
	v_mul_f32_e32 v7, 0x3fb8aa3b, v7
	v_exp_f32_e32 v13, v7
	v_mul_f32_e32 v7, 0x3fb8aa3b, v8
	v_exp_f32_e32 v8, v7
	v_mul_f32_e32 v7, 0x3fb8aa3b, v9
	v_exp_f32_e32 v9, v7
	v_pk_mul_f32 v[12:13], v[16:17], v[12:13]
	v_pk_mul_f32 v[8:9], v[16:17], v[8:9]
	s_nop 0
	v_cvt_pk_bf16_f32 v7, v8, v9
	v_mov_b64_e32 v[8:9], s[68:69]
	v_mad_u64_u32 v[8:9], s[2:3], v100, s4, v[8:9]
	v_cvt_pk_bf16_f32 v3, v12, v13
	v_mov_b32_e32 v12, v9
	v_mad_u64_u32 v[12:13], s[2:3], v101, s4, v[12:13]
	v_mov_b32_e32 v9, v12
	v_lshlrev_b32_e32 v12, 1, v109
	v_mov_b32_e32 v13, v177
	v_lshl_add_u64 v[8:9], v[8:9], 0, v[12:13]
	v_lshlrev_b32_e32 v12, 1, v15
	v_lshl_add_u64 v[8:9], v[8:9], 0, v[12:13]
	s_mov_b32 s2, 0xece4000
	v_add_co_u32_e64 v8, s[38:39], s2, v8
	s_nop 1
	v_addc_co_u32_e64 v9, s[38:39], 0, v9, s[38:39]
	global_store_dwordx4 v[8:9], v[4:7], off offset:512 sc1
	s_nop 1
	v_mad_u32_u24 v4, v107, 33, v15
	v_lshl_add_u32 v29, v4, 2, v105
	ds_read2_b32 v[4:5], v29 offset1:1
	v_add_u32_e32 v6, 0x4400, v29
	ds_read2_b32 v[6:7], v6 offset1:1
	s_waitcnt lgkmcnt(1)
	v_sub_f32_e32 v4, v26, v4
	v_sub_f32_e32 v5, v25, v5
	v_min_f32_e32 v4, 0x42a00000, v4
	v_min_f32_e32 v5, 0x42a00000, v5
	v_mul_f32_e32 v4, 0x3fb8aa3b, v4
	v_mul_f32_e32 v5, 0x3fb8aa3b, v5
	v_exp_f32_e32 v4, v4
	v_exp_f32_e32 v5, v5
	s_waitcnt lgkmcnt(0)
	v_pk_mul_f32 v[4:5], v[6:7], v[4:5]
	ds_read2_b32 v[6:7], v29 offset0:2 offset1:3
	v_cvt_pk_bf16_f32 v4, v4, v5
	v_add_u32_e32 v5, 0x4408, v29
	ds_read2_b32 v[8:9], v5 offset1:1
	s_waitcnt lgkmcnt(1)
	v_sub_f32_e32 v6, v28, v6
	v_sub_f32_e32 v7, v27, v7
	v_min_f32_e32 v6, 0x42a00000, v6
	v_min_f32_e32 v7, 0x42a00000, v7
	v_mul_f32_e32 v6, 0x3fb8aa3b, v6
	v_mul_f32_e32 v7, 0x3fb8aa3b, v7
	v_exp_f32_e32 v6, v6
	v_exp_f32_e32 v7, v7
	s_waitcnt lgkmcnt(0)
	v_pk_mul_f32 v[6:7], v[8:9], v[6:7]
	s_nop 0
	v_cvt_pk_bf16_f32 v5, v6, v7
	ds_read2_b32 v[6:7], v29 offset0:4 offset1:5
	v_add_u32_e32 v8, 0x4410, v29
	ds_read2_b32 v[8:9], v8 offset1:1
	s_waitcnt lgkmcnt(1)
	v_sub_f32_e32 v6, v21, v6
	v_sub_f32_e32 v7, v20, v7
	v_min_f32_e32 v6, 0x42a00000, v6
	v_min_f32_e32 v7, 0x42a00000, v7
	v_mul_f32_e32 v6, 0x3fb8aa3b, v6
	v_mul_f32_e32 v7, 0x3fb8aa3b, v7
	v_exp_f32_e32 v6, v6
	v_exp_f32_e32 v7, v7
	s_waitcnt lgkmcnt(0)
	v_pk_mul_f32 v[6:7], v[8:9], v[6:7]
	ds_read2_b32 v[8:9], v29 offset0:6 offset1:7
	v_cvt_pk_bf16_f32 v6, v6, v7
	v_add_u32_e32 v7, 0x4418, v29
	ds_read2_b32 v[12:13], v7 offset1:1
	s_waitcnt lgkmcnt(1)
	v_sub_f32_e32 v8, v23, v8
	v_sub_f32_e32 v9, v22, v9
	v_min_f32_e32 v8, 0x42a00000, v8
	v_min_f32_e32 v9, 0x42a00000, v9
	v_mul_f32_e32 v8, 0x3fb8aa3b, v8
	v_mul_f32_e32 v9, 0x3fb8aa3b, v9
	v_exp_f32_e32 v8, v8
	v_exp_f32_e32 v9, v9
	s_waitcnt lgkmcnt(0)
	v_pk_mul_f32 v[8:9], v[12:13], v[8:9]
	s_nop 0
	v_cvt_pk_bf16_f32 v7, v8, v9
	v_mov_b32_e32 v8, 0
	s_nop 0
	v_mfma_f32_16x16x32_bf16 v[4:7], v[4:7], v[0:3], 0
	s_and_saveexec_b64 s[2:3], s[36:37]
	v_cmp_gt_u32_e64 s[36:37], v24, v107
	s_nop 5
	v_cndmask_b32_e64 v9, v4, 0, s[36:37]
	v_cmp_lt_u32_e64 s[36:37], v24, v107
	s_nop 1
	v_cndmask_b32_e64 v4, v9, v4, s[36:37]
	v_cndmask_b32_e64 v5, 0, v5, s[36:37]
	v_cmp_le_u32_e64 s[36:37], v31, v107
	s_nop 1
	v_cndmask_b32_e64 v6, 0, v6, s[36:37]
	v_cmp_le_u32_e64 s[36:37], v30, v107
	s_nop 1
	v_cndmask_b32_e64 v7, 0, v7, s[36:37]
	s_or_b64 exec, exec, s[2:3]
	v_mov_b32_e32 v16, 0
	v_mov_b32_e32 v17, 0
	v_mov_b32_e32 v18, 0
	v_mov_b32_e32 v19, 0
	s_and_saveexec_b64 s[4:5], vcc
	s_cbranch_execz .LBB0_222
	v_mad_u32_u24 v9, v10, 33, v15
	v_lshl_add_u32 v9, v9, 2, v105
	ds_read2_b32 v[10:11], v9 offset1:1
	v_add_u32_e32 v12, 0x4400, v9
	ds_read2_b32 v[12:13], v12 offset1:1
	v_add_u32_e32 v14, 0x4410, v9
	v_cmp_eq_u32_e32 vcc, 1, v108
	s_waitcnt lgkmcnt(1)
	v_sub_f32_e32 v10, v26, v10
	v_sub_f32_e32 v11, v25, v11
	v_min_f32_e32 v10, 0x42a00000, v10
	v_min_f32_e32 v11, 0x42a00000, v11
	v_mul_f32_e32 v10, 0x3fb8aa3b, v10
	v_mul_f32_e32 v11, 0x3fb8aa3b, v11
	v_exp_f32_e32 v10, v10
	v_exp_f32_e32 v11, v11
	s_waitcnt lgkmcnt(0)
	v_pk_mul_f32 v[10:11], v[12:13], v[10:11]
	ds_read2_b32 v[12:13], v9 offset0:2 offset1:3
	v_cvt_pk_bf16_f32 v10, v10, v11
	v_add_u32_e32 v11, 0x4408, v9
	ds_read2_b32 v[16:17], v11 offset1:1
	s_waitcnt lgkmcnt(1)
	v_sub_f32_e32 v12, v28, v12
	v_sub_f32_e32 v13, v27, v13
	v_min_f32_e32 v12, 0x42a00000, v12
	v_min_f32_e32 v13, 0x42a00000, v13
	v_mul_f32_e32 v12, 0x3fb8aa3b, v12
	v_mul_f32_e32 v13, 0x3fb8aa3b, v13
	v_exp_f32_e32 v12, v12
	v_exp_f32_e32 v13, v13
	s_waitcnt lgkmcnt(0)
	v_pk_mul_f32 v[12:13], v[16:17], v[12:13]
	s_nop 0
	v_cvt_pk_bf16_f32 v11, v12, v13
	ds_read2_b32 v[12:13], v9 offset0:4 offset1:5
	ds_read2_b32 v[16:17], v14 offset1:1
	s_waitcnt lgkmcnt(1)
	v_sub_f32_e32 v12, v21, v12
	v_sub_f32_e32 v13, v20, v13
	v_min_f32_e32 v12, 0x42a00000, v12
	v_min_f32_e32 v13, 0x42a00000, v13
	v_mul_f32_e32 v12, 0x3fb8aa3b, v12
	v_mul_f32_e32 v13, 0x3fb8aa3b, v13
	v_exp_f32_e32 v12, v12
	v_exp_f32_e32 v13, v13
	s_waitcnt lgkmcnt(0)
	v_pk_mul_f32 v[12:13], v[16:17], v[12:13]
	ds_read2_b32 v[16:17], v9 offset0:6 offset1:7
	v_cvt_pk_bf16_f32 v12, v12, v13
	v_add_u32_e32 v13, 0x4418, v9
	ds_read2_b32 v[18:19], v13 offset1:1
	s_waitcnt lgkmcnt(1)
	v_sub_f32_e32 v9, v23, v16
	v_min_f32_e32 v9, 0x42a00000, v9
	v_mul_f32_e32 v9, 0x3fb8aa3b, v9
	v_exp_f32_e32 v16, v9
	v_sub_f32_e32 v9, v22, v17
	v_min_f32_e32 v9, 0x42a00000, v9
	v_mul_f32_e32 v9, 0x3fb8aa3b, v9
	v_exp_f32_e32 v17, v9
	s_waitcnt lgkmcnt(0)
	v_pk_mul_f32 v[16:17], v[18:19], v[16:17]
	s_nop 0
	v_cvt_pk_bf16_f32 v13, v16, v17
	s_nop 1
	v_mfma_f32_16x16x32_bf16 v[16:19], v[10:13], v[0:3], 0
	s_and_saveexec_b64 s[2:3], vcc
	s_cbranch_execz .LBB0_221
	v_cmp_gt_u32_e32 vcc, v24, v107
	s_nop 4
	v_cndmask_b32_e32 v9, v18, v18, vcc
	v_cndmask_b32_e32 v10, v19, v19, vcc
	v_cndmask_b32_e64 v11, v16, 0, vcc
	v_cmp_lt_u32_e32 vcc, v24, v107
	s_nop 1
	v_cndmask_b32_e32 v16, v11, v16, vcc
	v_cndmask_b32_e32 v10, v10, v19, vcc
	v_cndmask_b32_e32 v9, v9, v18, vcc
	v_cndmask_b32_e32 v17, 0, v17, vcc
	v_cmp_le_u32_e32 vcc, v31, v107
	s_nop 1
	v_cndmask_b32_e32 v18, 0, v9, vcc
	v_cmp_le_u32_e32 vcc, v30, v107
	s_nop 1
	v_cndmask_b32_e32 v19, 0, v10, vcc

.LBB0_244:
	s_or_b64 exec, exec, s[2:3]
	s_movk_i32 s2, 0x1040
	v_mad_u32_u24 v23, v27, s2, v28
	v_add_u32_e32 v8, 0xfffffefc, v23
	v_cmp_eq_u32_e64 s[36:37], 0, v27
	v_cmp_ne_u32_e32 vcc, 0, v27
	v_mov_b32_e32 v32, 0
	v_lshl_add_u32 v50, v29, 2, v8
	v_mov_b32_e32 v33, 0
	s_and_saveexec_b64 s[2:3], vcc
	ds_read_b32 v33, v50
	s_or_b64 exec, exec, s[2:3]
	v_lshlrev_b32_e32 v49, 2, v29
	s_and_saveexec_b64 s[2:3], vcc
	s_movk_i32 s4, 0xff00
	v_add3_u32 v8, v23, v49, s4
	ds_read_b32 v32, v8
	s_or_b64 exec, exec, s[2:3]
	v_mul_u32_u24_e32 v8, 0x104, v19
	v_add3_u32 v22, v28, v8, v49
	ds_read2_b32 v[8:9], v22 offset1:1
	v_mov_b32_e32 v36, 0
	v_mov_b32_e32 v38, 0
	s_and_saveexec_b64 s[2:3], vcc
	ds_read_b32 v38, v50 offset:8
	s_or_b64 exec, exec, s[2:3]
	s_and_saveexec_b64 s[2:3], vcc
	s_movk_i32 s4, 0xff08
	v_add3_u32 v10, v23, v49, s4
	ds_read_b32 v36, v10
	s_or_b64 exec, exec, s[2:3]
	ds_read2_b32 v[10:11], v22 offset0:2 offset1:3
	v_mov_b32_e32 v39, 0
	v_mov_b32_e32 v42, 0
	s_and_saveexec_b64 s[2:3], vcc
	ds_read_b32 v42, v50 offset:16
	s_or_b64 exec, exec, s[2:3]
	s_and_saveexec_b64 s[2:3], vcc
	s_movk_i32 s4, 0xff10
	v_add3_u32 v12, v23, v49, s4
	ds_read_b32 v39, v12
	s_or_b64 exec, exec, s[2:3]
	ds_read2_b32 v[12:13], v22 offset0:4 offset1:5
	v_mov_b32_e32 v44, 0
	v_mov_b32_e32 v46, 0
	s_and_saveexec_b64 s[2:3], vcc
	ds_read_b32 v46, v50 offset:24
	s_or_b64 exec, exec, s[2:3]
	s_and_saveexec_b64 s[2:3], vcc
	s_movk_i32 s4, 0xff18
	v_add3_u32 v14, v23, v49, s4
	ds_read_b32 v44, v14
	s_or_b64 exec, exec, s[2:3]
	ds_read2_b32 v[14:15], v22 offset0:6 offset1:7
	v_mov_b32_e32 v34, 0
	v_mov_b32_e32 v35, 0
	s_and_saveexec_b64 s[2:3], vcc
	ds_read_b32 v35, v50 offset:128
	s_or_b64 exec, exec, s[2:3]
	s_and_saveexec_b64 s[2:3], vcc
	s_movk_i32 s4, 0xff80
	v_add3_u32 v16, v23, v49, s4
	ds_read_b32 v34, v16
	s_or_b64 exec, exec, s[2:3]
	ds_read2_b32 v[16:17], v22 offset0:32 offset1:33
	v_mov_b32_e32 v37, 0
	v_mov_b32_e32 v40, 0
	s_and_saveexec_b64 s[2:3], vcc
	ds_read_b32 v40, v50 offset:136
	s_or_b64 exec, exec, s[2:3]
	s_and_saveexec_b64 s[2:3], vcc
	s_movk_i32 s4, 0xff88
	v_add3_u32 v18, v23, v49, s4
	ds_read_b32 v37, v18
	s_or_b64 exec, exec, s[2:3]
	ds_read2_b32 v[18:19], v22 offset0:34 offset1:35
	v_mov_b32_e32 v41, 0
	v_mov_b32_e32 v43, 0
	s_and_saveexec_b64 s[2:3], vcc
	ds_read_b32 v43, v50 offset:144
	s_or_b64 exec, exec, s[2:3]
	s_and_saveexec_b64 s[2:3], vcc
	s_movk_i32 s4, 0xff90
	v_add3_u32 v20, v23, v49, s4
	ds_read_b32 v41, v20
	s_or_b64 exec, exec, s[2:3]
	ds_read2_b32 v[20:21], v22 offset0:36 offset1:37
	v_mov_b32_e32 v45, 0
	v_mov_b32_e32 v47, 0
	s_and_saveexec_b64 s[2:3], vcc
	ds_read_b32 v47, v50 offset:152
	s_or_b64 exec, exec, s[2:3]
	s_and_saveexec_b64 s[2:3], vcc
	s_movk_i32 s4, 0xff98
	v_add3_u32 v23, v23, v49, s4
	ds_read_b32 v45, v23
	s_or_b64 exec, exec, s[2:3]
	s_waitcnt lgkmcnt(2)
	v_sub_f32_e32 v23, v16, v35
	v_mul_f32_e32 v23, 0x3fb8aa3b, v23
	v_exp_f32_e32 v52, v23
	v_sub_f32_e32 v23, v17, v34
	v_mul_f32_e32 v16, 0x3fb8aa3b, v16
	v_mul_f32_e32 v17, 0x3fb8aa3b, v17
	v_exp_f32_e32 v16, v16
	v_exp_f32_e32 v17, v17
	v_mul_f32_e32 v23, 0x3fb8aa3b, v23
	v_exp_f32_e32 v53, v23
	v_lshlrev_b32_e32 v54, 16, v0
	v_and_b32_e32 v55, 0xffff0000, v0
	v_pk_mul_f32 v[16:17], v[16:17], v[54:55]
	v_pk_mul_f32 v[52:53], v[52:53], v[54:55]
	v_cvt_pk_bf16_f32 v16, v16, v17
	s_waitcnt lgkmcnt(1)
	v_sub_f32_e32 v17, v18, v40
	v_mul_f32_e32 v17, 0x3fb8aa3b, v17
	v_cvt_pk_bf16_f32 v0, v52, v53
	v_exp_f32_e32 v52, v17
	v_sub_f32_e32 v17, v19, v37
	v_mul_f32_e32 v17, 0x3fb8aa3b, v17
	v_exp_f32_e32 v53, v17
	v_mul_f32_e32 v17, 0x3fb8aa3b, v18
	v_exp_f32_e32 v18, v17
	v_mul_f32_e32 v17, 0x3fb8aa3b, v19
	v_exp_f32_e32 v19, v17
	v_lshlrev_b32_e32 v54, 16, v1
	v_and_b32_e32 v55, 0xffff0000, v1
	v_pk_mul_f32 v[52:53], v[52:53], v[54:55]
	v_pk_mul_f32 v[18:19], v[18:19], v[54:55]
	v_cvt_pk_bf16_f32 v1, v52, v53
	v_cvt_pk_bf16_f32 v17, v18, v19
	s_waitcnt lgkmcnt(0)
	v_sub_f32_e32 v18, v20, v43
	v_sub_f32_e32 v19, v21, v41
	v_mul_f32_e32 v18, 0x3fb8aa3b, v18
	v_mul_f32_e32 v19, 0x3fb8aa3b, v19
	v_exp_f32_e32 v18, v18
	v_exp_f32_e32 v19, v19
	v_mul_f32_e32 v20, 0x3fb8aa3b, v20
	v_mul_f32_e32 v21, 0x3fb8aa3b, v21
	v_exp_f32_e32 v20, v20
	v_exp_f32_e32 v21, v21
	v_lshlrev_b32_e32 v52, 16, v2
	v_and_b32_e32 v53, 0xffff0000, v2
	v_pk_mul_f32 v[18:19], v[18:19], v[52:53]
	s_movk_i32 s4, 0x300
	v_cvt_pk_bf16_f32 v2, v18, v19
	v_pk_mul_f32 v[18:19], v[20:21], v[52:53]
	v_lshlrev_b32_e32 v52, 16, v4
	v_cvt_pk_bf16_f32 v18, v18, v19
	v_sub_f32_e32 v19, v8, v33
	v_mul_f32_e32 v19, 0x3fb8aa3b, v19
	v_exp_f32_e32 v20, v19
	v_sub_f32_e32 v19, v9, v32
	v_mul_f32_e32 v8, 0x3fb8aa3b, v8
	v_mul_f32_e32 v9, 0x3fb8aa3b, v9
	v_exp_f32_e32 v8, v8
	v_exp_f32_e32 v9, v9
	v_mul_f32_e32 v19, 0x3fb8aa3b, v19
	v_exp_f32_e32 v21, v19
	v_and_b32_e32 v53, 0xffff0000, v4
	v_pk_mul_f32 v[8:9], v[8:9], v[52:53]
	v_or_b32_e32 v50, 2, v30
	v_cvt_pk_bf16_f32 v8, v8, v9
	v_sub_f32_e32 v9, v10, v38
	v_pk_mul_f32 v[20:21], v[20:21], v[52:53]
	v_mul_f32_e32 v9, 0x3fb8aa3b, v9
	v_cvt_pk_bf16_f32 v4, v20, v21
	v_exp_f32_e32 v20, v9
	v_sub_f32_e32 v9, v11, v36
	v_mul_f32_e32 v9, 0x3fb8aa3b, v9
	v_exp_f32_e32 v21, v9
	v_mul_f32_e32 v9, 0x3fb8aa3b, v10
	v_exp_f32_e32 v10, v9
	v_mul_f32_e32 v9, 0x3fb8aa3b, v11
	v_exp_f32_e32 v11, v9
	v_lshlrev_b32_e32 v52, 16, v5
	v_and_b32_e32 v53, 0xffff0000, v5
	v_pk_mul_f32 v[20:21], v[20:21], v[52:53]
	v_pk_mul_f32 v[10:11], v[10:11], v[52:53]
	v_cvt_pk_bf16_f32 v5, v20, v21
	v_cvt_pk_bf16_f32 v9, v10, v11
	v_sub_f32_e32 v10, v12, v42
	v_sub_f32_e32 v11, v13, v39
	v_mul_f32_e32 v10, 0x3fb8aa3b, v10
	v_mul_f32_e32 v11, 0x3fb8aa3b, v11
	v_exp_f32_e32 v10, v10
	v_exp_f32_e32 v11, v11
	v_mul_f32_e32 v12, 0x3fb8aa3b, v12
	v_mul_f32_e32 v13, 0x3fb8aa3b, v13
	v_exp_f32_e32 v12, v12
	v_exp_f32_e32 v13, v13
	v_lshlrev_b32_e32 v20, 16, v6
	v_and_b32_e32 v21, 0xffff0000, v6
	v_pk_mul_f32 v[10:11], v[10:11], v[20:21]
	v_or_b32_e32 v49, 3, v30
	v_cvt_pk_bf16_f32 v6, v10, v11
	v_pk_mul_f32 v[10:11], v[12:13], v[20:21]
	v_lshlrev_b32_e32 v20, 16, v7
	v_cvt_pk_bf16_f32 v10, v10, v11
	v_sub_f32_e32 v11, v14, v46
	v_mul_f32_e32 v11, 0x3fb8aa3b, v11
	v_exp_f32_e32 v12, v11
	v_sub_f32_e32 v11, v15, v44
	v_mul_f32_e32 v11, 0x3fb8aa3b, v11
	v_exp_f32_e32 v13, v11
	v_mul_f32_e32 v11, 0x3fb8aa3b, v14
	v_exp_f32_e32 v14, v11
	v_mul_f32_e32 v11, 0x3fb8aa3b, v15
	v_exp_f32_e32 v15, v11
	v_and_b32_e32 v21, 0xffff0000, v7
	v_pk_mul_f32 v[12:13], v[12:13], v[20:21]
	s_nop 0
	v_cvt_pk_bf16_f32 v7, v12, v13
	v_pk_mul_f32 v[12:13], v[14:15], v[20:21]
	v_lshlrev_b32_e32 v20, 16, v3
	v_cvt_pk_bf16_f32 v11, v12, v13
	ds_read2_b32 v[12:13], v22 offset0:38 offset1:39
	v_and_b32_e32 v21, 0xffff0000, v3
	s_waitcnt lgkmcnt(0)
	v_sub_f32_e32 v14, v12, v47
	v_sub_f32_e32 v15, v13, v45
	v_mul_f32_e32 v12, 0x3fb8aa3b, v12
	v_mul_f32_e32 v13, 0x3fb8aa3b, v13
	v_exp_f32_e32 v12, v12
	v_exp_f32_e32 v13, v13
	v_mul_f32_e32 v14, 0x3fb8aa3b, v14
	v_mul_f32_e32 v15, 0x3fb8aa3b, v15
	v_exp_f32_e32 v14, v14
	v_exp_f32_e32 v15, v15
	v_pk_mul_f32 v[12:13], v[12:13], v[20:21]
	v_pk_mul_f32 v[14:15], v[14:15], v[20:21]
	v_cvt_pk_bf16_f32 v19, v12, v13
	v_mov_b64_e32 v[12:13], s[64:65]
	v_mad_u64_u32 v[12:13], s[2:3], v24, s4, v[12:13]
	v_cvt_pk_bf16_f32 v3, v14, v15
	v_mov_b32_e32 v14, v13
	v_mad_u64_u32 v[14:15], s[2:3], v25, s4, v[14:15]
	v_mov_b32_e32 v13, v14
	v_lshl_add_u64 v[12:13], v[12:13], 0, v[176:177]
	v_lshlrev_b32_e32 v14, 1, v29
	v_mov_b32_e32 v15, v177
	v_lshl_add_u64 v[12:13], v[12:13], 0, v[14:15]
	s_movk_i32 s2, 0x41
	global_store_dwordx4 v[12:13], v[8:11], off sc1
	global_store_dwordx4 v[12:13], v[16:19], off offset:64 sc1
	s_nop 0
	v_mad_u32_u24 v8, v26, s2, v29
	v_lshl_add_u32 v15, v8, 2, v28
	ds_read2_b32 v[8:9], v15 offset1:1
	v_add_u32_e32 v10, 0x4400, v15
	ds_read2_b32 v[10:11], v10 offset1:1
	v_add_u32_e32 v14, 0x4480, v15
	s_waitcnt lgkmcnt(1)
	v_sub_f32_e32 v8, v33, v8
	v_sub_f32_e32 v9, v32, v9
	v_min_f32_e32 v8, 0x42a00000, v8
	v_min_f32_e32 v9, 0x42a00000, v9
	v_mul_f32_e32 v8, 0x3fb8aa3b, v8
	v_mul_f32_e32 v9, 0x3fb8aa3b, v9
	v_exp_f32_e32 v8, v8
	v_exp_f32_e32 v9, v9
	s_waitcnt lgkmcnt(0)
	v_pk_mul_f32 v[8:9], v[10:11], v[8:9]
	ds_read2_b32 v[10:11], v15 offset0:2 offset1:3
	v_cvt_pk_bf16_f32 v8, v8, v9
	v_add_u32_e32 v9, 0x4408, v15
	ds_read2_b32 v[12:13], v9 offset1:1
	s_waitcnt lgkmcnt(1)
	v_sub_f32_e32 v10, v38, v10
	v_sub_f32_e32 v11, v36, v11
	v_min_f32_e32 v10, 0x42a00000, v10
	v_min_f32_e32 v11, 0x42a00000, v11
	v_mul_f32_e32 v10, 0x3fb8aa3b, v10
	v_mul_f32_e32 v11, 0x3fb8aa3b, v11
	v_exp_f32_e32 v10, v10
	v_exp_f32_e32 v11, v11
	s_waitcnt lgkmcnt(0)
	v_pk_mul_f32 v[10:11], v[12:13], v[10:11]
	s_nop 0
	v_cvt_pk_bf16_f32 v9, v10, v11
	ds_read2_b32 v[10:11], v15 offset0:4 offset1:5
	v_add_u32_e32 v12, 0x4410, v15
	ds_read2_b32 v[12:13], v12 offset1:1
	s_waitcnt lgkmcnt(1)
	v_sub_f32_e32 v10, v42, v10
	v_sub_f32_e32 v11, v39, v11
	v_min_f32_e32 v10, 0x42a00000, v10
	v_min_f32_e32 v11, 0x42a00000, v11
	v_mul_f32_e32 v10, 0x3fb8aa3b, v10
	v_mul_f32_e32 v11, 0x3fb8aa3b, v11
	v_exp_f32_e32 v10, v10
	v_exp_f32_e32 v11, v11
	s_waitcnt lgkmcnt(0)
	v_pk_mul_f32 v[10:11], v[12:13], v[10:11]
	ds_read2_b32 v[12:13], v15 offset0:6 offset1:7
	v_cvt_pk_bf16_f32 v10, v10, v11
	v_add_u32_e32 v11, 0x4418, v15
	ds_read2_b32 v[16:17], v11 offset1:1
	s_waitcnt lgkmcnt(1)
	v_sub_f32_e32 v12, v46, v12
	v_sub_f32_e32 v13, v44, v13
	v_min_f32_e32 v12, 0x42a00000, v12
	v_min_f32_e32 v13, 0x42a00000, v13
	v_mul_f32_e32 v12, 0x3fb8aa3b, v12
	v_mul_f32_e32 v13, 0x3fb8aa3b, v13
	v_exp_f32_e32 v12, v12
	v_exp_f32_e32 v13, v13
	s_waitcnt lgkmcnt(0)
	v_pk_mul_f32 v[12:13], v[16:17], v[12:13]
	s_nop 0
	v_cvt_pk_bf16_f32 v11, v12, v13
	ds_read2_b32 v[12:13], v15 offset0:32 offset1:33
	ds_read2_b32 v[16:17], v14 offset1:1
	v_mfma_f32_16x16x32_bf16 v[8:11], v[8:11], v[4:7], 0
	s_waitcnt lgkmcnt(1)
	v_sub_f32_e32 v12, v35, v12
	v_sub_f32_e32 v13, v34, v13
	v_min_f32_e32 v12, 0x42a00000, v12
	v_min_f32_e32 v13, 0x42a00000, v13
	v_mul_f32_e32 v12, 0x3fb8aa3b, v12
	v_mul_f32_e32 v13, 0x3fb8aa3b, v13
	v_exp_f32_e32 v12, v12
	v_exp_f32_e32 v13, v13
	s_waitcnt lgkmcnt(0)
	v_pk_mul_f32 v[12:13], v[16:17], v[12:13]
	ds_read2_b32 v[16:17], v15 offset0:34 offset1:35
	v_cvt_pk_bf16_f32 v12, v12, v13
	v_add_u32_e32 v13, 0x4488, v15
	ds_read2_b32 v[18:19], v13 offset1:1
	s_waitcnt lgkmcnt(1)
	v_sub_f32_e32 v14, v40, v16
	v_min_f32_e32 v14, 0x42a00000, v14
	v_mul_f32_e32 v14, 0x3fb8aa3b, v14
	v_exp_f32_e32 v16, v14
	v_sub_f32_e32 v14, v37, v17
	v_min_f32_e32 v14, 0x42a00000, v14
	v_mul_f32_e32 v14, 0x3fb8aa3b, v14
	v_exp_f32_e32 v17, v14
	v_add_u32_e32 v14, 0x4490, v15
	s_waitcnt lgkmcnt(0)
	v_pk_mul_f32 v[16:17], v[18:19], v[16:17]
	s_nop 0
	v_cvt_pk_bf16_f32 v13, v16, v17
	ds_read2_b32 v[16:17], v15 offset0:36 offset1:37
	ds_read2_b32 v[18:19], v14 offset1:1
	s_waitcnt lgkmcnt(1)
	v_sub_f32_e32 v16, v43, v16
	v_sub_f32_e32 v17, v41, v17
	v_min_f32_e32 v16, 0x42a00000, v16
	v_min_f32_e32 v17, 0x42a00000, v17
	v_mul_f32_e32 v16, 0x3fb8aa3b, v16
	v_mul_f32_e32 v17, 0x3fb8aa3b, v17
	v_exp_f32_e32 v16, v16
	v_exp_f32_e32 v17, v17
	s_waitcnt lgkmcnt(0)
	v_pk_mul_f32 v[16:17], v[18:19], v[16:17]
	s_nop 0
	v_cvt_pk_bf16_f32 v14, v16, v17
	ds_read2_b32 v[16:17], v15 offset0:38 offset1:39
	v_add_u32_e32 v18, 0x4498, v15
	ds_read2_b32 v[18:19], v18 offset1:1
	s_waitcnt lgkmcnt(1)
	v_sub_f32_e32 v15, v47, v16
	v_min_f32_e32 v15, 0x42a00000, v15
	v_mul_f32_e32 v15, 0x3fb8aa3b, v15
	v_exp_f32_e32 v16, v15
	v_sub_f32_e32 v15, v45, v17
	v_min_f32_e32 v15, 0x42a00000, v15
	v_mul_f32_e32 v15, 0x3fb8aa3b, v15
	v_exp_f32_e32 v17, v15
	s_waitcnt lgkmcnt(0)
	v_pk_mul_f32 v[16:17], v[18:19], v[16:17]
	s_nop 0
	v_cvt_pk_bf16_f32 v15, v16, v17
	v_mov_b32_e32 v16, 0
	s_nop 0
	v_mfma_f32_16x16x32_bf16 v[8:11], v[12:15], v[0:3], v[8:11]
	s_and_saveexec_b64 s[2:3], s[36:37]
	v_cmp_gt_u32_e64 s[36:37], v30, v26
	s_nop 5
	v_cndmask_b32_e64 v12, v8, 0, s[36:37]
	v_cmp_lt_u32_e64 s[36:37], v30, v26
	s_nop 1
	v_cndmask_b32_e64 v8, v12, v8, s[36:37]
	v_cndmask_b32_e64 v9, 0, v9, s[36:37]
	v_cmp_le_u32_e64 s[36:37], v50, v26
	s_nop 1
	v_cndmask_b32_e64 v10, 0, v10, s[36:37]
	v_cmp_le_u32_e64 s[36:37], v49, v26
	s_nop 1
	v_cndmask_b32_e64 v11, 0, v11, s[36:37]
	s_or_b64 exec, exec, s[2:3]
	v_mov_b32_e32 v20, 0
	v_mov_b32_e32 v21, 0
	v_mov_b32_e32 v22, 0
	v_mov_b32_e32 v23, 0
	s_and_saveexec_b64 s[4:5], vcc
	s_cbranch_execz .LBB0_282
	s_movk_i32 s2, 0x41
	v_mad_u32_u24 v12, v51, s2, v29
	v_lshl_add_u32 v17, v12, 2, v28
	ds_read2_b32 v[12:13], v17 offset1:1
	v_add_u32_e32 v14, 0x4400, v17
	ds_read2_b32 v[14:15], v14 offset1:1
	v_cmp_eq_u32_e32 vcc, 1, v27
	s_waitcnt lgkmcnt(1)
	v_sub_f32_e32 v12, v33, v12
	v_sub_f32_e32 v13, v32, v13
	v_min_f32_e32 v12, 0x42a00000, v12
	v_min_f32_e32 v13, 0x42a00000, v13
	v_mul_f32_e32 v12, 0x3fb8aa3b, v12
	v_mul_f32_e32 v13, 0x3fb8aa3b, v13
	v_exp_f32_e32 v12, v12
	v_exp_f32_e32 v13, v13
	s_waitcnt lgkmcnt(0)
	v_pk_mul_f32 v[12:13], v[14:15], v[12:13]
	ds_read2_b32 v[14:15], v17 offset0:2 offset1:3
	v_cvt_pk_bf16_f32 v12, v12, v13
	v_add_u32_e32 v13, 0x4408, v17
	ds_read2_b32 v[18:19], v13 offset1:1
	s_waitcnt lgkmcnt(1)
	v_sub_f32_e32 v14, v38, v14
	v_sub_f32_e32 v15, v36, v15
	v_min_f32_e32 v14, 0x42a00000, v14
	v_min_f32_e32 v15, 0x42a00000, v15
	v_mul_f32_e32 v14, 0x3fb8aa3b, v14
	v_mul_f32_e32 v15, 0x3fb8aa3b, v15
	v_exp_f32_e32 v14, v14
	v_exp_f32_e32 v15, v15
	s_waitcnt lgkmcnt(0)
	v_pk_mul_f32 v[14:15], v[18:19], v[14:15]
	s_nop 0
	v_cvt_pk_bf16_f32 v13, v14, v15
	ds_read2_b32 v[14:15], v17 offset0:4 offset1:5
	v_add_u32_e32 v18, 0x4410, v17
	ds_read2_b32 v[18:19], v18 offset1:1
	s_waitcnt lgkmcnt(1)
	v_sub_f32_e32 v14, v42, v14
	v_sub_f32_e32 v15, v39, v15
	v_min_f32_e32 v14, 0x42a00000, v14
	v_min_f32_e32 v15, 0x42a00000, v15
	v_mul_f32_e32 v14, 0x3fb8aa3b, v14
	v_mul_f32_e32 v15, 0x3fb8aa3b, v15
	v_exp_f32_e32 v14, v14
	v_exp_f32_e32 v15, v15
	s_waitcnt lgkmcnt(0)
	v_pk_mul_f32 v[14:15], v[18:19], v[14:15]
	ds_read2_b32 v[18:19], v17 offset0:6 offset1:7
	v_cvt_pk_bf16_f32 v14, v14, v15
	v_add_u32_e32 v15, 0x4418, v17
	ds_read2_b32 v[20:21], v15 offset1:1
	s_waitcnt lgkmcnt(1)
	v_sub_f32_e32 v18, v46, v18
	v_sub_f32_e32 v19, v44, v19
	v_min_f32_e32 v18, 0x42a00000, v18
	v_min_f32_e32 v19, 0x42a00000, v19
	v_mul_f32_e32 v18, 0x3fb8aa3b, v18
	v_mul_f32_e32 v19, 0x3fb8aa3b, v19
	v_exp_f32_e32 v18, v18
	v_exp_f32_e32 v19, v19
	s_waitcnt lgkmcnt(0)
	v_pk_mul_f32 v[18:19], v[20:21], v[18:19]
	s_nop 0
	v_cvt_pk_bf16_f32 v15, v18, v19
	ds_read2_b32 v[18:19], v17 offset0:32 offset1:33
	v_add_u32_e32 v20, 0x4480, v17
	ds_read2_b32 v[20:21], v20 offset1:1
	v_mfma_f32_16x16x32_bf16 v[12:15], v[12:15], v[4:7], 0
	s_waitcnt lgkmcnt(1)
	v_sub_f32_e32 v18, v35, v18
	v_sub_f32_e32 v19, v34, v19
	v_min_f32_e32 v18, 0x42a00000, v18
	v_min_f32_e32 v19, 0x42a00000, v19
	v_mul_f32_e32 v18, 0x3fb8aa3b, v18
	v_mul_f32_e32 v19, 0x3fb8aa3b, v19
	v_exp_f32_e32 v18, v18
	v_exp_f32_e32 v19, v19
	s_waitcnt lgkmcnt(0)
	v_pk_mul_f32 v[18:19], v[20:21], v[18:19]
	ds_read2_b32 v[20:21], v17 offset0:34 offset1:35
	v_cvt_pk_bf16_f32 v18, v18, v19
	v_add_u32_e32 v19, 0x4488, v17
	ds_read2_b32 v[22:23], v19 offset1:1
	s_waitcnt lgkmcnt(1)
	v_sub_f32_e32 v20, v40, v20
	v_sub_f32_e32 v21, v37, v21
	v_min_f32_e32 v20, 0x42a00000, v20
	v_min_f32_e32 v21, 0x42a00000, v21
	v_mul_f32_e32 v20, 0x3fb8aa3b, v20
	v_mul_f32_e32 v21, 0x3fb8aa3b, v21
	v_exp_f32_e32 v20, v20
	v_exp_f32_e32 v21, v21
	s_waitcnt lgkmcnt(0)
	v_pk_mul_f32 v[20:21], v[22:23], v[20:21]
	s_nop 0
	v_cvt_pk_bf16_f32 v19, v20, v21
	ds_read2_b32 v[20:21], v17 offset0:36 offset1:37
	v_add_u32_e32 v22, 0x4490, v17
	ds_read2_b32 v[22:23], v22 offset1:1
	s_waitcnt lgkmcnt(1)
	v_sub_f32_e32 v20, v43, v20
	v_sub_f32_e32 v21, v41, v21
	v_min_f32_e32 v20, 0x42a00000, v20
	v_min_f32_e32 v21, 0x42a00000, v21
	v_mul_f32_e32 v20, 0x3fb8aa3b, v20
	v_mul_f32_e32 v21, 0x3fb8aa3b, v21
	v_exp_f32_e32 v20, v20
	v_exp_f32_e32 v21, v21
	s_waitcnt lgkmcnt(0)
	v_pk_mul_f32 v[20:21], v[22:23], v[20:21]
	ds_read2_b32 v[22:23], v17 offset0:38 offset1:39
	v_cvt_pk_bf16_f32 v20, v20, v21
	v_add_u32_e32 v21, 0x4498, v17
	ds_read2_b32 v[52:53], v21 offset1:1
	s_waitcnt lgkmcnt(1)
	v_sub_f32_e32 v17, v47, v22
	v_min_f32_e32 v17, 0x42a00000, v17
	v_mul_f32_e32 v17, 0x3fb8aa3b, v17
	v_exp_f32_e32 v22, v17
	v_sub_f32_e32 v17, v45, v23
	v_min_f32_e32 v17, 0x42a00000, v17
	v_mul_f32_e32 v17, 0x3fb8aa3b, v17
	v_exp_f32_e32 v23, v17
	s_waitcnt lgkmcnt(0)
	v_pk_mul_f32 v[22:23], v[52:53], v[22:23]
	s_nop 0
	v_cvt_pk_bf16_f32 v21, v22, v23
	s_nop 1
	v_mfma_f32_16x16x32_bf16 v[20:23], v[18:21], v[0:3], v[12:15]
	s_and_saveexec_b64 s[2:3], vcc
	v_cmp_gt_u32_e32 vcc, v30, v26
	s_nop 5
	v_cndmask_b32_e64 v12, v20, 0, vcc
	v_cmp_lt_u32_e32 vcc, v30, v26
	s_nop 1
	v_cndmask_b32_e32 v20, v12, v20, vcc
	v_cndmask_b32_e32 v21, 0, v21, vcc
	v_cmp_le_u32_e32 vcc, v50, v26
	s_nop 1
	v_cndmask_b32_e32 v22, 0, v22, vcc
	v_cmp_le_u32_e32 vcc, v49, v26
	s_nop 1
	v_cndmask_b32_e32 v23, 0, v23, vcc
	s_or_b64 exec, exec, s[2:3]

.LBB0_363:
	s_or_b64 exec, exec, s[4:5]
	v_lshlrev_b32_e32 v32, 3, v192
	s_waitcnt lgkmcnt(0)
	s_barrier
	ds_read_b64 v[192:193], v32 offset:8192
	v_lshlrev_b64 v[32:33], 10, v[162:163]
	v_lshl_add_u64 v[194:195], v[32:33], 0, v[160:161]
	v_readlane_b32 s4, v254, 1
	v_readlane_b32 s10, v254, 7
	s_waitcnt lgkmcnt(0)
	v_sub_f32_e32 v33, v159, v192
	v_sub_f32_e32 v32, v158, v192
	v_sub_f32_e32 v35, v157, v192
	v_sub_f32_e32 v34, v156, v192
	v_pk_mul_f32 v[156:157], v[192:193], v[34:35] op_sel:[1,0]
	v_pk_mul_f32 v[32:33], v[192:193], v[32:33] op_sel:[1,0]
	v_readlane_b32 s11, v254, 8
	v_mov_b32_e32 v162, v193
	v_mov_b32_e32 v163, v193
	v_pk_fma_f32 v[34:35], v[26:27], v[32:33], v[30:31]
	v_pk_fma_f32 v[32:33], v[24:25], v[156:157], v[28:29]
	v_lshl_add_u64 v[156:157], v[194:195], 2, s[10:11]
	s_mov_b64 s[2:3], -1
	s_and_b64 vcc, exec, s[38:39]
	v_sub_f32_e32 v155, v155, v192
	v_sub_f32_e32 v154, v154, v192
	v_sub_f32_e32 v159, v153, v192
	v_sub_f32_e32 v158, v152, v192
	v_readlane_b32 s5, v254, 2
	v_readlane_b32 s6, v254, 3
	v_readlane_b32 s7, v254, 4
	v_readlane_b32 s8, v254, 5
	v_readlane_b32 s9, v254, 6
	global_store_dwordx4 v[156:157], v[32:35], off sc1
	s_cbranch_vccz .LBB0_365
	v_mov_b32_e32 v204, v193
	v_mov_b32_e32 v205, v193
	v_pk_mul_f32 v[152:153], v[162:163], v[158:159]
	v_pk_mul_f32 v[204:205], v[204:205], v[154:155]
	v_pk_fma_f32 v[220:221], v[16:17], v[152:153], v[20:21]
	v_pk_fma_f32 v[222:223], v[18:19], v[204:205], v[22:23]
	global_store_dwordx4 v[156:157], v[220:223], off offset:64 sc1
	s_mov_b64 s[2:3], 0
.LBB0_365:
	s_andn2_b64 vcc, exec, s[2:3]
	v_lshl_add_u64 v[152:153], v[194:195], 1, s[80:81]
	s_cbranch_vccnz .LBB0_367
	v_cvt_pk_bf16_f32 v32, v32, v33
	v_cvt_pk_bf16_f32 v33, v34, v35
	v_mov_b32_e32 v34, v193
	v_mov_b32_e32 v35, v193
	global_store_dwordx2 v[152:153], v[32:33], off
	v_pk_mul_f32 v[32:33], v[162:163], v[158:159]
	v_pk_mul_f32 v[34:35], v[34:35], v[154:155]
	v_pk_fma_f32 v[32:33], v[16:17], v[32:33], v[20:21]
	v_pk_fma_f32 v[34:35], v[18:19], v[34:35], v[22:23]
	global_store_dwordx4 v[156:157], v[32:35], off offset:64 sc1
	s_nop 1
	v_cvt_pk_bf16_f32 v32, v32, v33
	v_cvt_pk_bf16_f32 v33, v34, v35
	global_store_dwordx2 v[152:153], v[32:33], off offset:32
.LBB0_367:
	v_sub_f32_e32 v33, v151, v192
	v_sub_f32_e32 v32, v150, v192
	v_sub_f32_e32 v35, v149, v192
	v_sub_f32_e32 v34, v148, v192
	v_mov_b32_e32 v148, v193
	v_mov_b32_e32 v149, v193
	v_pk_mul_f32 v[150:151], v[162:163], v[34:35]
	v_pk_mul_f32 v[32:33], v[148:149], v[32:33]
	s_mov_b64 s[2:3], -1
	v_pk_fma_f32 v[34:35], v[10:11], v[32:33], v[14:15]
	v_pk_fma_f32 v[32:33], v[8:9], v[150:151], v[12:13]
	s_and_b64 vcc, exec, s[38:39]
	v_sub_f32_e32 v147, v147, v192
	v_sub_f32_e32 v146, v146, v192
	v_sub_f32_e32 v145, v145, v192
	v_sub_f32_e32 v144, v144, v192
	global_store_dwordx4 v[156:157], v[32:35], off offset:512 sc1
	s_cbranch_vccz .LBB0_369
	v_pk_mul_f32 v[154:155], v[162:163], v[144:145]
	v_pk_mul_f32 v[148:149], v[148:149], v[146:147]
	s_mov_b64 s[2:3], 0
	v_pk_fma_f32 v[150:151], v[2:3], v[148:149], v[6:7]
	v_pk_fma_f32 v[148:149], v[0:1], v[154:155], v[4:5]
	global_store_dwordx4 v[156:157], v[148:151], off offset:576 sc1
.LBB0_369:
	s_andn2_b64 vcc, exec, s[2:3]
	s_cbranch_vccnz .LBB0_371
	v_cvt_pk_bf16_f32 v32, v32, v33
	v_cvt_pk_bf16_f32 v33, v34, v35
	v_mov_b32_e32 v192, v193
	global_store_dwordx2 v[152:153], v[32:33], off offset:256
	v_pk_mul_f32 v[32:33], v[162:163], v[144:145]
	v_pk_mul_f32 v[34:35], v[192:193], v[146:147]
	v_pk_fma_f32 v[32:33], v[0:1], v[32:33], v[4:5]
	v_pk_fma_f32 v[34:35], v[2:3], v[34:35], v[6:7]
	global_store_dwordx4 v[156:157], v[32:35], off offset:576 sc1
	s_nop 1
	v_cvt_pk_bf16_f32 v32, v32, v33
	v_cvt_pk_bf16_f32 v33, v34, v35
	global_store_dwordx2 v[152:153], v[32:33], off offset:288
.LBB0_371:
	v_lshlrev_b32_e32 v32, 3, v196
	ds_read_b64 v[144:145], v32 offset:8192
	v_lshlrev_b64 v[32:33], 10, v[164:165]
	v_lshl_add_u64 v[148:149], v[32:33], 0, v[160:161]
	v_readlane_b32 s4, v254, 1
	v_readlane_b32 s10, v254, 7
	s_waitcnt lgkmcnt(0)
	v_sub_f32_e32 v33, v143, v144
	v_sub_f32_e32 v32, v142, v144
	v_sub_f32_e32 v35, v141, v144
	v_sub_f32_e32 v34, v140, v144
	v_pk_mul_f32 v[140:141], v[144:145], v[34:35] op_sel:[1,0]
	v_pk_mul_f32 v[32:33], v[144:145], v[32:33] op_sel:[1,0]
	v_readlane_b32 s11, v254, 8
	v_mov_b32_e32 v146, v145
	v_mov_b32_e32 v147, v145
	v_pk_fma_f32 v[34:35], v[26:27], v[32:33], v[30:31]
	v_pk_fma_f32 v[32:33], v[24:25], v[140:141], v[28:29]
	v_lshl_add_u64 v[140:141], v[148:149], 2, s[10:11]
	s_mov_b64 s[2:3], -1
	s_and_b64 vcc, exec, s[38:39]
	v_sub_f32_e32 v139, v139, v144
	v_sub_f32_e32 v138, v138, v144
	v_sub_f32_e32 v143, v137, v144
	v_sub_f32_e32 v142, v136, v144
	v_readlane_b32 s5, v254, 2
	v_readlane_b32 s6, v254, 3
	v_readlane_b32 s7, v254, 4
	v_readlane_b32 s8, v254, 5
	v_readlane_b32 s9, v254, 6
	global_store_dwordx4 v[140:141], v[32:35], off sc1
	s_cbranch_vccz .LBB0_373
	v_mov_b32_e32 v150, v145
	v_mov_b32_e32 v151, v145
	v_pk_mul_f32 v[136:137], v[146:147], v[142:143]
	v_pk_mul_f32 v[150:151], v[150:151], v[138:139]
	s_mov_b64 s[2:3], 0
	v_pk_fma_f32 v[152:153], v[18:19], v[150:151], v[22:23]
	v_pk_fma_f32 v[150:151], v[16:17], v[136:137], v[20:21]
	global_store_dwordx4 v[140:141], v[150:153], off offset:64 sc1
.LBB0_373:
	s_andn2_b64 vcc, exec, s[2:3]
	v_lshl_add_u64 v[136:137], v[148:149], 1, s[80:81]
	s_cbranch_vccnz .LBB0_375
	v_cvt_pk_bf16_f32 v32, v32, v33
	v_cvt_pk_bf16_f32 v33, v34, v35
	v_mov_b32_e32 v34, v145
	v_mov_b32_e32 v35, v145
	global_store_dwordx2 v[136:137], v[32:33], off
	v_pk_mul_f32 v[32:33], v[146:147], v[142:143]
	v_pk_mul_f32 v[34:35], v[34:35], v[138:139]
	v_pk_fma_f32 v[32:33], v[16:17], v[32:33], v[20:21]
	v_pk_fma_f32 v[34:35], v[18:19], v[34:35], v[22:23]
	global_store_dwordx4 v[140:141], v[32:35], off offset:64 sc1
	s_nop 1
	v_cvt_pk_bf16_f32 v32, v32, v33
	v_cvt_pk_bf16_f32 v33, v34, v35
	global_store_dwordx2 v[136:137], v[32:33], off offset:32
.LBB0_375:
	v_sub_f32_e32 v33, v135, v144
	v_sub_f32_e32 v32, v134, v144
	v_sub_f32_e32 v35, v133, v144
	v_sub_f32_e32 v34, v132, v144
	v_mov_b32_e32 v132, v145
	v_mov_b32_e32 v133, v145
	v_pk_mul_f32 v[134:135], v[146:147], v[34:35]
	v_pk_mul_f32 v[32:33], v[132:133], v[32:33]
	s_mov_b64 s[2:3], -1
	v_pk_fma_f32 v[34:35], v[10:11], v[32:33], v[14:15]
	v_pk_fma_f32 v[32:33], v[8:9], v[134:135], v[12:13]
	s_and_b64 vcc, exec, s[38:39]
	v_sub_f32_e32 v131, v131, v144
	v_sub_f32_e32 v130, v130, v144
	v_sub_f32_e32 v129, v129, v144
	v_sub_f32_e32 v128, v128, v144
	global_store_dwordx4 v[140:141], v[32:35], off offset:512 sc1
	s_cbranch_vccz .LBB0_377
	v_pk_mul_f32 v[138:139], v[146:147], v[128:129]
	v_pk_mul_f32 v[132:133], v[132:133], v[130:131]
	s_mov_b64 s[2:3], 0
	v_pk_fma_f32 v[134:135], v[2:3], v[132:133], v[6:7]
	v_pk_fma_f32 v[132:133], v[0:1], v[138:139], v[4:5]
	global_store_dwordx4 v[140:141], v[132:135], off offset:576 sc1
.LBB0_377:
	s_andn2_b64 vcc, exec, s[2:3]
	s_cbranch_vccnz .LBB0_379
	v_cvt_pk_bf16_f32 v32, v32, v33
	v_cvt_pk_bf16_f32 v33, v34, v35
	v_mov_b32_e32 v144, v145
	global_store_dwordx2 v[136:137], v[32:33], off offset:256
	v_pk_mul_f32 v[32:33], v[146:147], v[128:129]
	v_pk_mul_f32 v[34:35], v[144:145], v[130:131]
	v_pk_fma_f32 v[32:33], v[0:1], v[32:33], v[4:5]
	v_pk_fma_f32 v[34:35], v[2:3], v[34:35], v[6:7]
	global_store_dwordx4 v[140:141], v[32:35], off offset:576 sc1
	s_nop 1
	v_cvt_pk_bf16_f32 v32, v32, v33
	v_cvt_pk_bf16_f32 v33, v34, v35
	global_store_dwordx2 v[136:137], v[32:33], off offset:288
.LBB0_379:
	v_lshlrev_b32_e32 v32, 3, v197
	ds_read_b64 v[128:129], v32 offset:8192
	v_lshlrev_b64 v[32:33], 10, v[166:167]
	v_lshl_add_u64 v[132:133], v[32:33], 0, v[160:161]
	v_readlane_b32 s4, v254, 1
	v_readlane_b32 s10, v254, 7
	s_waitcnt lgkmcnt(0)
	v_sub_f32_e32 v33, v127, v128
	v_sub_f32_e32 v32, v126, v128
	v_sub_f32_e32 v35, v125, v128
	v_sub_f32_e32 v34, v124, v128
	v_pk_mul_f32 v[124:125], v[128:129], v[34:35] op_sel:[1,0]
	v_pk_mul_f32 v[32:33], v[128:129], v[32:33] op_sel:[1,0]
	v_readlane_b32 s11, v254, 8
	v_mov_b32_e32 v130, v129
	v_mov_b32_e32 v131, v129
	v_pk_fma_f32 v[34:35], v[26:27], v[32:33], v[30:31]
	v_pk_fma_f32 v[32:33], v[24:25], v[124:125], v[28:29]
	v_lshl_add_u64 v[124:125], v[132:133], 2, s[10:11]
	s_mov_b64 s[2:3], -1
	s_and_b64 vcc, exec, s[38:39]
	v_sub_f32_e32 v123, v123, v128
	v_sub_f32_e32 v122, v122, v128
	v_sub_f32_e32 v127, v121, v128
	v_sub_f32_e32 v126, v120, v128
	v_readlane_b32 s5, v254, 2
	v_readlane_b32 s6, v254, 3
	v_readlane_b32 s7, v254, 4
	v_readlane_b32 s8, v254, 5
	v_readlane_b32 s9, v254, 6
	global_store_dwordx4 v[124:125], v[32:35], off sc1
	s_cbranch_vccz .LBB0_381
	v_mov_b32_e32 v134, v129
	v_mov_b32_e32 v135, v129
	v_pk_mul_f32 v[120:121], v[130:131], v[126:127]
	v_pk_mul_f32 v[134:135], v[134:135], v[122:123]
	s_mov_b64 s[2:3], 0
	v_pk_fma_f32 v[136:137], v[18:19], v[134:135], v[22:23]
	v_pk_fma_f32 v[134:135], v[16:17], v[120:121], v[20:21]
	global_store_dwordx4 v[124:125], v[134:137], off offset:64 sc1
.LBB0_381:
	s_andn2_b64 vcc, exec, s[2:3]
	v_lshl_add_u64 v[120:121], v[132:133], 1, s[80:81]
	s_cbranch_vccnz .LBB0_383
	v_cvt_pk_bf16_f32 v32, v32, v33
	v_cvt_pk_bf16_f32 v33, v34, v35
	v_mov_b32_e32 v34, v129
	v_mov_b32_e32 v35, v129
	global_store_dwordx2 v[120:121], v[32:33], off
	v_pk_mul_f32 v[32:33], v[130:131], v[126:127]
	v_pk_mul_f32 v[34:35], v[34:35], v[122:123]
	v_pk_fma_f32 v[32:33], v[16:17], v[32:33], v[20:21]
	v_pk_fma_f32 v[34:35], v[18:19], v[34:35], v[22:23]
	global_store_dwordx4 v[124:125], v[32:35], off offset:64 sc1
	s_nop 1
	v_cvt_pk_bf16_f32 v32, v32, v33
	v_cvt_pk_bf16_f32 v33, v34, v35
	global_store_dwordx2 v[120:121], v[32:33], off offset:32
.LBB0_383:
	v_sub_f32_e32 v33, v119, v128
	v_sub_f32_e32 v32, v118, v128
	v_sub_f32_e32 v35, v117, v128
	v_sub_f32_e32 v34, v116, v128
	v_mov_b32_e32 v116, v129
	v_mov_b32_e32 v117, v129
	v_pk_mul_f32 v[118:119], v[130:131], v[34:35]
	v_pk_mul_f32 v[32:33], v[116:117], v[32:33]
	s_mov_b64 s[2:3], -1
	v_pk_fma_f32 v[34:35], v[10:11], v[32:33], v[14:15]
	v_pk_fma_f32 v[32:33], v[8:9], v[118:119], v[12:13]
	s_and_b64 vcc, exec, s[38:39]
	v_sub_f32_e32 v115, v115, v128
	v_sub_f32_e32 v114, v114, v128
	v_sub_f32_e32 v113, v113, v128
	v_sub_f32_e32 v112, v112, v128
	global_store_dwordx4 v[124:125], v[32:35], off offset:512 sc1
	s_cbranch_vccz .LBB0_385
	v_pk_mul_f32 v[122:123], v[130:131], v[112:113]
	v_pk_mul_f32 v[116:117], v[116:117], v[114:115]
	s_mov_b64 s[2:3], 0
	v_pk_fma_f32 v[118:119], v[2:3], v[116:117], v[6:7]
	v_pk_fma_f32 v[116:117], v[0:1], v[122:123], v[4:5]
	global_store_dwordx4 v[124:125], v[116:119], off offset:576 sc1
.LBB0_385:
	s_andn2_b64 vcc, exec, s[2:3]
	s_cbranch_vccnz .LBB0_387
	v_cvt_pk_bf16_f32 v32, v32, v33
	v_cvt_pk_bf16_f32 v33, v34, v35
	v_mov_b32_e32 v128, v129
	global_store_dwordx2 v[120:121], v[32:33], off offset:256
	v_pk_mul_f32 v[32:33], v[130:131], v[112:113]
	v_pk_mul_f32 v[34:35], v[128:129], v[114:115]
	v_pk_fma_f32 v[32:33], v[0:1], v[32:33], v[4:5]
	v_pk_fma_f32 v[34:35], v[2:3], v[34:35], v[6:7]
	global_store_dwordx4 v[124:125], v[32:35], off offset:576 sc1
	s_nop 1
	v_cvt_pk_bf16_f32 v32, v32, v33
	v_cvt_pk_bf16_f32 v33, v34, v35
	global_store_dwordx2 v[120:121], v[32:33], off offset:288
.LBB0_387:
	v_lshlrev_b32_e32 v32, 3, v198
	ds_read_b64 v[112:113], v32 offset:8192
	v_lshlrev_b64 v[32:33], 10, v[168:169]
	v_lshl_add_u64 v[116:117], v[32:33], 0, v[160:161]
	v_readlane_b32 s4, v254, 1
	v_readlane_b32 s10, v254, 7
	s_waitcnt lgkmcnt(0)
	v_sub_f32_e32 v33, v111, v112
	v_sub_f32_e32 v32, v110, v112
	v_sub_f32_e32 v35, v109, v112
	v_sub_f32_e32 v34, v108, v112
	v_pk_mul_f32 v[108:109], v[112:113], v[34:35] op_sel:[1,0]
	v_pk_mul_f32 v[32:33], v[112:113], v[32:33] op_sel:[1,0]
	v_readlane_b32 s11, v254, 8
	v_mov_b32_e32 v114, v113
	v_mov_b32_e32 v115, v113
	v_pk_fma_f32 v[34:35], v[26:27], v[32:33], v[30:31]
	v_pk_fma_f32 v[32:33], v[24:25], v[108:109], v[28:29]
	v_lshl_add_u64 v[108:109], v[116:117], 2, s[10:11]
	s_mov_b64 s[2:3], -1
	s_and_b64 vcc, exec, s[38:39]
	v_sub_f32_e32 v107, v107, v112
	v_sub_f32_e32 v106, v106, v112
	v_sub_f32_e32 v111, v105, v112
	v_sub_f32_e32 v110, v104, v112
	v_readlane_b32 s5, v254, 2
	v_readlane_b32 s6, v254, 3
	v_readlane_b32 s7, v254, 4
	v_readlane_b32 s8, v254, 5
	v_readlane_b32 s9, v254, 6
	global_store_dwordx4 v[108:109], v[32:35], off sc1
	s_cbranch_vccz .LBB0_389
	v_mov_b32_e32 v118, v113
	v_mov_b32_e32 v119, v113
	v_pk_mul_f32 v[104:105], v[114:115], v[110:111]
	v_pk_mul_f32 v[118:119], v[118:119], v[106:107]
	s_mov_b64 s[2:3], 0
	v_pk_fma_f32 v[120:121], v[18:19], v[118:119], v[22:23]
	v_pk_fma_f32 v[118:119], v[16:17], v[104:105], v[20:21]
	global_store_dwordx4 v[108:109], v[118:121], off offset:64 sc1
.LBB0_389:
	s_andn2_b64 vcc, exec, s[2:3]
	v_lshl_add_u64 v[104:105], v[116:117], 1, s[80:81]
	s_cbranch_vccnz .LBB0_391
	v_cvt_pk_bf16_f32 v32, v32, v33
	v_cvt_pk_bf16_f32 v33, v34, v35
	v_mov_b32_e32 v34, v113
	v_mov_b32_e32 v35, v113
	global_store_dwordx2 v[104:105], v[32:33], off
	v_pk_mul_f32 v[32:33], v[114:115], v[110:111]
	v_pk_mul_f32 v[34:35], v[34:35], v[106:107]
	v_pk_fma_f32 v[32:33], v[16:17], v[32:33], v[20:21]
	v_pk_fma_f32 v[34:35], v[18:19], v[34:35], v[22:23]
	global_store_dwordx4 v[108:109], v[32:35], off offset:64 sc1
	s_nop 1
	v_cvt_pk_bf16_f32 v32, v32, v33
	v_cvt_pk_bf16_f32 v33, v34, v35
	global_store_dwordx2 v[104:105], v[32:33], off offset:32
.LBB0_391:
	v_sub_f32_e32 v33, v103, v112
	v_sub_f32_e32 v32, v102, v112
	v_sub_f32_e32 v35, v101, v112
	v_sub_f32_e32 v34, v100, v112
	v_mov_b32_e32 v100, v113
	v_mov_b32_e32 v101, v113
	v_pk_mul_f32 v[102:103], v[114:115], v[34:35]
	v_pk_mul_f32 v[32:33], v[100:101], v[32:33]
	s_mov_b64 s[2:3], -1
	v_pk_fma_f32 v[34:35], v[10:11], v[32:33], v[14:15]
	v_pk_fma_f32 v[32:33], v[8:9], v[102:103], v[12:13]
	s_and_b64 vcc, exec, s[38:39]
	v_sub_f32_e32 v99, v99, v112
	v_sub_f32_e32 v98, v98, v112
	v_sub_f32_e32 v97, v97, v112
	v_sub_f32_e32 v96, v96, v112
	global_store_dwordx4 v[108:109], v[32:35], off offset:512 sc1
	s_cbranch_vccz .LBB0_393
	v_pk_mul_f32 v[106:107], v[114:115], v[96:97]
	v_pk_mul_f32 v[100:101], v[100:101], v[98:99]
	s_mov_b64 s[2:3], 0
	v_pk_fma_f32 v[102:103], v[2:3], v[100:101], v[6:7]
	v_pk_fma_f32 v[100:101], v[0:1], v[106:107], v[4:5]
	global_store_dwordx4 v[108:109], v[100:103], off offset:576 sc1
.LBB0_393:
	s_andn2_b64 vcc, exec, s[2:3]
	s_cbranch_vccnz .LBB0_395
	v_cvt_pk_bf16_f32 v32, v32, v33
	v_cvt_pk_bf16_f32 v33, v34, v35
	v_mov_b32_e32 v112, v113
	global_store_dwordx2 v[104:105], v[32:33], off offset:256
	v_pk_mul_f32 v[32:33], v[114:115], v[96:97]
	v_pk_mul_f32 v[34:35], v[112:113], v[98:99]
	v_pk_fma_f32 v[32:33], v[0:1], v[32:33], v[4:5]
	v_pk_fma_f32 v[34:35], v[2:3], v[34:35], v[6:7]
	global_store_dwordx4 v[108:109], v[32:35], off offset:576 sc1
	s_nop 1
	v_cvt_pk_bf16_f32 v32, v32, v33
	v_cvt_pk_bf16_f32 v33, v34, v35
	global_store_dwordx2 v[104:105], v[32:33], off offset:288
.LBB0_395:
	v_lshlrev_b32_e32 v32, 3, v199
	ds_read_b64 v[96:97], v32 offset:8192
	v_lshlrev_b64 v[32:33], 10, v[170:171]
	v_lshl_add_u64 v[100:101], v[32:33], 0, v[160:161]
	v_readlane_b32 s4, v254, 1
	v_readlane_b32 s10, v254, 7
	s_waitcnt lgkmcnt(0)
	v_sub_f32_e32 v33, v95, v96
	v_sub_f32_e32 v32, v94, v96
	v_sub_f32_e32 v35, v93, v96
	v_sub_f32_e32 v34, v92, v96
	v_pk_mul_f32 v[92:93], v[96:97], v[34:35] op_sel:[1,0]
	v_pk_mul_f32 v[32:33], v[96:97], v[32:33] op_sel:[1,0]
	v_readlane_b32 s11, v254, 8
	v_mov_b32_e32 v98, v97
	v_mov_b32_e32 v99, v97
	v_pk_fma_f32 v[34:35], v[26:27], v[32:33], v[30:31]
	v_pk_fma_f32 v[32:33], v[24:25], v[92:93], v[28:29]
	v_lshl_add_u64 v[92:93], v[100:101], 2, s[10:11]
	s_mov_b64 s[2:3], -1
	s_and_b64 vcc, exec, s[38:39]
	v_sub_f32_e32 v91, v91, v96
	v_sub_f32_e32 v90, v90, v96
	v_sub_f32_e32 v95, v89, v96
	v_sub_f32_e32 v94, v88, v96
	v_readlane_b32 s5, v254, 2
	v_readlane_b32 s6, v254, 3
	v_readlane_b32 s7, v254, 4
	v_readlane_b32 s8, v254, 5
	v_readlane_b32 s9, v254, 6
	global_store_dwordx4 v[92:93], v[32:35], off sc1
	s_cbranch_vccz .LBB0_397
	v_mov_b32_e32 v102, v97
	v_mov_b32_e32 v103, v97
	v_pk_mul_f32 v[88:89], v[98:99], v[94:95]
	v_pk_mul_f32 v[102:103], v[102:103], v[90:91]
	s_mov_b64 s[2:3], 0
	v_pk_fma_f32 v[104:105], v[18:19], v[102:103], v[22:23]
	v_pk_fma_f32 v[102:103], v[16:17], v[88:89], v[20:21]
	global_store_dwordx4 v[92:93], v[102:105], off offset:64 sc1
.LBB0_397:
	s_andn2_b64 vcc, exec, s[2:3]
	v_lshl_add_u64 v[88:89], v[100:101], 1, s[80:81]
	s_cbranch_vccnz .LBB0_399
	v_cvt_pk_bf16_f32 v32, v32, v33
	v_cvt_pk_bf16_f32 v33, v34, v35
	v_mov_b32_e32 v34, v97
	v_mov_b32_e32 v35, v97
	global_store_dwordx2 v[88:89], v[32:33], off
	v_pk_mul_f32 v[32:33], v[98:99], v[94:95]
	v_pk_mul_f32 v[34:35], v[34:35], v[90:91]
	v_pk_fma_f32 v[32:33], v[16:17], v[32:33], v[20:21]
	v_pk_fma_f32 v[34:35], v[18:19], v[34:35], v[22:23]
	global_store_dwordx4 v[92:93], v[32:35], off offset:64 sc1
	s_nop 1
	v_cvt_pk_bf16_f32 v32, v32, v33
	v_cvt_pk_bf16_f32 v33, v34, v35
	global_store_dwordx2 v[88:89], v[32:33], off offset:32
.LBB0_399:
	v_sub_f32_e32 v33, v87, v96
	v_sub_f32_e32 v32, v86, v96
	v_sub_f32_e32 v35, v85, v96
	v_sub_f32_e32 v34, v84, v96
	v_mov_b32_e32 v84, v97
	v_mov_b32_e32 v85, v97
	v_pk_mul_f32 v[86:87], v[98:99], v[34:35]
	v_pk_mul_f32 v[32:33], v[84:85], v[32:33]
	s_mov_b64 s[2:3], -1
	v_pk_fma_f32 v[34:35], v[10:11], v[32:33], v[14:15]
	v_pk_fma_f32 v[32:33], v[8:9], v[86:87], v[12:13]
	s_and_b64 vcc, exec, s[38:39]
	v_sub_f32_e32 v83, v83, v96
	v_sub_f32_e32 v82, v82, v96
	v_sub_f32_e32 v81, v81, v96
	v_sub_f32_e32 v80, v80, v96
	global_store_dwordx4 v[92:93], v[32:35], off offset:512 sc1
	s_cbranch_vccz .LBB0_401
	v_pk_mul_f32 v[90:91], v[98:99], v[80:81]
	v_pk_mul_f32 v[84:85], v[84:85], v[82:83]
	s_mov_b64 s[2:3], 0
	v_pk_fma_f32 v[86:87], v[2:3], v[84:85], v[6:7]
	v_pk_fma_f32 v[84:85], v[0:1], v[90:91], v[4:5]
	global_store_dwordx4 v[92:93], v[84:87], off offset:576 sc1
.LBB0_401:
	s_andn2_b64 vcc, exec, s[2:3]
	s_cbranch_vccnz .LBB0_403
	v_cvt_pk_bf16_f32 v32, v32, v33
	v_cvt_pk_bf16_f32 v33, v34, v35
	v_mov_b32_e32 v96, v97
	global_store_dwordx2 v[88:89], v[32:33], off offset:256
	v_pk_mul_f32 v[32:33], v[98:99], v[80:81]
	v_pk_mul_f32 v[34:35], v[96:97], v[82:83]
	v_pk_fma_f32 v[32:33], v[0:1], v[32:33], v[4:5]
	v_pk_fma_f32 v[34:35], v[2:3], v[34:35], v[6:7]
	global_store_dwordx4 v[92:93], v[32:35], off offset:576 sc1
	s_nop 1
	v_cvt_pk_bf16_f32 v32, v32, v33
	v_cvt_pk_bf16_f32 v33, v34, v35
	global_store_dwordx2 v[88:89], v[32:33], off offset:288
.LBB0_403:
	v_lshlrev_b32_e32 v32, 3, v200
	ds_read_b64 v[80:81], v32 offset:8192
	v_lshlrev_b64 v[32:33], 10, v[172:173]
	v_lshl_add_u64 v[84:85], v[32:33], 0, v[160:161]
	v_readlane_b32 s4, v254, 1
	v_readlane_b32 s10, v254, 7
	s_waitcnt lgkmcnt(0)
	v_sub_f32_e32 v33, v79, v80
	v_sub_f32_e32 v32, v78, v80
	v_sub_f32_e32 v35, v77, v80
	v_sub_f32_e32 v34, v76, v80
	v_pk_mul_f32 v[76:77], v[80:81], v[34:35] op_sel:[1,0]
	v_pk_mul_f32 v[32:33], v[80:81], v[32:33] op_sel:[1,0]
	v_readlane_b32 s11, v254, 8
	v_mov_b32_e32 v82, v81
	v_mov_b32_e32 v83, v81
	v_pk_fma_f32 v[34:35], v[26:27], v[32:33], v[30:31]
	v_pk_fma_f32 v[32:33], v[24:25], v[76:77], v[28:29]
	v_lshl_add_u64 v[76:77], v[84:85], 2, s[10:11]
	s_mov_b64 s[2:3], -1
	s_and_b64 vcc, exec, s[38:39]
	v_sub_f32_e32 v75, v75, v80
	v_sub_f32_e32 v74, v74, v80
	v_sub_f32_e32 v79, v73, v80
	v_sub_f32_e32 v78, v72, v80
	v_readlane_b32 s5, v254, 2
	v_readlane_b32 s6, v254, 3
	v_readlane_b32 s7, v254, 4
	v_readlane_b32 s8, v254, 5
	v_readlane_b32 s9, v254, 6
	global_store_dwordx4 v[76:77], v[32:35], off sc1
	s_cbranch_vccz .LBB0_405
	v_mov_b32_e32 v86, v81
	v_mov_b32_e32 v87, v81
	v_pk_mul_f32 v[72:73], v[82:83], v[78:79]
	v_pk_mul_f32 v[86:87], v[86:87], v[74:75]
	s_mov_b64 s[2:3], 0
	v_pk_fma_f32 v[88:89], v[18:19], v[86:87], v[22:23]
	v_pk_fma_f32 v[86:87], v[16:17], v[72:73], v[20:21]
	global_store_dwordx4 v[76:77], v[86:89], off offset:64 sc1
.LBB0_405:
	s_andn2_b64 vcc, exec, s[2:3]
	v_lshl_add_u64 v[72:73], v[84:85], 1, s[80:81]
	s_cbranch_vccnz .LBB0_407
	v_cvt_pk_bf16_f32 v32, v32, v33
	v_cvt_pk_bf16_f32 v33, v34, v35
	v_mov_b32_e32 v34, v81
	v_mov_b32_e32 v35, v81
	global_store_dwordx2 v[72:73], v[32:33], off
	v_pk_mul_f32 v[32:33], v[82:83], v[78:79]
	v_pk_mul_f32 v[34:35], v[34:35], v[74:75]
	v_pk_fma_f32 v[32:33], v[16:17], v[32:33], v[20:21]
	v_pk_fma_f32 v[34:35], v[18:19], v[34:35], v[22:23]
	global_store_dwordx4 v[76:77], v[32:35], off offset:64 sc1
	s_nop 1
	v_cvt_pk_bf16_f32 v32, v32, v33
	v_cvt_pk_bf16_f32 v33, v34, v35
	global_store_dwordx2 v[72:73], v[32:33], off offset:32
.LBB0_407:
	v_sub_f32_e32 v33, v71, v80
	v_sub_f32_e32 v32, v70, v80
	v_sub_f32_e32 v35, v69, v80
	v_sub_f32_e32 v34, v68, v80
	v_mov_b32_e32 v68, v81
	v_mov_b32_e32 v69, v81
	v_pk_mul_f32 v[70:71], v[82:83], v[34:35]
	v_pk_mul_f32 v[32:33], v[68:69], v[32:33]
	s_mov_b64 s[2:3], -1
	v_pk_fma_f32 v[34:35], v[10:11], v[32:33], v[14:15]
	v_pk_fma_f32 v[32:33], v[8:9], v[70:71], v[12:13]
	s_and_b64 vcc, exec, s[38:39]
	v_sub_f32_e32 v67, v67, v80
	v_sub_f32_e32 v66, v66, v80
	v_sub_f32_e32 v65, v65, v80
	v_sub_f32_e32 v64, v64, v80
	global_store_dwordx4 v[76:77], v[32:35], off offset:512 sc1
	s_cbranch_vccz .LBB0_409
	v_pk_mul_f32 v[74:75], v[82:83], v[64:65]
	v_pk_mul_f32 v[68:69], v[68:69], v[66:67]
	s_mov_b64 s[2:3], 0
	v_pk_fma_f32 v[70:71], v[2:3], v[68:69], v[6:7]
	v_pk_fma_f32 v[68:69], v[0:1], v[74:75], v[4:5]
	global_store_dwordx4 v[76:77], v[68:71], off offset:576 sc1
.LBB0_409:
	s_andn2_b64 vcc, exec, s[2:3]
	s_cbranch_vccnz .LBB0_411
	v_cvt_pk_bf16_f32 v32, v32, v33
	v_cvt_pk_bf16_f32 v33, v34, v35
	v_mov_b32_e32 v80, v81
	global_store_dwordx2 v[72:73], v[32:33], off offset:256
	v_pk_mul_f32 v[32:33], v[82:83], v[64:65]
	v_pk_mul_f32 v[34:35], v[80:81], v[66:67]
	v_pk_fma_f32 v[32:33], v[0:1], v[32:33], v[4:5]
	v_pk_fma_f32 v[34:35], v[2:3], v[34:35], v[6:7]
	global_store_dwordx4 v[76:77], v[32:35], off offset:576 sc1
	s_nop 1
	v_cvt_pk_bf16_f32 v32, v32, v33
	v_cvt_pk_bf16_f32 v33, v34, v35
	global_store_dwordx2 v[72:73], v[32:33], off offset:288
.LBB0_411:
	v_lshlrev_b32_e32 v32, 3, v201
	ds_read_b64 v[64:65], v32 offset:8192
	v_lshlrev_b64 v[32:33], 10, v[174:175]
	v_lshl_add_u64 v[68:69], v[32:33], 0, v[160:161]
	v_readlane_b32 s4, v254, 1
	v_readlane_b32 s10, v254, 7
	s_waitcnt lgkmcnt(0)
	v_sub_f32_e32 v33, v63, v64
	v_sub_f32_e32 v32, v62, v64
	v_sub_f32_e32 v35, v61, v64
	v_sub_f32_e32 v34, v60, v64
	v_pk_mul_f32 v[60:61], v[64:65], v[34:35] op_sel:[1,0]
	v_pk_mul_f32 v[32:33], v[64:65], v[32:33] op_sel:[1,0]
	v_readlane_b32 s11, v254, 8
	v_mov_b32_e32 v66, v65
	v_mov_b32_e32 v67, v65
	v_pk_fma_f32 v[34:35], v[26:27], v[32:33], v[30:31]
	v_pk_fma_f32 v[32:33], v[24:25], v[60:61], v[28:29]
	v_lshl_add_u64 v[60:61], v[68:69], 2, s[10:11]
	s_mov_b64 s[2:3], -1
	s_and_b64 vcc, exec, s[38:39]
	v_sub_f32_e32 v59, v59, v64
	v_sub_f32_e32 v58, v58, v64
	v_sub_f32_e32 v63, v57, v64
	v_sub_f32_e32 v62, v56, v64
	v_readlane_b32 s5, v254, 2
	v_readlane_b32 s6, v254, 3
	v_readlane_b32 s7, v254, 4
	v_readlane_b32 s8, v254, 5
	v_readlane_b32 s9, v254, 6
	global_store_dwordx4 v[60:61], v[32:35], off sc1
	s_cbranch_vccz .LBB0_413
	v_mov_b32_e32 v70, v65
	v_mov_b32_e32 v71, v65
	v_pk_mul_f32 v[56:57], v[66:67], v[62:63]
	v_pk_mul_f32 v[70:71], v[70:71], v[58:59]
	s_mov_b64 s[2:3], 0
	v_pk_fma_f32 v[72:73], v[18:19], v[70:71], v[22:23]
	v_pk_fma_f32 v[70:71], v[16:17], v[56:57], v[20:21]
	global_store_dwordx4 v[60:61], v[70:73], off offset:64 sc1
.LBB0_413:
	s_andn2_b64 vcc, exec, s[2:3]
	v_lshl_add_u64 v[56:57], v[68:69], 1, s[80:81]
	s_cbranch_vccnz .LBB0_415
	v_cvt_pk_bf16_f32 v32, v32, v33
	v_cvt_pk_bf16_f32 v33, v34, v35
	v_mov_b32_e32 v34, v65
	v_mov_b32_e32 v35, v65
	global_store_dwordx2 v[56:57], v[32:33], off
	v_pk_mul_f32 v[32:33], v[66:67], v[62:63]
	v_pk_mul_f32 v[34:35], v[34:35], v[58:59]
	v_pk_fma_f32 v[32:33], v[16:17], v[32:33], v[20:21]
	v_pk_fma_f32 v[34:35], v[18:19], v[34:35], v[22:23]
	global_store_dwordx4 v[60:61], v[32:35], off offset:64 sc1
	s_nop 1
	v_cvt_pk_bf16_f32 v32, v32, v33
	v_cvt_pk_bf16_f32 v33, v34, v35
	global_store_dwordx2 v[56:57], v[32:33], off offset:32
.LBB0_415:
	v_sub_f32_e32 v33, v55, v64
	v_sub_f32_e32 v32, v54, v64
	v_sub_f32_e32 v35, v53, v64
	v_sub_f32_e32 v34, v52, v64
	v_mov_b32_e32 v52, v65
	v_mov_b32_e32 v53, v65
	v_pk_mul_f32 v[54:55], v[66:67], v[34:35]
	v_pk_mul_f32 v[32:33], v[52:53], v[32:33]
	s_mov_b64 s[2:3], -1
	v_pk_fma_f32 v[34:35], v[10:11], v[32:33], v[14:15]
	v_pk_fma_f32 v[32:33], v[8:9], v[54:55], v[12:13]
	s_and_b64 vcc, exec, s[38:39]
	v_sub_f32_e32 v51, v51, v64
	v_sub_f32_e32 v50, v50, v64
	v_sub_f32_e32 v49, v49, v64
	v_sub_f32_e32 v48, v48, v64
	global_store_dwordx4 v[60:61], v[32:35], off offset:512 sc1
	s_cbranch_vccz .LBB0_417
	v_pk_mul_f32 v[58:59], v[66:67], v[48:49]
	v_pk_mul_f32 v[52:53], v[52:53], v[50:51]
	s_mov_b64 s[2:3], 0
	v_pk_fma_f32 v[54:55], v[2:3], v[52:53], v[6:7]
	v_pk_fma_f32 v[52:53], v[0:1], v[58:59], v[4:5]
	global_store_dwordx4 v[60:61], v[52:55], off offset:576 sc1
.LBB0_417:
	s_andn2_b64 vcc, exec, s[2:3]
	s_cbranch_vccnz .LBB0_419
	v_cvt_pk_bf16_f32 v32, v32, v33
	v_cvt_pk_bf16_f32 v33, v34, v35
	v_mov_b32_e32 v64, v65
	global_store_dwordx2 v[56:57], v[32:33], off offset:256
	v_pk_mul_f32 v[32:33], v[66:67], v[48:49]
	v_pk_mul_f32 v[34:35], v[64:65], v[50:51]
	v_pk_fma_f32 v[32:33], v[0:1], v[32:33], v[4:5]
	v_pk_fma_f32 v[34:35], v[2:3], v[34:35], v[6:7]
	global_store_dwordx4 v[60:61], v[32:35], off offset:576 sc1
	s_nop 1
	v_cvt_pk_bf16_f32 v32, v32, v33
	v_cvt_pk_bf16_f32 v33, v34, v35
	global_store_dwordx2 v[56:57], v[32:33], off offset:288
.LBB0_419:
	v_lshlrev_b32_e32 v32, 3, v202
	ds_read_b64 v[32:33], v32 offset:8192
	v_lshlrev_b64 v[34:35], 10, v[186:187]
	v_readlane_b32 s4, v254, 1
	v_lshl_add_u64 v[48:49], v[34:35], 0, v[160:161]
	v_readlane_b32 s10, v254, 7
	s_waitcnt lgkmcnt(0)
	v_sub_f32_e32 v47, v47, v32
	v_sub_f32_e32 v46, v46, v32
	v_sub_f32_e32 v45, v45, v32
	v_sub_f32_e32 v44, v44, v32
	v_pk_mul_f32 v[44:45], v[32:33], v[44:45] op_sel:[1,0]
	v_pk_mul_f32 v[46:47], v[32:33], v[46:47] op_sel:[1,0]
	v_readlane_b32 s11, v254, 8
	v_mov_b32_e32 v34, v33
	v_mov_b32_e32 v35, v33
	v_pk_fma_f32 v[26:27], v[26:27], v[46:47], v[30:31]
	v_pk_fma_f32 v[24:25], v[24:25], v[44:45], v[28:29]
	v_lshl_add_u64 v[28:29], v[48:49], 2, s[10:11]
	s_mov_b64 s[2:3], -1
	s_and_b64 vcc, exec, s[38:39]
	v_sub_f32_e32 v43, v43, v32
	v_sub_f32_e32 v42, v42, v32
	v_sub_f32_e32 v41, v41, v32
	v_sub_f32_e32 v40, v40, v32
	v_readlane_b32 s5, v254, 2
	v_readlane_b32 s6, v254, 3
	v_readlane_b32 s7, v254, 4
	v_readlane_b32 s8, v254, 5
	v_readlane_b32 s9, v254, 6
	global_store_dwordx4 v[28:29], v[24:27], off sc1
	s_cbranch_vccz .LBB0_421
	v_mov_b32_e32 v44, v33
	v_mov_b32_e32 v45, v33
	v_pk_mul_f32 v[30:31], v[34:35], v[40:41]
	v_pk_mul_f32 v[44:45], v[44:45], v[42:43]
	s_mov_b64 s[2:3], 0
	v_pk_fma_f32 v[46:47], v[18:19], v[44:45], v[22:23]
	v_pk_fma_f32 v[44:45], v[16:17], v[30:31], v[20:21]
	global_store_dwordx4 v[28:29], v[44:47], off offset:64 sc1
.LBB0_421:
	s_andn2_b64 vcc, exec, s[2:3]
	v_lshl_add_u64 v[30:31], v[48:49], 1, s[80:81]
	s_cbranch_vccnz .LBB0_423
	v_cvt_pk_bf16_f32 v24, v24, v25
	v_cvt_pk_bf16_f32 v25, v26, v27
	v_mov_b32_e32 v26, v33
	v_mov_b32_e32 v27, v33
	global_store_dwordx2 v[30:31], v[24:25], off
	v_pk_mul_f32 v[24:25], v[34:35], v[40:41]
	v_pk_mul_f32 v[26:27], v[26:27], v[42:43]
	v_pk_fma_f32 v[16:17], v[16:17], v[24:25], v[20:21]
	v_pk_fma_f32 v[18:19], v[18:19], v[26:27], v[22:23]
	global_store_dwordx4 v[28:29], v[16:19], off offset:64 sc1
	s_nop 1
	v_cvt_pk_bf16_f32 v16, v16, v17
	v_cvt_pk_bf16_f32 v17, v18, v19
	global_store_dwordx2 v[30:31], v[16:17], off offset:32
.LBB0_423:
	v_sub_f32_e32 v17, v37, v32
	v_sub_f32_e32 v16, v36, v32
	v_sub_f32_e32 v19, v39, v32
	v_sub_f32_e32 v18, v38, v32
	v_pk_mul_f32 v[20:21], v[34:35], v[16:17]
	v_mov_b32_e32 v16, v33
	v_mov_b32_e32 v17, v33
	v_pk_mul_f32 v[18:19], v[16:17], v[18:19]
	v_pk_fma_f32 v[8:9], v[8:9], v[20:21], v[12:13]
	v_pk_fma_f32 v[10:11], v[10:11], v[18:19], v[14:15]
	s_mov_b64 s[2:3], -1
	s_and_b64 vcc, exec, s[38:39]
	v_sub_f32_e32 v13, v189, v32
	v_sub_f32_e32 v12, v188, v32
	v_sub_f32_e32 v15, v191, v32
	v_sub_f32_e32 v14, v190, v32
	global_store_dwordx4 v[28:29], v[8:11], off offset:512 sc1
	s_cbranch_vccz .LBB0_425
	v_pk_mul_f32 v[20:21], v[34:35], v[14:15]
	v_pk_mul_f32 v[16:17], v[16:17], v[12:13]
	s_mov_b64 s[2:3], 0
	v_pk_fma_f32 v[18:19], v[2:3], v[16:17], v[6:7]
	v_pk_fma_f32 v[16:17], v[0:1], v[20:21], v[4:5]
	global_store_dwordx4 v[28:29], v[16:19], off offset:576 sc1
.LBB0_425:
	s_andn2_b64 vcc, exec, s[2:3]
	s_cbranch_vccnz .LBB0_427
	v_cvt_pk_bf16_f32 v8, v8, v9
	v_cvt_pk_bf16_f32 v9, v10, v11
	v_mov_b32_e32 v32, v33
	global_store_dwordx2 v[30:31], v[8:9], off offset:256
	v_pk_mul_f32 v[8:9], v[34:35], v[14:15]
	v_pk_mul_f32 v[10:11], v[32:33], v[12:13]
	v_pk_fma_f32 v[0:1], v[0:1], v[8:9], v[4:5]
	v_pk_fma_f32 v[2:3], v[2:3], v[10:11], v[6:7]
	global_store_dwordx4 v[28:29], v[0:3], off offset:576 sc1
	s_nop 1
	v_cvt_pk_bf16_f32 v0, v0, v1
	v_cvt_pk_bf16_f32 v1, v2, v3
	global_store_dwordx2 v[30:31], v[0:1], off offset:288

.LBB0_441:
	v_lshl_or_b32 v144, s72, 8, v141
	v_lshl_add_u32 v143, s4, 8, v138
	v_ashrrev_i32_e32 v145, 31, v144
	v_lshl_add_u64 v[144:145], v[144:145], 1, s[76:77]
	v_cvt_pk_bf16_f32 v68, v68, v69
	v_cvt_pk_bf16_f32 v69, v70, v71
	v_cvt_pk_bf16_f32 v70, v64, v65
	v_add_u32_e32 v64, 0x80, v143
	v_mad_i64_i32 v[146:147], s[2:3], v143, s13, v[144:145]
	v_cvt_pk_bf16_f32 v108, v108, v109
	v_cvt_pk_bf16_f32 v109, v110, v111
	v_cvt_pk_bf16_f32 v110, v104, v105
	v_cvt_pk_bf16_f32 v111, v106, v107
	v_or_b32_e32 v104, 16, v143
	v_mad_i64_i32 v[64:65], s[2:3], v64, s13, v[144:145]
	v_cvt_pk_bf16_f32 v44, v44, v45
	v_cvt_pk_bf16_f32 v45, v46, v47
	v_cvt_pk_bf16_f32 v46, v40, v41
	v_cvt_pk_bf16_f32 v47, v42, v43
	v_add_u32_e32 v40, 0x90, v143
	global_store_dwordx4 v[146:147], v[108:111], off offset:256 sc1
	v_cvt_pk_bf16_f32 v92, v92, v93
	v_cvt_pk_bf16_f32 v93, v94, v95
	v_mad_i64_i32 v[108:109], s[2:3], v104, s13, v[144:145]
	v_cvt_pk_bf16_f32 v94, v88, v89
	v_cvt_pk_bf16_f32 v95, v90, v91
	v_or_b32_e32 v88, 32, v143
	global_store_dwordx4 v[64:65], v[44:47], off offset:256 sc1
	v_cvt_pk_bf16_f32 v28, v28, v29
	v_cvt_pk_bf16_f32 v29, v30, v31
	v_mad_i64_i32 v[44:45], s[2:3], v40, s13, v[144:145]
	v_cvt_pk_bf16_f32 v30, v24, v25
	v_cvt_pk_bf16_f32 v31, v26, v27
	v_add_u32_e32 v24, 0xa0, v143
	global_store_dwordx4 v[108:109], v[92:95], off offset:256 sc1
	v_cvt_pk_bf16_f32 v76, v76, v77
	v_cvt_pk_bf16_f32 v77, v78, v79
	v_mad_i64_i32 v[92:93], s[2:3], v88, s13, v[144:145]
	v_cvt_pk_bf16_f32 v78, v72, v73
	v_cvt_pk_bf16_f32 v79, v74, v75
	v_or_b32_e32 v72, 48, v143
	global_store_dwordx4 v[44:45], v[28:31], off offset:256 sc1
	v_cvt_pk_bf16_f32 v12, v12, v13
	v_cvt_pk_bf16_f32 v13, v14, v15
	v_mad_i64_i32 v[28:29], s[2:3], v24, s13, v[144:145]
	v_cvt_pk_bf16_f32 v14, v8, v9
	v_cvt_pk_bf16_f32 v15, v10, v11
	v_add_u32_e32 v8, 0xb0, v143
	global_store_dwordx4 v[92:93], v[76:79], off offset:256 sc1
	global_store_dwordx4 v[28:29], v[12:15], off offset:256 sc1
	v_cvt_pk_bf16_f32 v124, v124, v125
	v_mad_i64_i32 v[76:77], s[2:3], v72, s13, v[144:145]
	v_mad_i64_i32 v[12:13], s[2:3], v8, s13, v[144:145]
	v_cvt_pk_bf16_f32 v125, v126, v127
	v_cvt_pk_bf16_f32 v126, v120, v121
	v_cvt_pk_bf16_f32 v127, v122, v123
	v_cvt_pk_bf16_f32 v104, v116, v117
	v_cvt_pk_bf16_f32 v105, v118, v119
	v_cvt_pk_bf16_f32 v106, v112, v113
	v_cvt_pk_bf16_f32 v107, v114, v115
	v_cvt_pk_bf16_f32 v88, v100, v101
	v_cvt_pk_bf16_f32 v89, v102, v103
	v_cvt_pk_bf16_f32 v90, v96, v97
	v_cvt_pk_bf16_f32 v91, v98, v99
	v_cvt_pk_bf16_f32 v72, v84, v85
	v_cvt_pk_bf16_f32 v73, v86, v87
	v_cvt_pk_bf16_f32 v74, v80, v81
	v_cvt_pk_bf16_f32 v75, v82, v83
	v_cvt_pk_bf16_f32 v71, v66, v67
	v_cvt_pk_bf16_f32 v60, v60, v61
	v_cvt_pk_bf16_f32 v61, v62, v63
	v_cvt_pk_bf16_f32 v62, v56, v57
	v_cvt_pk_bf16_f32 v63, v58, v59
	v_cvt_pk_bf16_f32 v40, v52, v53
	v_cvt_pk_bf16_f32 v41, v54, v55
	v_cvt_pk_bf16_f32 v42, v48, v49
	v_cvt_pk_bf16_f32 v43, v50, v51
	v_cvt_pk_bf16_f32 v24, v36, v37
	v_cvt_pk_bf16_f32 v25, v38, v39
	v_cvt_pk_bf16_f32 v26, v32, v33
	v_cvt_pk_bf16_f32 v27, v34, v35
	v_cvt_pk_bf16_f32 v8, v20, v21
	v_cvt_pk_bf16_f32 v9, v22, v23
	v_cvt_pk_bf16_f32 v10, v16, v17
	v_cvt_pk_bf16_f32 v11, v18, v19
	v_cvt_pk_bf16_f32 v4, v4, v5
	v_cvt_pk_bf16_f32 v5, v6, v7
	v_cvt_pk_bf16_f32 v6, v0, v1
	v_cvt_pk_bf16_f32 v7, v2, v3
	s_andn2_b64 vcc, exec, s[36:37]
	s_mov_b64 s[2:3], -1
	global_store_dwordx4 v[146:147], v[124:127], off sc1
	global_store_dwordx4 v[108:109], v[104:107], off sc1
	global_store_dwordx4 v[92:93], v[88:91], off sc1
	global_store_dwordx4 v[76:77], v[72:75], off sc1
	global_store_dwordx4 v[76:77], v[68:71], off offset:256 sc1
	global_store_dwordx4 v[64:65], v[60:63], off sc1
	global_store_dwordx4 v[44:45], v[40:43], off sc1
	global_store_dwordx4 v[28:29], v[24:27], off sc1
	global_store_dwordx4 v[12:13], v[8:11], off sc1
	global_store_dwordx4 v[12:13], v[4:7], off offset:256 sc1
	s_cbranch_vccnz .LBB0_434
	s_andn2_b64 vcc, exec, s[40:41]
	s_cbranch_vccnz .LBB0_433
	s_barrier
	s_branch .LBB0_433

.LBB0_473:
	v_lshl_add_u64 v[24:25], v[10:11], 0, s[6:7]
	global_load_dwordx4 v[16:19], v[24:25], off offset:-256
	v_lshl_add_u64 v[20:21], v[12:13], 0, s[6:7]
	v_add_co_u32_e32 v26, vcc, 0x1e80000, v20
	s_add_u32 s6, s6, 0x200
	s_nop 0
	v_addc_co_u32_e32 v27, vcc, 0, v21, vcc
	global_load_dwordx4 v[20:23], v[26:27], off
	s_addc_u32 s7, s7, 0
	s_cmpk_eq_i32 s6, 0x800
	s_waitcnt vmcnt(0)
	v_mfma_f32_16x16x32_bf16 v[0:3], v[16:19], v[20:23], v[0:3]
	global_load_dwordx4 v[16:19], v[24:25], off offset:-192
	global_load_dwordx4 v[20:23], v[26:27], off offset:64
	s_waitcnt vmcnt(0)
	v_mfma_f32_16x16x32_bf16 v[0:3], v[16:19], v[20:23], v[0:3]
	global_load_dwordx4 v[16:19], v[24:25], off offset:-128
	global_load_dwordx4 v[20:23], v[26:27], off offset:128
	s_waitcnt vmcnt(0)
	v_mfma_f32_16x16x32_bf16 v[0:3], v[16:19], v[20:23], v[0:3]
	global_load_dwordx4 v[16:19], v[24:25], off offset:-64
	global_load_dwordx4 v[20:23], v[26:27], off offset:192
	s_waitcnt vmcnt(0)
	v_mfma_f32_16x16x32_bf16 v[0:3], v[16:19], v[20:23], v[0:3]
	global_load_dwordx4 v[16:19], v[24:25], off
	global_load_dwordx4 v[20:23], v[26:27], off offset:256
	s_waitcnt vmcnt(0)
	v_mfma_f32_16x16x32_bf16 v[0:3], v[16:19], v[20:23], v[0:3]
	global_load_dwordx4 v[16:19], v[24:25], off offset:64
	global_load_dwordx4 v[20:23], v[26:27], off offset:320
	s_waitcnt vmcnt(0)
	v_mfma_f32_16x16x32_bf16 v[0:3], v[16:19], v[20:23], v[0:3]
	global_load_dwordx4 v[16:19], v[24:25], off offset:128
	global_load_dwordx4 v[20:23], v[26:27], off offset:384
	s_waitcnt vmcnt(0)
	v_mfma_f32_16x16x32_bf16 v[0:3], v[16:19], v[20:23], v[0:3]
	global_load_dwordx4 v[16:19], v[24:25], off offset:192
	global_load_dwordx4 v[20:23], v[26:27], off offset:448
	s_waitcnt vmcnt(0)
	v_mfma_f32_16x16x32_bf16 v[0:3], v[16:19], v[20:23], v[0:3]
	s_cbranch_scc0 .LBB0_473
	v_lshl_or_b32 v12, v14, 4, v15
	v_ashrrev_i32_e32 v13, 31, v12
	v_add_u32_e32 v14, s8, v14
	s_movk_i32 s6, 0x3ff
	v_lshlrev_b64 v[12:13], 6, v[12:13]
	v_cmp_lt_i32_e32 vcc, s6, v14
	v_lshl_add_u64 v[12:13], v[4:5], 0, v[12:13]
	s_or_b64 s[4:5], vcc, s[4:5]
	v_add_u32_e32 v8, s9, v8
	global_store_dwordx4 v[12:13], v[0:3], off sc1
	s_andn2_b64 exec, exec, s[4:5]
	s_cbranch_execnz .LBB0_472

.LBB0_481:
	s_mul_hi_i32 s2, s22, 0x84210843
	s_add_i32 s2, s2, s22
	s_lshr_b32 s3, s2, 31
	s_ashr_i32 s2, s2, 8
	s_add_i32 s4, s2, s3
	s_mul_i32 s2, s4, 0xfffffe10
	s_add_i32 s8, s22, s2
	s_cmpk_gt_i32 s8, 0x17f
	s_cbranch_scc0 .LBB0_492
	s_cmpk_gt_u32 s8, 0x1af
	s_cbranch_scc0 .LBB0_493
	s_ashr_i32 s5, s4, 31
	s_lshl_b64 s[2:3], s[4:5], 22
	v_readlane_b32 s24, v254, 1
	v_readlane_b32 s25, v254, 2
	s_add_u32 s2, s24, s2
	s_mul_i32 s6, s4, 0xffffe100
	s_addc_u32 s3, s25, s3
	s_add_i32 s6, s20, s6
	v_mov_b32_e32 v35, v206
	s_and_b32 s7, s12, 0x3c0
	s_and_b32 s6, s6, 0x7fffff00
	s_addk_i32 s6, 0xe500
	v_lshlrev_b32_e32 v0, 2, v35
	v_ashrrev_i32_e32 v32, 6, v35
	v_add_u32_e32 v6, 0x200, v35
	v_and_b32_e32 v7, 0xfc, v0
	v_add_u32_e32 v2, s7, v32
	v_ashrrev_i32_e32 v33, 6, v6
	v_or_b32_e32 v176, s6, v7
	v_ashrrev_i32_e32 v3, 31, v2
	v_add_u32_e32 v4, s7, v33
	v_lshl_add_u64 v[0:1], v[176:177], 2, s[2:3]
	v_lshlrev_b64 v[2:3], 12, v[2:3]
	v_ashrrev_i32_e32 v5, 31, v4
	v_lshl_add_u64 v[2:3], v[0:1], 0, v[2:3]
	v_lshlrev_b64 v[4:5], 12, v[4:5]
	s_waitcnt vmcnt(0)
	s_barrier
	v_lshl_add_u64 v[4:5], v[0:1], 0, v[4:5]
	global_load_dwordx4 v[8:11], v[2:3], off
	global_load_dwordx4 v[12:15], v[4:5], off
	v_add_u32_e32 v3, 0x400, v35
	v_add_u32_e32 v2, 0x600, v35
	v_ashrrev_i32_e32 v44, 6, v3
	v_ashrrev_i32_e32 v46, 6, v2
	v_add_u32_e32 v4, s7, v44
	v_add_u32_e32 v16, s7, v46
	v_ashrrev_i32_e32 v5, 31, v4
	v_ashrrev_i32_e32 v17, 31, v16
	v_lshlrev_b64 v[4:5], 12, v[4:5]
	v_lshlrev_b64 v[16:17], 12, v[16:17]
	v_lshl_add_u64 v[4:5], v[0:1], 0, v[4:5]
	v_lshl_add_u64 v[20:21], v[0:1], 0, v[16:17]
	global_load_dwordx4 v[16:19], v[4:5], off
	s_nop 0
	global_load_dwordx4 v[20:23], v[20:21], off
	v_add_u32_e32 v4, 0x800, v35
	v_add_u32_e32 v24, 0xa00, v35
	v_ashrrev_i32_e32 v47, 6, v4
	v_ashrrev_i32_e32 v48, 6, v24
	v_add_u32_e32 v4, s7, v47
	v_add_u32_e32 v24, s7, v48
	v_ashrrev_i32_e32 v5, 31, v4
	v_ashrrev_i32_e32 v25, 31, v24
	v_lshlrev_b64 v[4:5], 12, v[4:5]
	v_lshlrev_b64 v[24:25], 12, v[24:25]
	v_lshl_add_u64 v[4:5], v[0:1], 0, v[4:5]
	v_lshl_add_u64 v[28:29], v[0:1], 0, v[24:25]
	global_load_dwordx4 v[24:27], v[4:5], off
	s_nop 0
	global_load_dwordx4 v[28:31], v[28:29], off
	v_add_u32_e32 v4, 0xc00, v35
	v_ashrrev_i32_e32 v49, 6, v4
	v_add_u32_e32 v4, s7, v49
	v_ashrrev_i32_e32 v5, 31, v4
	v_lshlrev_b64 v[4:5], 12, v[4:5]
	v_lshl_add_u64 v[4:5], v[0:1], 0, v[4:5]
	global_load_dwordx4 v[36:39], v[4:5], off
	v_add_u32_e32 v4, 0xe00, v35
	v_ashrrev_i32_e32 v50, 6, v4
	v_add_u32_e32 v4, s7, v50
	v_ashrrev_i32_e32 v5, 31, v4
	v_lshlrev_b64 v[4:5], 12, v[4:5]
	v_lshl_add_u64 v[0:1], v[0:1], 0, v[4:5]
	global_load_dwordx4 v[40:43], v[0:1], off
	s_lshl_b64 s[2:3], s[4:5], 21
	v_lshlrev_b32_e32 v0, 2, v7
	v_mad_u64_u32 v[4:5], s[24:25], v32, s15, v[0:1]
	s_add_u32 s5, s43, s2
	v_readlane_b32 s2, v254, 23
	v_mad_u64_u32 v[32:33], s[24:25], v33, s15, v[0:1]
	v_mad_u64_u32 v[44:45], s[24:25], v44, s15, v[0:1]
	s_addc_u32 s9, s2, s3
	v_readlane_b32 s26, v254, 3
	v_readlane_b32 s27, v254, 4
	v_readlane_b32 s28, v254, 5
	v_readlane_b32 s29, v254, 6
	v_readlane_b32 s30, v254, 7
	v_readlane_b32 s31, v254, 8
	s_waitcnt vmcnt(7)
	ds_write2_b32 v4, v8, v9 offset1:1
	ds_write2_b32 v4, v10, v11 offset0:2 offset1:3
	s_waitcnt vmcnt(6)
	ds_write2_b32 v32, v12, v13 offset1:1
	ds_write2_b32 v32, v14, v15 offset0:2 offset1:3
	s_waitcnt vmcnt(5)
	ds_write2_b32 v44, v16, v17 offset1:1
	ds_write2_b32 v44, v18, v19 offset0:2 offset1:3
	v_mad_u64_u32 v[4:5], s[2:3], v46, s15, v[0:1]
	s_waitcnt vmcnt(4)
	ds_write2_b32 v4, v20, v21 offset1:1
	ds_write2_b32 v4, v22, v23 offset0:2 offset1:3
	v_mad_u64_u32 v[4:5], s[2:3], v47, s15, v[0:1]
	s_waitcnt vmcnt(3)
	ds_write2_b32 v4, v24, v25 offset1:1
	ds_write2_b32 v4, v26, v27 offset0:2 offset1:3
	v_mad_u64_u32 v[4:5], s[2:3], v48, s15, v[0:1]
	s_waitcnt vmcnt(2)
	ds_write2_b32 v4, v28, v29 offset1:1
	ds_write2_b32 v4, v30, v31 offset0:2 offset1:3
	v_mad_u64_u32 v[4:5], s[2:3], v49, s15, v[0:1]
	v_mad_u64_u32 v[0:1], s[2:3], v50, s15, v[0:1]
	s_waitcnt vmcnt(1)
	ds_write2_b32 v4, v36, v37 offset1:1
	ds_write2_b32 v4, v38, v39 offset0:2 offset1:3
	s_waitcnt vmcnt(0)
	ds_write2_b32 v0, v40, v41 offset1:1
	ds_write2_b32 v0, v42, v43 offset0:2 offset1:3
	v_lshlrev_b32_e32 v0, 3, v35
	s_lshl_b32 s2, s7, 1
	v_and_b32_e32 v0, 56, v0
	s_add_u32 s2, s5, s2
	v_ashrrev_i32_e32 v1, 3, v35
	v_mul_u32_u24_e32 v7, 0x404, v0
	s_addc_u32 s3, s9, 0
	v_lshlrev_b32_e32 v176, 1, v0
	v_add_u32_e32 v0, s6, v1
	v_lshl_add_u64 v[4:5], s[2:3], 0, v[176:177]
	v_cmp_gt_i32_e32 vcc, s93, v0
	s_waitcnt lgkmcnt(0)
	s_barrier
	s_and_saveexec_b64 s[2:3], vcc
	s_cbranch_execz .LBB0_485
	v_lshl_add_u32 v1, v1, 2, v7
	ds_read_b32 v8, v1
	ds_read_b32 v9, v1 offset:1028
	s_waitcnt lgkmcnt(0)
	v_cvt_pk_bf16_f32 v8, v8, v9
	ds_read_b32 v9, v1 offset:2056
	ds_read_b32 v10, v1 offset:3084
	s_waitcnt lgkmcnt(0)
	v_cvt_pk_bf16_f32 v9, v9, v10
	ds_read_b32 v10, v1 offset:4112
	ds_read_b32 v11, v1 offset:5140
	s_waitcnt lgkmcnt(0)
	v_cvt_pk_bf16_f32 v10, v10, v11
	ds_read_b32 v11, v1 offset:6168
	ds_read_b32 v1, v1 offset:7196
	s_waitcnt lgkmcnt(0)
	v_cvt_pk_bf16_f32 v11, v11, v1
	v_ashrrev_i32_e32 v1, 31, v0
	v_lshlrev_b64 v[0:1], 11, v[0:1]
	v_lshl_add_u64 v[0:1], v[4:5], 0, v[0:1]
	global_store_dwordx4 v[0:1], v[8:11], off sc1
.LBB0_485:
	s_or_b64 exec, exec, s[2:3]
	v_ashrrev_i32_e32 v1, 3, v6
	v_add_u32_e32 v0, s6, v1
	v_cmp_gt_i32_e32 vcc, s93, v0
	s_and_saveexec_b64 s[2:3], vcc
	s_cbranch_execz .LBB0_487
	v_lshl_add_u32 v1, v1, 2, v7
	ds_read_b32 v6, v1
	ds_read_b32 v8, v1 offset:1028
	s_waitcnt lgkmcnt(0)
	v_cvt_pk_bf16_f32 v8, v6, v8
	ds_read_b32 v6, v1 offset:2056
	ds_read_b32 v9, v1 offset:3084
	s_waitcnt lgkmcnt(0)
	v_cvt_pk_bf16_f32 v9, v6, v9
	ds_read_b32 v6, v1 offset:4112
	ds_read_b32 v10, v1 offset:5140
	s_waitcnt lgkmcnt(0)
	v_cvt_pk_bf16_f32 v10, v6, v10
	ds_read_b32 v6, v1 offset:6168
	ds_read_b32 v1, v1 offset:7196
	s_waitcnt lgkmcnt(0)
	v_cvt_pk_bf16_f32 v11, v6, v1
	v_ashrrev_i32_e32 v1, 31, v0
	v_lshlrev_b64 v[0:1], 11, v[0:1]
	v_lshl_add_u64 v[0:1], v[4:5], 0, v[0:1]
	global_store_dwordx4 v[0:1], v[8:11], off sc1
.LBB0_487:
	s_or_b64 exec, exec, s[2:3]
	v_ashrrev_i32_e32 v1, 3, v3
	v_add_u32_e32 v0, s6, v1
	v_cmp_gt_i32_e32 vcc, s93, v0
	s_and_saveexec_b64 s[2:3], vcc
	s_movk_i32 s26, 0x1ff
	s_cbranch_execz .LBB0_489
	v_lshl_add_u32 v1, v1, 2, v7
	ds_read_b32 v3, v1
	ds_read_b32 v6, v1 offset:1028
	s_waitcnt lgkmcnt(0)
	v_cvt_pk_bf16_f32 v8, v3, v6
	ds_read_b32 v3, v1 offset:2056
	ds_read_b32 v6, v1 offset:3084
	s_waitcnt lgkmcnt(0)
	v_cvt_pk_bf16_f32 v9, v3, v6
	ds_read_b32 v3, v1 offset:4112
	ds_read_b32 v6, v1 offset:5140
	s_waitcnt lgkmcnt(0)
	v_cvt_pk_bf16_f32 v10, v3, v6
	ds_read_b32 v3, v1 offset:6168
	ds_read_b32 v1, v1 offset:7196
	s_waitcnt lgkmcnt(0)
	v_cvt_pk_bf16_f32 v11, v3, v1
	v_ashrrev_i32_e32 v1, 31, v0
	v_lshlrev_b64 v[0:1], 11, v[0:1]
	v_lshl_add_u64 v[0:1], v[4:5], 0, v[0:1]
	global_store_dwordx4 v[0:1], v[8:11], off sc1

.LBB0_494:
	s_add_i32 s2, s8, 0xfffffe80
	s_lshr_b32 s72, s2, 4
	s_mul_i32 s2, s4, 3
	s_mul_hi_i32 s3, s4, 3
	s_add_u32 s2, s2, s72
	s_addc_u32 s3, s3, 0
	s_lshl_b64 s[2:3], s[2:3], 20
	s_add_u32 s2, s58, s2
	s_mul_i32 s5, s4, 0xffff8400
	v_mov_b32_e32 v35, v206
	s_addc_u32 s3, s59, s3
	s_add_i32 s5, s12, s5
	s_and_b32 s6, s5, 0xc0
	v_lshlrev_b32_e32 v0, 2, v35
	s_and_b32 s5, s5, 0x300
	v_and_b32_e32 v7, 0xfc, v0
	v_ashrrev_i32_e32 v32, 6, v35
	v_add_u32_e32 v6, 0x200, v35
	v_or_b32_e32 v0, s5, v7
	v_add_u32_e32 v2, s6, v32
	v_ashrrev_i32_e32 v33, 6, v6
	v_lshlrev_b32_e32 v176, 2, v0
	v_ashrrev_i32_e32 v3, 31, v2
	v_add_u32_e32 v4, s6, v33
	v_lshl_add_u64 v[0:1], s[2:3], 0, v[176:177]
	v_lshlrev_b64 v[2:3], 12, v[2:3]
	v_ashrrev_i32_e32 v5, 31, v4
	v_lshl_add_u64 v[2:3], v[0:1], 0, v[2:3]
	v_lshlrev_b64 v[4:5], 12, v[4:5]
	s_waitcnt vmcnt(0)
	s_barrier
	v_lshl_add_u64 v[4:5], v[0:1], 0, v[4:5]
	global_load_dwordx4 v[8:11], v[2:3], off
	global_load_dwordx4 v[12:15], v[4:5], off
	v_add_u32_e32 v3, 0x400, v35
	v_add_u32_e32 v2, 0x600, v35
	v_ashrrev_i32_e32 v44, 6, v3
	v_ashrrev_i32_e32 v45, 6, v2
	v_add_u32_e32 v4, s6, v44
	v_add_u32_e32 v16, s6, v45
	v_ashrrev_i32_e32 v5, 31, v4
	v_ashrrev_i32_e32 v17, 31, v16
	v_lshlrev_b64 v[4:5], 12, v[4:5]
	v_lshlrev_b64 v[16:17], 12, v[16:17]
	v_lshl_add_u64 v[4:5], v[0:1], 0, v[4:5]
	v_lshl_add_u64 v[20:21], v[0:1], 0, v[16:17]
	global_load_dwordx4 v[16:19], v[4:5], off
	s_nop 0
	global_load_dwordx4 v[20:23], v[20:21], off
	v_add_u32_e32 v4, 0x800, v35
	v_add_u32_e32 v24, 0xa00, v35
	v_ashrrev_i32_e32 v46, 6, v4
	v_ashrrev_i32_e32 v47, 6, v24
	v_add_u32_e32 v4, s6, v46
	v_add_u32_e32 v24, s6, v47
	v_ashrrev_i32_e32 v5, 31, v4
	v_ashrrev_i32_e32 v25, 31, v24
	v_lshlrev_b64 v[4:5], 12, v[4:5]
	v_lshlrev_b64 v[24:25], 12, v[24:25]
	v_lshl_add_u64 v[4:5], v[0:1], 0, v[4:5]
	v_lshl_add_u64 v[28:29], v[0:1], 0, v[24:25]
	global_load_dwordx4 v[24:27], v[4:5], off
	s_nop 0
	global_load_dwordx4 v[28:31], v[28:29], off
	v_add_u32_e32 v4, 0xc00, v35
	v_ashrrev_i32_e32 v48, 6, v4
	v_add_u32_e32 v4, s6, v48
	v_ashrrev_i32_e32 v5, 31, v4
	v_lshlrev_b64 v[4:5], 12, v[4:5]
	v_lshl_add_u64 v[4:5], v[0:1], 0, v[4:5]
	global_load_dwordx4 v[36:39], v[4:5], off
	v_add_u32_e32 v4, 0xe00, v35
	v_ashrrev_i32_e32 v49, 6, v4
	v_add_u32_e32 v4, s6, v49
	v_ashrrev_i32_e32 v5, 31, v4
	v_lshlrev_b64 v[4:5], 12, v[4:5]
	v_lshl_add_u64 v[0:1], v[0:1], 0, v[4:5]
	global_load_dwordx4 v[40:43], v[0:1], off
	s_mul_i32 s9, s4, 0x180000
	v_lshlrev_b32_e32 v0, 2, v7
	s_mul_hi_i32 s7, s4, 0x180000
	v_mad_u64_u32 v[4:5], s[2:3], v32, s15, v[0:1]
	v_mad_u64_u32 v[32:33], s[2:3], v33, s15, v[0:1]
	s_add_u32 s9, s35, s9
	s_addc_u32 s7, s42, s7
	s_lshl_b64 s[2:3], s[72:73], 19
	s_add_u32 s9, s9, s2
	s_addc_u32 s7, s7, s3
	s_waitcnt vmcnt(7)
	ds_write2_b32 v4, v8, v9 offset1:1
	ds_write2_b32 v4, v10, v11 offset0:2 offset1:3
	s_waitcnt vmcnt(6)
	ds_write2_b32 v32, v12, v13 offset1:1
	ds_write2_b32 v32, v14, v15 offset0:2 offset1:3
	v_mad_u64_u32 v[4:5], s[2:3], v44, s15, v[0:1]
	s_waitcnt vmcnt(5)
	ds_write2_b32 v4, v16, v17 offset1:1
	ds_write2_b32 v4, v18, v19 offset0:2 offset1:3
	v_mad_u64_u32 v[4:5], s[2:3], v45, s15, v[0:1]
	s_waitcnt vmcnt(4)
	ds_write2_b32 v4, v20, v21 offset1:1
	ds_write2_b32 v4, v22, v23 offset0:2 offset1:3
	v_mad_u64_u32 v[4:5], s[2:3], v46, s15, v[0:1]
	s_waitcnt vmcnt(3)
	ds_write2_b32 v4, v24, v25 offset1:1
	ds_write2_b32 v4, v26, v27 offset0:2 offset1:3
	v_mad_u64_u32 v[4:5], s[2:3], v47, s15, v[0:1]
	s_waitcnt vmcnt(2)
	ds_write2_b32 v4, v28, v29 offset1:1
	ds_write2_b32 v4, v30, v31 offset0:2 offset1:3
	v_mad_u64_u32 v[4:5], s[2:3], v48, s15, v[0:1]
	v_mad_u64_u32 v[0:1], s[2:3], v49, s15, v[0:1]
	s_waitcnt vmcnt(1)
	ds_write2_b32 v4, v36, v37 offset1:1
	ds_write2_b32 v4, v38, v39 offset0:2 offset1:3
	s_waitcnt vmcnt(0)
	ds_write2_b32 v0, v40, v41 offset1:1
	ds_write2_b32 v0, v42, v43 offset0:2 offset1:3
	v_lshlrev_b32_e32 v0, 3, v35
	s_lshl_b32 s2, s6, 1
	v_and_b32_e32 v0, 56, v0
	s_add_u32 s2, s9, s2
	v_ashrrev_i32_e32 v1, 3, v35
	v_mul_u32_u24_e32 v7, 0x404, v0
	s_addc_u32 s3, s7, 0
	v_lshlrev_b32_e32 v176, 1, v0
	v_add_u32_e32 v0, s5, v1
	v_lshl_add_u64 v[4:5], s[2:3], 0, v[176:177]
	v_cmp_gt_i32_e32 vcc, s93, v0
	s_waitcnt lgkmcnt(0)
	s_barrier
	s_and_saveexec_b64 s[2:3], vcc
	s_cbranch_execz .LBB0_496
	v_lshl_add_u32 v1, v1, 2, v7
	ds_read_b32 v8, v1
	ds_read_b32 v9, v1 offset:1028
	s_waitcnt lgkmcnt(0)
	v_cvt_pk_bf16_f32 v8, v8, v9
	ds_read_b32 v9, v1 offset:2056
	ds_read_b32 v10, v1 offset:3084
	s_waitcnt lgkmcnt(0)
	v_cvt_pk_bf16_f32 v9, v9, v10
	ds_read_b32 v10, v1 offset:4112
	ds_read_b32 v11, v1 offset:5140
	s_waitcnt lgkmcnt(0)
	v_cvt_pk_bf16_f32 v10, v10, v11
	ds_read_b32 v11, v1 offset:6168
	ds_read_b32 v1, v1 offset:7196
	s_waitcnt lgkmcnt(0)
	v_cvt_pk_bf16_f32 v11, v11, v1
	v_ashrrev_i32_e32 v1, 31, v0
	v_lshlrev_b64 v[0:1], 9, v[0:1]
	v_lshl_add_u64 v[0:1], v[4:5], 0, v[0:1]
	global_store_dwordx4 v[0:1], v[8:11], off sc1
.LBB0_496:
	s_or_b64 exec, exec, s[2:3]
	v_ashrrev_i32_e32 v1, 3, v6
	v_add_u32_e32 v0, s5, v1
	v_cmp_gt_i32_e32 vcc, s93, v0
	s_and_saveexec_b64 s[2:3], vcc
	s_cbranch_execz .LBB0_498
	v_lshl_add_u32 v1, v1, 2, v7
	ds_read_b32 v6, v1
	ds_read_b32 v8, v1 offset:1028
	s_waitcnt lgkmcnt(0)
	v_cvt_pk_bf16_f32 v8, v6, v8
	ds_read_b32 v6, v1 offset:2056
	ds_read_b32 v9, v1 offset:3084
	s_waitcnt lgkmcnt(0)
	v_cvt_pk_bf16_f32 v9, v6, v9
	ds_read_b32 v6, v1 offset:4112
	ds_read_b32 v10, v1 offset:5140
	s_waitcnt lgkmcnt(0)
	v_cvt_pk_bf16_f32 v10, v6, v10
	ds_read_b32 v6, v1 offset:6168
	ds_read_b32 v1, v1 offset:7196
	s_waitcnt lgkmcnt(0)
	v_cvt_pk_bf16_f32 v11, v6, v1
	v_ashrrev_i32_e32 v1, 31, v0
	v_lshlrev_b64 v[0:1], 9, v[0:1]
	v_lshl_add_u64 v[0:1], v[4:5], 0, v[0:1]
	global_store_dwordx4 v[0:1], v[8:11], off sc1
.LBB0_498:
	s_or_b64 exec, exec, s[2:3]
	v_ashrrev_i32_e32 v1, 3, v3
	v_add_u32_e32 v0, s5, v1
	v_cmp_gt_i32_e32 vcc, s93, v0
	s_and_saveexec_b64 s[2:3], vcc
	s_cbranch_execz .LBB0_500
	v_lshl_add_u32 v1, v1, 2, v7
	ds_read_b32 v3, v1
	ds_read_b32 v6, v1 offset:1028
	s_waitcnt lgkmcnt(0)
	v_cvt_pk_bf16_f32 v8, v3, v6
	ds_read_b32 v3, v1 offset:2056
	ds_read_b32 v6, v1 offset:3084
	s_waitcnt lgkmcnt(0)
	v_cvt_pk_bf16_f32 v9, v3, v6
	ds_read_b32 v3, v1 offset:4112
	ds_read_b32 v6, v1 offset:5140
	s_waitcnt lgkmcnt(0)
	v_cvt_pk_bf16_f32 v10, v3, v6
	ds_read_b32 v3, v1 offset:6168
	ds_read_b32 v1, v1 offset:7196
	s_waitcnt lgkmcnt(0)
	v_cvt_pk_bf16_f32 v11, v3, v1
	v_ashrrev_i32_e32 v1, 31, v0
	v_lshlrev_b64 v[0:1], 9, v[0:1]
	v_lshl_add_u64 v[0:1], v[4:5], 0, v[0:1]
	global_store_dwordx4 v[0:1], v[8:11], off sc1

.LBB0_531:
	s_or_b64 exec, exec, s[4:5]
	v_lshl_add_u32 v1, v1, 2, v7
	ds_read_b32 v2, v1
	ds_read_b32 v3, v1 offset:1028
	s_waitcnt lgkmcnt(0)
	v_cvt_pk_bf16_f32 v8, v2, v3
	ds_read_b32 v2, v1 offset:2056
	ds_read_b32 v3, v1 offset:3084
	s_waitcnt lgkmcnt(0)
	v_cvt_pk_bf16_f32 v9, v2, v3
	ds_read_b32 v2, v1 offset:4112
	ds_read_b32 v3, v1 offset:5140
	s_waitcnt lgkmcnt(0)
	v_cvt_pk_bf16_f32 v10, v2, v3
	ds_read_b32 v2, v1 offset:6168
	ds_read_b32 v1, v1 offset:7196
	s_waitcnt lgkmcnt(0)
	v_cvt_pk_bf16_f32 v11, v2, v1
	v_ashrrev_i32_e32 v1, 31, v0
	v_lshlrev_b64 v[0:1], 11, v[0:1]
	v_lshl_add_u64 v[0:1], v[4:5], 0, v[0:1]
	global_store_dwordx4 v[0:1], v[8:11], off sc1

.LBB0_569:
	s_and_saveexec_b64 s[2:3], s[36:37]
	s_cbranch_execz .LBB0_480
	ds_read_b32 v3, v8
	ds_read_b32 v7, v9
	s_waitcnt lgkmcnt(0)
	v_cvt_pk_bf16_f32 v3, v7, v3
	v_ashrrev_i32_e32 v7, 31, v6
	v_lshlrev_b64 v[6:7], s6, v[6:7]
	v_lshl_add_u64 v[4:5], v[4:5], 0, v[6:7]
	global_store_dwordx4 v[4:5], v[0:3], off sc1
	s_branch .LBB0_480
